# K-loop 12-read sections: B reads first, full LDS wait before barrier; s_nop kept between m0 write and LDS-DMA
# baseline (speedup 1.0000x reference)
.LBB0_175:
	ds_read_b128 v[40:43], v234
	ds_read_b128 v[44:47], v234 offset:1024
	ds_read_b128 v[48:51], v234 offset:2048
	ds_read_b128 v[52:55], v234 offset:3072
	ds_read_b128 v[186:189], v234 offset:4096
	ds_read_b128 v[190:193], v234 offset:5120
	ds_read_b128 v[194:197], v234 offset:6144
	ds_read_b128 v[198:201], v234 offset:7168
	ds_read_b128 v[16:19], v233
	ds_read_b128 v[20:23], v233 offset:1024
	ds_read_b128 v[24:27], v233 offset:2048
	ds_read_b128 v[28:31], v233 offset:3072
	s_add_u32 s6, s4, 0xfffc0080
	s_addc_u32 s7, s5, -1
	s_cmp_eq_u32 s34, 12
	s_cselect_b32 s9, s10, s7
	s_cselect_b32 s8, s11, s6
	s_cselect_b32 s7, s25, s31
	s_cselect_b32 s6, s29, s30
	v_lshl_add_u64 v[202:203], s[4:5], 0, v[182:183]
	s_add_i32 m0, s92, 0xc000
	s_nop 0
	global_load_lds_dwordx4 v[202:203], off
	v_lshl_add_u64 v[202:203], s[4:5], 0, v[184:185]
	s_add_i32 m0, s92, 0xe000
	s_nop 0
	global_load_lds_dwordx4 v[202:203], off
	s_waitcnt lgkmcnt(0)
	s_barrier
	s_waitcnt lgkmcnt(0)
	v_mfma_f32_16x16x32_bf16 v[156:159], v[16:19], v[40:43], v[156:159]
	v_mfma_f32_16x16x32_bf16 v[152:155], v[24:27], v[40:43], v[152:155]
	v_mfma_f32_16x16x32_bf16 v[140:143], v[16:19], v[48:51], v[140:143]
	v_mfma_f32_16x16x32_bf16 v[136:139], v[24:27], v[48:51], v[136:139]
	v_mfma_f32_16x16x32_bf16 v[124:127], v[16:19], v[186:189], v[124:127]
	v_mfma_f32_16x16x32_bf16 v[120:123], v[24:27], v[186:189], v[120:123]
	v_mfma_f32_16x16x32_bf16 v[108:111], v[16:19], v[194:197], v[108:111]
	v_mfma_f32_16x16x32_bf16 v[104:107], v[24:27], v[194:197], v[104:107]
	v_mfma_f32_16x16x32_bf16 v[156:159], v[20:23], v[44:47], v[156:159]
	v_mfma_f32_16x16x32_bf16 v[152:155], v[28:31], v[44:47], v[152:155]
	v_mfma_f32_16x16x32_bf16 v[140:143], v[20:23], v[52:55], v[140:143]
	v_mfma_f32_16x16x32_bf16 v[136:139], v[28:31], v[52:55], v[136:139]
	v_mfma_f32_16x16x32_bf16 v[124:127], v[20:23], v[190:193], v[124:127]
	v_mfma_f32_16x16x32_bf16 v[120:123], v[28:31], v[190:193], v[120:123]
	v_mfma_f32_16x16x32_bf16 v[108:111], v[20:23], v[198:201], v[108:111]
	v_mfma_f32_16x16x32_bf16 v[104:107], v[28:31], v[198:201], v[104:107]
	s_barrier
	s_add_i32 s35, s1, s33
	v_lshl_add_u64 v[218:219], s[6:7], 0, v[166:167]
	s_mov_b32 m0, s35
	ds_read_b128 v[202:205], v235
	ds_read_b128 v[206:209], v235 offset:1024
	ds_read_b128 v[210:213], v235 offset:2048
	ds_read_b128 v[214:217], v235 offset:3072
	global_load_lds_dwordx4 v[218:219], off
	v_lshl_add_u64 v[246:247], s[6:7], 0, v[162:163]
	s_add_i32 m0, s35, 0x2000
	s_nop 0
	global_load_lds_dwordx4 v[246:247], off
	s_barrier
	s_waitcnt lgkmcnt(0)
	v_mfma_f32_16x16x32_bf16 v[148:151], v[202:205], v[40:43], v[148:151]
	v_mfma_f32_16x16x32_bf16 v[40:43], v[210:213], v[40:43], v[144:147]
	v_mfma_f32_16x16x32_bf16 v[148:151], v[206:209], v[44:47], v[148:151]
	v_mfma_f32_16x16x32_bf16 v[40:43], v[214:217], v[44:47], v[40:43]
	v_mfma_f32_16x16x32_bf16 v[44:47], v[202:205], v[48:51], v[132:135]
	v_mfma_f32_16x16x32_bf16 v[48:51], v[210:213], v[48:51], v[128:131]
	v_mfma_f32_16x16x32_bf16 v[112:115], v[210:213], v[186:189], v[112:115]
	v_mfma_f32_16x16x32_bf16 v[100:103], v[202:205], v[194:197], v[100:103]
	v_mfma_f32_16x16x32_bf16 v[96:99], v[210:213], v[194:197], v[96:99]
	v_mfma_f32_16x16x32_bf16 v[44:47], v[206:209], v[52:55], v[44:47]
	v_mfma_f32_16x16x32_bf16 v[48:51], v[214:217], v[52:55], v[48:51]
	v_mfma_f32_16x16x32_bf16 v[52:55], v[202:205], v[186:189], v[116:119]
	v_mfma_f32_16x16x32_bf16 v[112:115], v[214:217], v[190:193], v[112:115]
	v_mfma_f32_16x16x32_bf16 v[100:103], v[206:209], v[198:201], v[100:103]
	v_mfma_f32_16x16x32_bf16 v[96:99], v[214:217], v[198:201], v[96:99]
	v_mfma_f32_16x16x32_bf16 v[52:55], v[206:209], v[190:193], v[52:55]
	s_mov_b32 m0, s92
	v_lshl_add_u64 v[248:249], s[8:9], 0, v[168:169]
	s_barrier
	ds_read_b128 v[116:119], v234 offset:16384
	ds_read_b128 v[128:131], v234 offset:17408
	ds_read_b128 v[132:135], v234 offset:18432
	ds_read_b128 v[144:147], v234 offset:19456
	ds_read_b128 v[186:189], v234 offset:20480
	ds_read_b128 v[190:193], v234 offset:21504
	ds_read_b128 v[194:197], v234 offset:22528
	ds_read_b128 v[198:201], v234 offset:23552
	global_load_lds_dwordx4 v[248:249], off
	v_lshl_add_u64 v[250:251], s[8:9], 0, v[164:165]
	s_mov_b32 m0, s93
	s_nop 0
	global_load_lds_dwordx4 v[250:251], off
	s_barrier
	s_waitcnt lgkmcnt(0)
	v_mfma_f32_16x16x32_bf16 v[92:95], v[16:19], v[116:119], v[92:95]
	v_mfma_f32_16x16x32_bf16 v[88:91], v[24:27], v[116:119], v[88:91]
	v_mfma_f32_16x16x32_bf16 v[76:79], v[16:19], v[132:135], v[76:79]
	v_mfma_f32_16x16x32_bf16 v[72:75], v[24:27], v[132:135], v[72:75]
	v_mfma_f32_16x16x32_bf16 v[60:63], v[16:19], v[186:189], v[60:63]
	v_mfma_f32_16x16x32_bf16 v[56:59], v[24:27], v[186:189], v[56:59]
	v_mfma_f32_16x16x32_bf16 v[12:15], v[16:19], v[194:197], v[12:15]
	v_mfma_f32_16x16x32_bf16 v[8:11], v[24:27], v[194:197], v[8:11]
	v_mfma_f32_16x16x32_bf16 v[92:95], v[20:23], v[128:131], v[92:95]
	v_mfma_f32_16x16x32_bf16 v[88:91], v[28:31], v[128:131], v[88:91]
	v_mfma_f32_16x16x32_bf16 v[76:79], v[20:23], v[144:147], v[76:79]
	v_mfma_f32_16x16x32_bf16 v[72:75], v[28:31], v[144:147], v[72:75]
	v_mfma_f32_16x16x32_bf16 v[60:63], v[20:23], v[190:193], v[60:63]
	v_mfma_f32_16x16x32_bf16 v[56:59], v[28:31], v[190:193], v[56:59]
	v_mfma_f32_16x16x32_bf16 v[12:15], v[20:23], v[198:201], v[12:15]
	v_mfma_f32_16x16x32_bf16 v[8:11], v[28:31], v[198:201], v[8:11]
	s_barrier
	s_add_u32 s56, s6, 0x40000
	s_addc_u32 s57, s7, 0
	s_add_i32 s35, s18, s33
	v_lshl_add_u64 v[16:17], s[56:57], 0, v[166:167]
	s_mov_b32 m0, s35
	s_nop 0
	global_load_lds_dwordx4 v[16:17], off
	v_lshl_add_u64 v[16:17], s[56:57], 0, v[162:163]
	s_add_i32 m0, s35, 0x2000
	s_nop 0
	global_load_lds_dwordx4 v[16:17], off
	s_waitcnt vmcnt(6)
	s_barrier
	v_mfma_f32_16x16x32_bf16 v[36:39], v[202:205], v[186:189], v[36:39]
	v_mfma_f32_16x16x32_bf16 v[32:35], v[210:213], v[186:189], v[32:35]
	v_mfma_f32_16x16x32_bf16 v[4:7], v[202:205], v[194:197], v[4:7]
	v_mfma_f32_16x16x32_bf16 v[0:3], v[210:213], v[194:197], v[0:3]
	v_mfma_f32_16x16x32_bf16 v[16:19], v[202:205], v[116:119], v[84:87]
	v_mfma_f32_16x16x32_bf16 v[20:23], v[210:213], v[116:119], v[80:83]
	v_mfma_f32_16x16x32_bf16 v[24:27], v[202:205], v[132:135], v[68:71]
	v_mfma_f32_16x16x32_bf16 v[28:31], v[210:213], v[132:135], v[64:67]
	v_mfma_f32_16x16x32_bf16 v[36:39], v[206:209], v[190:193], v[36:39]
	v_mfma_f32_16x16x32_bf16 v[32:35], v[214:217], v[190:193], v[32:35]
	v_mfma_f32_16x16x32_bf16 v[4:7], v[206:209], v[198:201], v[4:7]
	v_mfma_f32_16x16x32_bf16 v[0:3], v[214:217], v[198:201], v[0:3]
	v_mfma_f32_16x16x32_bf16 v[16:19], v[206:209], v[128:131], v[16:19]
	v_mfma_f32_16x16x32_bf16 v[20:23], v[214:217], v[128:131], v[20:23]
	v_mfma_f32_16x16x32_bf16 v[24:27], v[206:209], v[144:147], v[24:27]
	v_mfma_f32_16x16x32_bf16 v[28:31], v[214:217], v[144:147], v[28:31]
	s_add_i32 s35, 0, 0x18000
	v_add_u32_e32 v84, s35, v232
	s_barrier
	ds_read_b128 v[116:119], v234 offset:32768
	ds_read_b128 v[128:131], v234 offset:33792
	ds_read_b128 v[186:189], v234 offset:34816
	ds_read_b128 v[190:193], v234 offset:35840
	ds_read_b128 v[194:197], v234 offset:36864
	ds_read_b128 v[198:201], v234 offset:37888
	ds_read_b128 v[202:205], v234 offset:38912
	ds_read_b128 v[206:209], v234 offset:39936
	ds_read_b128 v[64:67], v84
	ds_read_b128 v[68:71], v84 offset:1024
	ds_read_b128 v[80:83], v84 offset:2048
	ds_read_b128 v[84:87], v84 offset:3072
	s_add_u32 s8, s8, 0x40000
	s_addc_u32 s9, s9, 0
	s_mov_b32 m0, s96
	v_lshl_add_u64 v[132:133], s[8:9], 0, v[168:169]
	global_load_lds_dwordx4 v[132:133], off
	v_lshl_add_u64 v[132:133], s[8:9], 0, v[164:165]
	s_mov_b32 m0, s97
	s_nop 0
	global_load_lds_dwordx4 v[132:133], off
	s_waitcnt lgkmcnt(0)
	s_barrier
	s_waitcnt lgkmcnt(0)
	v_mfma_f32_16x16x32_bf16 v[132:135], v[64:67], v[116:119], v[156:159]
	v_mfma_f32_16x16x32_bf16 v[156:159], v[68:71], v[128:131], v[132:135]
	v_mfma_f32_16x16x32_bf16 v[132:135], v[80:83], v[116:119], v[152:155]
	v_mfma_f32_16x16x32_bf16 v[152:155], v[84:87], v[128:131], v[132:135]
	v_mfma_f32_16x16x32_bf16 v[132:135], v[64:67], v[186:189], v[140:143]
	v_mfma_f32_16x16x32_bf16 v[140:143], v[68:71], v[190:193], v[132:135]
	v_mfma_f32_16x16x32_bf16 v[132:135], v[80:83], v[186:189], v[136:139]
	v_mfma_f32_16x16x32_bf16 v[124:127], v[64:67], v[194:197], v[124:127]
	v_mfma_f32_16x16x32_bf16 v[120:123], v[80:83], v[194:197], v[120:123]
	v_mfma_f32_16x16x32_bf16 v[108:111], v[64:67], v[202:205], v[108:111]
	v_mfma_f32_16x16x32_bf16 v[104:107], v[80:83], v[202:205], v[104:107]
	v_mfma_f32_16x16x32_bf16 v[136:139], v[84:87], v[190:193], v[132:135]
	v_mfma_f32_16x16x32_bf16 v[124:127], v[68:71], v[198:201], v[124:127]
	v_mfma_f32_16x16x32_bf16 v[120:123], v[84:87], v[198:201], v[120:123]
	v_mfma_f32_16x16x32_bf16 v[108:111], v[68:71], v[206:209], v[108:111]
	v_mfma_f32_16x16x32_bf16 v[104:107], v[84:87], v[206:209], v[104:107]
	s_barrier
	s_add_i32 s8, 0, 0x1c000
	v_add_u32_e32 v132, s8, v232
	s_add_i32 s9, s35, s33
	ds_read_b128 v[210:213], v132
	ds_read_b128 v[214:217], v132 offset:1024
	ds_read_b128 v[238:241], v132 offset:2048
	ds_read_b128 v[242:245], v132 offset:3072
	v_lshl_add_u64 v[132:133], v[218:219], 0, s[14:15]
	s_mov_b32 m0, s9
	s_nop 0
	global_load_lds_dwordx4 v[132:133], off
	v_lshl_add_u64 v[132:133], v[246:247], 0, s[14:15]
	s_add_i32 m0, s9, 0x2000
	s_nop 0
	global_load_lds_dwordx4 v[132:133], off
	s_barrier
	s_waitcnt lgkmcnt(0)
	v_mfma_f32_16x16x32_bf16 v[40:43], v[238:241], v[116:119], v[40:43]
	v_mfma_f32_16x16x32_bf16 v[132:135], v[210:213], v[116:119], v[148:151]
	v_mfma_f32_16x16x32_bf16 v[144:147], v[242:245], v[128:131], v[40:43]
	v_mfma_f32_16x16x32_bf16 v[40:43], v[210:213], v[186:189], v[44:47]
	v_mfma_f32_16x16x32_bf16 v[148:151], v[214:217], v[128:131], v[132:135]
	v_mfma_f32_16x16x32_bf16 v[132:135], v[214:217], v[190:193], v[40:43]
	v_mfma_f32_16x16x32_bf16 v[40:43], v[238:241], v[186:189], v[48:51]
	v_mfma_f32_16x16x32_bf16 v[128:131], v[242:245], v[190:193], v[40:43]
	v_mfma_f32_16x16x32_bf16 v[40:43], v[210:213], v[194:197], v[52:55]
	v_mfma_f32_16x16x32_bf16 v[116:119], v[214:217], v[198:201], v[40:43]
	v_mfma_f32_16x16x32_bf16 v[40:43], v[238:241], v[194:197], v[112:115]
	v_mfma_f32_16x16x32_bf16 v[112:115], v[242:245], v[198:201], v[40:43]
	v_mfma_f32_16x16x32_bf16 v[40:43], v[210:213], v[202:205], v[100:103]
	v_mfma_f32_16x16x32_bf16 v[100:103], v[214:217], v[206:209], v[40:43]
	v_mfma_f32_16x16x32_bf16 v[40:43], v[238:241], v[202:205], v[96:99]
	v_mfma_f32_16x16x32_bf16 v[96:99], v[242:245], v[206:209], v[40:43]
	s_mov_b32 m0, s53
	v_lshl_add_u64 v[202:203], v[248:249], 0, s[14:15]
	s_barrier
	s_nop 2
	ds_read_b128 v[40:43], v234 offset:49152
	ds_read_b128 v[44:47], v234 offset:50176
	ds_read_b128 v[48:51], v234 offset:51200
	ds_read_b128 v[52:55], v234 offset:52224
	ds_read_b128 v[186:189], v234 offset:53248
	ds_read_b128 v[190:193], v234 offset:54272
	ds_read_b128 v[194:197], v234 offset:55296
	ds_read_b128 v[198:201], v234 offset:56320
	global_load_lds_dwordx4 v[202:203], off
	v_lshl_add_u64 v[202:203], v[250:251], 0, s[14:15]
	s_mov_b32 m0, s23
	s_nop 0
	global_load_lds_dwordx4 v[202:203], off
	s_barrier
	s_waitcnt lgkmcnt(0)
	v_mfma_f32_16x16x32_bf16 v[92:95], v[64:67], v[40:43], v[92:95]
	v_mfma_f32_16x16x32_bf16 v[88:91], v[80:83], v[40:43], v[88:91]
	v_mfma_f32_16x16x32_bf16 v[76:79], v[64:67], v[48:51], v[76:79]
	v_mfma_f32_16x16x32_bf16 v[72:75], v[80:83], v[48:51], v[72:75]
	v_mfma_f32_16x16x32_bf16 v[60:63], v[64:67], v[186:189], v[60:63]
	v_mfma_f32_16x16x32_bf16 v[56:59], v[80:83], v[186:189], v[56:59]
	v_mfma_f32_16x16x32_bf16 v[12:15], v[64:67], v[194:197], v[12:15]
	v_mfma_f32_16x16x32_bf16 v[8:11], v[80:83], v[194:197], v[8:11]
	v_mfma_f32_16x16x32_bf16 v[92:95], v[68:71], v[44:47], v[92:95]
	v_mfma_f32_16x16x32_bf16 v[88:91], v[84:87], v[44:47], v[88:91]
	v_mfma_f32_16x16x32_bf16 v[76:79], v[68:71], v[52:55], v[76:79]
	v_mfma_f32_16x16x32_bf16 v[72:75], v[84:87], v[52:55], v[72:75]
	v_mfma_f32_16x16x32_bf16 v[60:63], v[68:71], v[190:193], v[60:63]
	v_mfma_f32_16x16x32_bf16 v[56:59], v[84:87], v[190:193], v[56:59]
	v_mfma_f32_16x16x32_bf16 v[12:15], v[68:71], v[198:201], v[12:15]
	v_mfma_f32_16x16x32_bf16 v[8:11], v[84:87], v[198:201], v[8:11]
	s_barrier
	s_add_u32 s6, s6, 0x40080
	s_addc_u32 s7, s7, 0
	s_add_i32 s8, s8, s33
	v_lshl_add_u64 v[64:65], s[6:7], 0, v[166:167]
	s_mov_b32 m0, s8
	s_nop 0
	global_load_lds_dwordx4 v[64:65], off
	v_lshl_add_u64 v[64:65], s[6:7], 0, v[162:163]
	s_add_i32 m0, s8, 0x2000
	s_nop 0
	global_load_lds_dwordx4 v[64:65], off
	s_waitcnt vmcnt(6)
	s_barrier
	v_mfma_f32_16x16x32_bf16 v[16:19], v[210:213], v[40:43], v[16:19]
	v_mfma_f32_16x16x32_bf16 v[84:87], v[214:217], v[44:47], v[16:19]
	v_mfma_f32_16x16x32_bf16 v[16:19], v[238:241], v[40:43], v[20:23]
	v_mfma_f32_16x16x32_bf16 v[80:83], v[242:245], v[44:47], v[16:19]
	v_mfma_f32_16x16x32_bf16 v[16:19], v[210:213], v[48:51], v[24:27]
	v_mfma_f32_16x16x32_bf16 v[68:71], v[214:217], v[52:55], v[16:19]
	v_mfma_f32_16x16x32_bf16 v[16:19], v[238:241], v[48:51], v[28:31]
	v_mfma_f32_16x16x32_bf16 v[64:67], v[242:245], v[52:55], v[16:19]
	v_mfma_f32_16x16x32_bf16 v[16:19], v[210:213], v[186:189], v[36:39]
	v_mfma_f32_16x16x32_bf16 v[36:39], v[214:217], v[190:193], v[16:19]
	v_mfma_f32_16x16x32_bf16 v[16:19], v[238:241], v[186:189], v[32:35]
	v_mfma_f32_16x16x32_bf16 v[4:7], v[210:213], v[194:197], v[4:7]
	v_mfma_f32_16x16x32_bf16 v[0:3], v[238:241], v[194:197], v[0:3]
	v_mfma_f32_16x16x32_bf16 v[32:35], v[242:245], v[190:193], v[16:19]
	v_mfma_f32_16x16x32_bf16 v[4:7], v[214:217], v[198:201], v[4:7]
	v_mfma_f32_16x16x32_bf16 v[0:3], v[242:245], v[198:201], v[0:3]
	s_add_i32 s34, s34, 2
	s_add_u32 s4, s4, 0x100
	s_addc_u32 s5, s5, 0
	s_add_u32 s30, s30, 0x100
	s_addc_u32 s31, s31, 0
	s_cmp_gt_u32 s34, 13
	s_barrier
	s_cbranch_scc0 .LBB0_175
	s_cmp_gt_i32 s28, 1
	s_cselect_b64 s[6:7], -1, 0
	s_cmp_lt_i32 s28, 2
	s_cselect_b64 s[4:5], -1, 0
	s_add_i32 s8, s28, -3
	s_cmp_lt_u32 s8, 2
	s_cselect_b64 s[8:9], -1, 0
	s_lshl_b32 s29, s12, 8
	s_add_i32 s29, s29, s52
	v_or_b32_e32 v196, s29, v179
	s_nop 0
	v_ashrrev_i32_e32 v197, 31, v196
	v_readlane_b32 s72, v253, 63
	v_readlane_b32 s73, v252, 0
	s_or_b64 s[4:5], s[4:5], s[8:9]
	s_and_b32 s8, s29, 0xfc0
	v_lshl_add_u64 v[16:17], v[196:197], 2, s[72:73]
	global_load_dword v204, v[16:17], off
	global_load_dword v200, v[16:17], off offset:64
	global_load_dword v198, v[16:17], off offset:128
	global_load_dword v194, v[16:17], off offset:192
	global_load_dword v192, v[16:17], off offset:512
	global_load_dword v190, v[16:17], off offset:576
	global_load_dword v188, v[16:17], off offset:640
	global_load_dword v186, v[16:17], off offset:704
	v_or_b32_e32 v16, s8, v179
	v_readlane_b32 s8, v252, 45
	v_readlane_b32 s9, v252, 46
	s_and_b64 s[62:63], s[8:9], s[4:5]
	v_cndmask_b32_e64 v17, 0, 1, s[62:63]
	v_readlane_b32 s68, v253, 59
	v_readlane_b32 s69, v253, 60
	v_readlane_b32 s76, v252, 3
	v_readlane_b32 s77, v252, 4
	v_readlane_b32 s78, v252, 5
	v_readlane_b32 s79, v252, 6
	v_cmp_ne_u32_e64 s[4:5], 1, v17
	s_andn2_b64 vcc, exec, s[62:63]
	v_lshlrev_b32_e32 v187, 6, v16
	s_nop 6
	s_cbranch_vccnz .LBB0_178
	global_load_dwordx4 v[40:43], v187, s[76:77] offset:48
	global_load_dwordx4 v[44:47], v187, s[76:77] offset:32
	global_load_dwordx4 v[48:51], v187, s[76:77] offset:16
	global_load_dwordx4 v[52:55], v187, s[76:77]
	global_load_dwordx4 v[16:19], v187, s[76:77] offset:1072
	global_load_dwordx4 v[20:23], v187, s[76:77] offset:1056
	global_load_dwordx4 v[24:27], v187, s[76:77] offset:1040
	global_load_dwordx4 v[28:31], v187, s[76:77] offset:1024

.LBB0_612:
	ds_read_b128 v[188:191], v162
	ds_read_b128 v[192:195], v162 offset:1024
	ds_read_b128 v[196:199], v162 offset:2048
	ds_read_b128 v[200:203], v162 offset:3072
	ds_read_b128 v[204:207], v162 offset:4096
	ds_read_b128 v[208:211], v162 offset:5120
	ds_read_b128 v[212:215], v162 offset:6144
	ds_read_b128 v[216:219], v162 offset:7168
	ds_read_b128 v[164:167], v159
	ds_read_b128 v[168:171], v159 offset:1024
	ds_read_b128 v[180:183], v159 offset:2048
	ds_read_b128 v[184:187], v159 offset:3072
	s_add_u32 s24, s22, 0xfffc0080
	s_addc_u32 s25, s23, -1
	s_cmp_eq_u32 s45, 4
	s_cselect_b32 s35, s9, s25
	s_cselect_b32 s34, s41, s24
	s_cselect_b32 s25, s7, s44
	s_cselect_b32 s24, s42, s43
	v_lshl_add_u64 v[172:173], s[22:23], 0, v[154:155]
	s_add_i32 m0, s3, 0xc000
	s_nop 0
	global_load_lds_dwordx4 v[172:173], off
	v_lshl_add_u64 v[172:173], s[22:23], 0, v[156:157]
	s_add_i32 m0, s3, 0xe000
	s_nop 0
	global_load_lds_dwordx4 v[172:173], off
	s_waitcnt lgkmcnt(0)
	s_barrier
	s_waitcnt lgkmcnt(0)
	v_mfma_f32_16x16x32_bf16 v[124:127], v[164:167], v[188:191], v[124:127]
	v_mfma_f32_16x16x32_bf16 v[120:123], v[180:183], v[188:191], v[120:123]
	v_mfma_f32_16x16x32_bf16 v[116:119], v[164:167], v[196:199], v[116:119]
	v_mfma_f32_16x16x32_bf16 v[112:115], v[180:183], v[196:199], v[112:115]
	v_mfma_f32_16x16x32_bf16 v[108:111], v[164:167], v[204:207], v[108:111]
	v_mfma_f32_16x16x32_bf16 v[100:103], v[180:183], v[204:207], v[100:103]
	v_mfma_f32_16x16x32_bf16 v[92:95], v[164:167], v[212:215], v[92:95]
	v_mfma_f32_16x16x32_bf16 v[84:87], v[180:183], v[212:215], v[84:87]
	v_mfma_f32_16x16x32_bf16 v[124:127], v[168:171], v[192:195], v[124:127]
	v_mfma_f32_16x16x32_bf16 v[120:123], v[184:187], v[192:195], v[120:123]
	v_mfma_f32_16x16x32_bf16 v[116:119], v[168:171], v[200:203], v[116:119]
	v_mfma_f32_16x16x32_bf16 v[112:115], v[184:187], v[200:203], v[112:115]
	v_mfma_f32_16x16x32_bf16 v[108:111], v[168:171], v[208:211], v[108:111]
	v_mfma_f32_16x16x32_bf16 v[100:103], v[184:187], v[208:211], v[100:103]
	v_mfma_f32_16x16x32_bf16 v[92:95], v[168:171], v[216:219], v[92:95]
	v_mfma_f32_16x16x32_bf16 v[84:87], v[184:187], v[216:219], v[84:87]
	s_barrier
	s_add_i32 s52, s31, s19
	v_lshl_add_u64 v[172:173], s[24:25], 0, v[130:131]
	s_mov_b32 m0, s52
	ds_read_b128 v[232:235], v163
	ds_read_b128 v[236:239], v163 offset:1024
	ds_read_b128 v[240:243], v163 offset:2048
	ds_read_b128 v[244:247], v163 offset:3072
	global_load_lds_dwordx4 v[172:173], off
	v_lshl_add_u64 v[176:177], s[24:25], 0, v[134:135]
	s_add_i32 m0, s52, 0x2000
	s_nop 0
	global_load_lds_dwordx4 v[176:177], off
	s_barrier
	s_waitcnt lgkmcnt(0)
	v_mfma_f32_16x16x32_bf16 v[104:107], v[232:235], v[188:191], v[104:107]
	v_mfma_f32_16x16x32_bf16 v[96:99], v[240:243], v[188:191], v[96:99]
	v_mfma_f32_16x16x32_bf16 v[88:91], v[232:235], v[196:199], v[88:91]
	v_mfma_f32_16x16x32_bf16 v[80:83], v[240:243], v[196:199], v[80:83]
	v_mfma_f32_16x16x32_bf16 v[76:79], v[232:235], v[204:207], v[76:79]
	v_mfma_f32_16x16x32_bf16 v[72:75], v[240:243], v[204:207], v[72:75]
	v_mfma_f32_16x16x32_bf16 v[68:71], v[232:235], v[212:215], v[68:71]
	v_mfma_f32_16x16x32_bf16 v[64:67], v[240:243], v[212:215], v[64:67]
	v_mfma_f32_16x16x32_bf16 v[104:107], v[236:239], v[192:195], v[104:107]
	v_mfma_f32_16x16x32_bf16 v[96:99], v[244:247], v[192:195], v[96:99]
	v_mfma_f32_16x16x32_bf16 v[88:91], v[236:239], v[200:203], v[88:91]
	v_mfma_f32_16x16x32_bf16 v[80:83], v[244:247], v[200:203], v[80:83]
	v_mfma_f32_16x16x32_bf16 v[76:79], v[236:239], v[208:211], v[76:79]
	v_mfma_f32_16x16x32_bf16 v[72:75], v[244:247], v[208:211], v[72:75]
	v_mfma_f32_16x16x32_bf16 v[68:71], v[236:239], v[216:219], v[68:71]
	v_mfma_f32_16x16x32_bf16 v[64:67], v[244:247], v[216:219], v[64:67]
	s_mov_b32 m0, s3
	v_lshl_add_u64 v[248:249], s[34:35], 0, v[128:129]
	s_barrier
	ds_read_b128 v[188:191], v162 offset:16384
	ds_read_b128 v[192:195], v162 offset:17408
	ds_read_b128 v[196:199], v162 offset:18432
	ds_read_b128 v[200:203], v162 offset:19456
	ds_read_b128 v[204:207], v162 offset:20480
	ds_read_b128 v[208:211], v162 offset:21504
	ds_read_b128 v[212:215], v162 offset:22528
	ds_read_b128 v[216:219], v162 offset:23552
	global_load_lds_dwordx4 v[248:249], off
	v_lshl_add_u64 v[250:251], s[34:35], 0, v[132:133]
	s_mov_b32 m0, s20
	s_nop 0
	global_load_lds_dwordx4 v[250:251], off
	s_barrier
	s_waitcnt lgkmcnt(0)
	v_mfma_f32_16x16x32_bf16 v[60:63], v[164:167], v[188:191], v[60:63]
	v_mfma_f32_16x16x32_bf16 v[56:59], v[180:183], v[188:191], v[56:59]
	v_mfma_f32_16x16x32_bf16 v[52:55], v[164:167], v[196:199], v[52:55]
	v_mfma_f32_16x16x32_bf16 v[48:51], v[180:183], v[196:199], v[48:51]
	v_mfma_f32_16x16x32_bf16 v[44:47], v[164:167], v[204:207], v[44:47]
	v_mfma_f32_16x16x32_bf16 v[40:43], v[180:183], v[204:207], v[40:43]
	v_mfma_f32_16x16x32_bf16 v[28:31], v[164:167], v[212:215], v[28:31]
	v_mfma_f32_16x16x32_bf16 v[24:27], v[180:183], v[212:215], v[24:27]
	v_mfma_f32_16x16x32_bf16 v[60:63], v[168:171], v[192:195], v[60:63]
	v_mfma_f32_16x16x32_bf16 v[56:59], v[184:187], v[192:195], v[56:59]
	v_mfma_f32_16x16x32_bf16 v[52:55], v[168:171], v[200:203], v[52:55]
	v_mfma_f32_16x16x32_bf16 v[48:51], v[184:187], v[200:203], v[48:51]
	v_mfma_f32_16x16x32_bf16 v[44:47], v[168:171], v[208:211], v[44:47]
	v_mfma_f32_16x16x32_bf16 v[40:43], v[184:187], v[208:211], v[40:43]
	v_mfma_f32_16x16x32_bf16 v[28:31], v[168:171], v[216:219], v[28:31]
	v_mfma_f32_16x16x32_bf16 v[24:27], v[184:187], v[216:219], v[24:27]
	s_barrier
	s_add_u32 s52, s24, 0x80000
	s_addc_u32 s53, s25, 0
	s_add_i32 s54, s33, s19
	v_lshl_add_u64 v[164:165], s[52:53], 0, v[130:131]
	s_mov_b32 m0, s54
	s_nop 0
	global_load_lds_dwordx4 v[164:165], off
	v_lshl_add_u64 v[164:165], s[52:53], 0, v[134:135]
	s_add_i32 m0, s54, 0x2000
	s_nop 0
	global_load_lds_dwordx4 v[164:165], off
	s_waitcnt vmcnt(6)
	s_barrier
	v_mfma_f32_16x16x32_bf16 v[36:39], v[232:235], v[188:191], v[36:39]
	v_mfma_f32_16x16x32_bf16 v[32:35], v[240:243], v[188:191], v[32:35]
	v_mfma_f32_16x16x32_bf16 v[20:23], v[232:235], v[196:199], v[20:23]
	v_mfma_f32_16x16x32_bf16 v[16:19], v[240:243], v[196:199], v[16:19]
	v_mfma_f32_16x16x32_bf16 v[12:15], v[232:235], v[204:207], v[12:15]
	v_mfma_f32_16x16x32_bf16 v[8:11], v[240:243], v[204:207], v[8:11]
	v_mfma_f32_16x16x32_bf16 v[4:7], v[232:235], v[212:215], v[4:7]
	v_mfma_f32_16x16x32_bf16 v[0:3], v[240:243], v[212:215], v[0:3]
	v_mfma_f32_16x16x32_bf16 v[36:39], v[236:239], v[192:195], v[36:39]
	v_mfma_f32_16x16x32_bf16 v[32:35], v[244:247], v[192:195], v[32:35]
	v_mfma_f32_16x16x32_bf16 v[20:23], v[236:239], v[200:203], v[20:23]
	v_mfma_f32_16x16x32_bf16 v[16:19], v[244:247], v[200:203], v[16:19]
	v_mfma_f32_16x16x32_bf16 v[12:15], v[236:239], v[208:211], v[12:15]
	v_mfma_f32_16x16x32_bf16 v[8:11], v[244:247], v[208:211], v[8:11]
	v_mfma_f32_16x16x32_bf16 v[4:7], v[236:239], v[216:219], v[4:7]
	v_mfma_f32_16x16x32_bf16 v[0:3], v[244:247], v[216:219], v[0:3]
	s_add_i32 s52, 0, 0x18000
	v_add_u32_e32 v174, s52, v158
	s_barrier
	ds_read_b128 v[188:191], v162 offset:32768
	ds_read_b128 v[192:195], v162 offset:33792
	ds_read_b128 v[196:199], v162 offset:34816
	ds_read_b128 v[200:203], v162 offset:35840
	ds_read_b128 v[204:207], v162 offset:36864
	ds_read_b128 v[208:211], v162 offset:37888
	ds_read_b128 v[212:215], v162 offset:38912
	ds_read_b128 v[216:219], v162 offset:39936
	ds_read_b128 v[164:167], v174
	ds_read_b128 v[168:171], v174 offset:1024
	ds_read_b128 v[180:183], v174 offset:2048
	ds_read_b128 v[184:187], v174 offset:3072
	s_add_u32 s34, s34, 0x40000
	s_addc_u32 s35, s35, 0
	s_mov_b32 m0, s21
	v_lshl_add_u64 v[232:233], s[34:35], 0, v[128:129]
	global_load_lds_dwordx4 v[232:233], off
	v_lshl_add_u64 v[232:233], s[34:35], 0, v[132:133]
	s_mov_b32 m0, s27
	s_nop 0
	global_load_lds_dwordx4 v[232:233], off
	s_waitcnt lgkmcnt(0)
	s_barrier
	s_waitcnt lgkmcnt(0)
	v_mfma_f32_16x16x32_bf16 v[124:127], v[164:167], v[188:191], v[124:127]
	v_mfma_f32_16x16x32_bf16 v[120:123], v[180:183], v[188:191], v[120:123]
	v_mfma_f32_16x16x32_bf16 v[116:119], v[164:167], v[196:199], v[116:119]
	v_mfma_f32_16x16x32_bf16 v[112:115], v[180:183], v[196:199], v[112:115]
	v_mfma_f32_16x16x32_bf16 v[108:111], v[164:167], v[204:207], v[108:111]
	v_mfma_f32_16x16x32_bf16 v[100:103], v[180:183], v[204:207], v[100:103]
	v_mfma_f32_16x16x32_bf16 v[92:95], v[164:167], v[212:215], v[92:95]
	v_mfma_f32_16x16x32_bf16 v[84:87], v[180:183], v[212:215], v[84:87]
	v_mfma_f32_16x16x32_bf16 v[124:127], v[168:171], v[192:195], v[124:127]
	v_mfma_f32_16x16x32_bf16 v[120:123], v[184:187], v[192:195], v[120:123]
	v_mfma_f32_16x16x32_bf16 v[116:119], v[168:171], v[200:203], v[116:119]
	v_mfma_f32_16x16x32_bf16 v[112:115], v[184:187], v[200:203], v[112:115]
	v_mfma_f32_16x16x32_bf16 v[108:111], v[168:171], v[208:211], v[108:111]
	v_mfma_f32_16x16x32_bf16 v[100:103], v[184:187], v[208:211], v[100:103]
	v_mfma_f32_16x16x32_bf16 v[92:95], v[168:171], v[216:219], v[92:95]
	v_mfma_f32_16x16x32_bf16 v[84:87], v[184:187], v[216:219], v[84:87]
	s_barrier
	s_add_i32 s34, 0, 0x1c000
	s_add_i32 s35, s52, s19
	v_add_u32_e32 v174, s34, v158
	v_lshl_add_u64 v[172:173], v[172:173], 0, s[4:5]
	s_mov_b32 m0, s35
	ds_read_b128 v[232:235], v174
	ds_read_b128 v[236:239], v174 offset:1024
	ds_read_b128 v[240:243], v174 offset:2048
	ds_read_b128 v[244:247], v174 offset:3072
	global_load_lds_dwordx4 v[172:173], off
	v_lshl_add_u64 v[172:173], v[176:177], 0, s[4:5]
	s_add_i32 m0, s35, 0x2000
	s_nop 0
	global_load_lds_dwordx4 v[172:173], off
	s_barrier
	s_waitcnt lgkmcnt(0)
	v_mfma_f32_16x16x32_bf16 v[104:107], v[232:235], v[188:191], v[104:107]
	v_mfma_f32_16x16x32_bf16 v[96:99], v[240:243], v[188:191], v[96:99]
	v_mfma_f32_16x16x32_bf16 v[88:91], v[232:235], v[196:199], v[88:91]
	v_mfma_f32_16x16x32_bf16 v[80:83], v[240:243], v[196:199], v[80:83]
	v_mfma_f32_16x16x32_bf16 v[76:79], v[232:235], v[204:207], v[76:79]
	v_mfma_f32_16x16x32_bf16 v[72:75], v[240:243], v[204:207], v[72:75]
	v_mfma_f32_16x16x32_bf16 v[68:71], v[232:235], v[212:215], v[68:71]
	v_mfma_f32_16x16x32_bf16 v[64:67], v[240:243], v[212:215], v[64:67]
	v_mfma_f32_16x16x32_bf16 v[104:107], v[236:239], v[192:195], v[104:107]
	v_mfma_f32_16x16x32_bf16 v[96:99], v[244:247], v[192:195], v[96:99]
	v_mfma_f32_16x16x32_bf16 v[88:91], v[236:239], v[200:203], v[88:91]
	v_mfma_f32_16x16x32_bf16 v[80:83], v[244:247], v[200:203], v[80:83]
	v_mfma_f32_16x16x32_bf16 v[76:79], v[236:239], v[208:211], v[76:79]
	v_mfma_f32_16x16x32_bf16 v[72:75], v[244:247], v[208:211], v[72:75]
	v_mfma_f32_16x16x32_bf16 v[68:71], v[236:239], v[216:219], v[68:71]
	v_mfma_f32_16x16x32_bf16 v[64:67], v[244:247], v[216:219], v[64:67]
	s_mov_b32 m0, s29
	v_lshl_add_u64 v[172:173], v[248:249], 0, s[4:5]
	s_barrier
	ds_read_b128 v[188:191], v162 offset:49152
	ds_read_b128 v[192:195], v162 offset:50176
	ds_read_b128 v[196:199], v162 offset:51200
	ds_read_b128 v[200:203], v162 offset:52224
	ds_read_b128 v[204:207], v162 offset:53248
	ds_read_b128 v[208:211], v162 offset:54272
	ds_read_b128 v[212:215], v162 offset:55296
	ds_read_b128 v[216:219], v162 offset:56320
	global_load_lds_dwordx4 v[172:173], off
	v_lshl_add_u64 v[172:173], v[250:251], 0, s[4:5]
	s_mov_b32 m0, s30
	s_nop 0
	global_load_lds_dwordx4 v[172:173], off
	s_barrier
	s_waitcnt lgkmcnt(0)
	v_mfma_f32_16x16x32_bf16 v[60:63], v[164:167], v[188:191], v[60:63]
	v_mfma_f32_16x16x32_bf16 v[56:59], v[180:183], v[188:191], v[56:59]
	v_mfma_f32_16x16x32_bf16 v[52:55], v[164:167], v[196:199], v[52:55]
	v_mfma_f32_16x16x32_bf16 v[48:51], v[180:183], v[196:199], v[48:51]
	v_mfma_f32_16x16x32_bf16 v[44:47], v[164:167], v[204:207], v[44:47]
	v_mfma_f32_16x16x32_bf16 v[40:43], v[180:183], v[204:207], v[40:43]
	v_mfma_f32_16x16x32_bf16 v[28:31], v[164:167], v[212:215], v[28:31]
	v_mfma_f32_16x16x32_bf16 v[24:27], v[180:183], v[212:215], v[24:27]
	v_mfma_f32_16x16x32_bf16 v[60:63], v[168:171], v[192:195], v[60:63]
	v_mfma_f32_16x16x32_bf16 v[56:59], v[184:187], v[192:195], v[56:59]
	v_mfma_f32_16x16x32_bf16 v[52:55], v[168:171], v[200:203], v[52:55]
	v_mfma_f32_16x16x32_bf16 v[48:51], v[184:187], v[200:203], v[48:51]
	v_mfma_f32_16x16x32_bf16 v[44:47], v[168:171], v[208:211], v[44:47]
	v_mfma_f32_16x16x32_bf16 v[40:43], v[184:187], v[208:211], v[40:43]
	v_mfma_f32_16x16x32_bf16 v[28:31], v[168:171], v[216:219], v[28:31]
	v_mfma_f32_16x16x32_bf16 v[24:27], v[184:187], v[216:219], v[24:27]
	s_barrier
	s_add_u32 s24, s24, 0x80080
	s_addc_u32 s25, s25, 0
	s_add_i32 s34, s34, s19
	v_lshl_add_u64 v[164:165], s[24:25], 0, v[130:131]
	s_mov_b32 m0, s34
	s_nop 0
	global_load_lds_dwordx4 v[164:165], off
	v_lshl_add_u64 v[164:165], s[24:25], 0, v[134:135]
	s_add_i32 m0, s34, 0x2000
	s_nop 0
	global_load_lds_dwordx4 v[164:165], off
	s_waitcnt vmcnt(6)
	s_barrier
	v_mfma_f32_16x16x32_bf16 v[36:39], v[232:235], v[188:191], v[36:39]
	v_mfma_f32_16x16x32_bf16 v[32:35], v[240:243], v[188:191], v[32:35]
	v_mfma_f32_16x16x32_bf16 v[20:23], v[232:235], v[196:199], v[20:23]
	v_mfma_f32_16x16x32_bf16 v[16:19], v[240:243], v[196:199], v[16:19]
	v_mfma_f32_16x16x32_bf16 v[12:15], v[232:235], v[204:207], v[12:15]
	v_mfma_f32_16x16x32_bf16 v[8:11], v[240:243], v[204:207], v[8:11]
	v_mfma_f32_16x16x32_bf16 v[4:7], v[232:235], v[212:215], v[4:7]
	v_mfma_f32_16x16x32_bf16 v[0:3], v[240:243], v[212:215], v[0:3]
	v_mfma_f32_16x16x32_bf16 v[36:39], v[236:239], v[192:195], v[36:39]
	v_mfma_f32_16x16x32_bf16 v[32:35], v[244:247], v[192:195], v[32:35]
	v_mfma_f32_16x16x32_bf16 v[20:23], v[236:239], v[200:203], v[20:23]
	v_mfma_f32_16x16x32_bf16 v[16:19], v[244:247], v[200:203], v[16:19]
	v_mfma_f32_16x16x32_bf16 v[12:15], v[236:239], v[208:211], v[12:15]
	v_mfma_f32_16x16x32_bf16 v[8:11], v[244:247], v[208:211], v[8:11]
	v_mfma_f32_16x16x32_bf16 v[4:7], v[236:239], v[216:219], v[4:7]
	v_mfma_f32_16x16x32_bf16 v[0:3], v[244:247], v[216:219], v[0:3]
	s_add_i32 s45, s45, 2
	s_add_u32 s22, s22, 0x100
	s_addc_u32 s23, s23, 0
	s_add_u32 s43, s43, 0x100
	s_addc_u32 s44, s44, 0
	s_cmp_gt_u32 s45, 5
	s_barrier
	s_cbranch_scc0 .LBB0_612
	s_lshl_b32 s7, s26, 2
	s_and_b32 s7, s7, 0x7fffffe0
	s_add_i32 s22, s7, s2
	s_ashr_i32 s23, s22, 31
	s_lshl_b64 s[22:23], s[22:23], 18
	s_add_u32 s22, s82, s22
	s_addc_u32 s23, s83, s23
	v_lshl_add_u64 v[164:165], s[22:23], 0, v[138:139]
	v_lshl_add_u64 v[164:165], v[164:165], 0, v[136:137]
	global_store_dwordx4 v[164:165], v[124:127], off
	global_store_dwordx4 v[164:165], v[120:123], off offset:16
	global_store_dwordx4 v[164:165], v[104:107], off offset:512
	global_store_dwordx4 v[164:165], v[96:99], off offset:528
	s_and_b64 vcc, exec, s[10:11]
	s_mov_b32 s26, s40
	v_lshl_add_u64 v[96:97], s[22:23], 0, v[140:141]
	v_lshl_add_u64 v[96:97], v[96:97], 0, v[136:137]
	global_store_dwordx4 v[96:97], v[116:119], off
	global_store_dwordx4 v[96:97], v[112:115], off offset:16
	global_store_dwordx4 v[96:97], v[88:91], off offset:512
	global_store_dwordx4 v[96:97], v[80:83], off offset:528
	s_mov_b32 s2, s8
	s_mov_b64 s[24:25], s[16:17]
	v_lshl_add_u64 v[80:81], s[22:23], 0, v[142:143]
	v_lshl_add_u64 v[80:81], v[80:81], 0, v[136:137]
	global_store_dwordx4 v[80:81], v[108:111], off
	global_store_dwordx4 v[80:81], v[100:103], off offset:16
	global_store_dwordx4 v[80:81], v[76:79], off offset:512
	global_store_dwordx4 v[80:81], v[72:75], off offset:528
	s_nop 1
	v_lshl_add_u64 v[72:73], s[22:23], 0, v[144:145]
	v_lshl_add_u64 v[72:73], v[72:73], 0, v[136:137]
	global_store_dwordx4 v[72:73], v[92:95], off
	global_store_dwordx4 v[72:73], v[84:87], off offset:16
	global_store_dwordx4 v[72:73], v[68:71], off offset:512
	global_store_dwordx4 v[72:73], v[64:67], off offset:528
	s_nop 1
	v_lshl_add_u64 v[64:65], s[22:23], 0, v[146:147]
	v_lshl_add_u64 v[64:65], v[64:65], 0, v[136:137]
	global_store_dwordx4 v[64:65], v[60:63], off
	global_store_dwordx4 v[64:65], v[56:59], off offset:16
	global_store_dwordx4 v[64:65], v[36:39], off offset:512
	global_store_dwordx4 v[64:65], v[32:35], off offset:528
	s_nop 1
	v_lshl_add_u64 v[32:33], s[22:23], 0, v[148:149]
	v_lshl_add_u64 v[32:33], v[32:33], 0, v[136:137]
	global_store_dwordx4 v[32:33], v[52:55], off
	global_store_dwordx4 v[32:33], v[48:51], off offset:16
	global_store_dwordx4 v[32:33], v[20:23], off offset:512
	global_store_dwordx4 v[32:33], v[16:19], off offset:528
	s_nop 1
	v_lshl_add_u64 v[16:17], s[22:23], 0, v[150:151]
	v_lshl_add_u64 v[16:17], v[16:17], 0, v[136:137]
	global_store_dwordx4 v[16:17], v[44:47], off
	global_store_dwordx4 v[16:17], v[40:43], off offset:16
	global_store_dwordx4 v[16:17], v[12:15], off offset:512
	global_store_dwordx4 v[16:17], v[8:11], off offset:528
	s_nop 1
	v_lshl_add_u64 v[8:9], s[22:23], 0, v[152:153]
	v_lshl_add_u64 v[8:9], v[8:9], 0, v[136:137]
	s_mov_b64 s[22:23], s[14:15]
	global_store_dwordx4 v[8:9], v[28:31], off
	global_store_dwordx4 v[8:9], v[24:27], off offset:16
	global_store_dwordx4 v[8:9], v[4:7], off offset:512
	global_store_dwordx4 v[8:9], v[0:3], off offset:528
	s_cbranch_vccz .LBB0_606
	s_waitcnt vmcnt(0)
	s_cmpk_gt_u32 s18, 0xff
	s_cbranch_scc1 .LBB0_616
	s_barrier

.LBB0_1268:
	ds_read_b128 v[164:167], v150
	ds_read_b128 v[168:171], v150 offset:1024
	ds_read_b128 v[172:175], v150 offset:2048
	ds_read_b128 v[180:183], v150 offset:3072
	ds_read_b128 v[184:187], v150 offset:4096
	ds_read_b128 v[188:191], v150 offset:5120
	ds_read_b128 v[192:195], v150 offset:6144
	ds_read_b128 v[196:199], v150 offset:7168
	ds_read_b128 v[140:143], v149
	ds_read_b128 v[152:155], v149 offset:1024
	ds_read_b128 v[156:159], v149 offset:2048
	ds_read_b128 v[160:163], v149 offset:3072
	s_add_u32 s22, s10, 0xfffe0080
	s_addc_u32 s23, s11, -1
	s_cmp_eq_u32 s44, 4
	s_cselect_b32 s25, s13, s23
	s_cselect_b32 s24, s40, s22
	s_cselect_b32 s23, s15, s43
	s_cselect_b32 s22, s41, s42
	v_lshl_add_u64 v[144:145], s[10:11], 0, v[136:137]
	s_add_i32 m0, s1, 0xc000
	s_nop 0
	global_load_lds_dwordx4 v[144:145], off
	v_lshl_add_u64 v[144:145], s[10:11], 0, v[138:139]
	s_add_i32 m0, s1, 0xe000
	s_nop 0
	global_load_lds_dwordx4 v[144:145], off
	s_waitcnt lgkmcnt(0)
	s_barrier
	s_waitcnt lgkmcnt(0)
	v_mfma_f32_16x16x32_bf16 v[124:127], v[140:143], v[164:167], v[124:127]
	v_mfma_f32_16x16x32_bf16 v[120:123], v[156:159], v[164:167], v[120:123]
	v_mfma_f32_16x16x32_bf16 v[112:115], v[140:143], v[172:175], v[112:115]
	v_mfma_f32_16x16x32_bf16 v[104:107], v[156:159], v[172:175], v[104:107]
	v_mfma_f32_16x16x32_bf16 v[96:99], v[140:143], v[184:187], v[96:99]
	v_mfma_f32_16x16x32_bf16 v[88:91], v[156:159], v[184:187], v[88:91]
	v_mfma_f32_16x16x32_bf16 v[80:83], v[140:143], v[192:195], v[80:83]
	v_mfma_f32_16x16x32_bf16 v[72:75], v[156:159], v[192:195], v[72:75]
	v_mfma_f32_16x16x32_bf16 v[124:127], v[152:155], v[168:171], v[124:127]
	v_mfma_f32_16x16x32_bf16 v[120:123], v[160:163], v[168:171], v[120:123]
	v_mfma_f32_16x16x32_bf16 v[112:115], v[152:155], v[180:183], v[112:115]
	v_mfma_f32_16x16x32_bf16 v[104:107], v[160:163], v[180:183], v[104:107]
	v_mfma_f32_16x16x32_bf16 v[96:99], v[152:155], v[188:191], v[96:99]
	v_mfma_f32_16x16x32_bf16 v[88:91], v[160:163], v[188:191], v[88:91]
	v_mfma_f32_16x16x32_bf16 v[80:83], v[152:155], v[196:199], v[80:83]
	v_mfma_f32_16x16x32_bf16 v[72:75], v[160:163], v[196:199], v[72:75]
	s_barrier
	s_add_i32 s45, s35, s27
	v_lshl_add_u64 v[144:145], s[22:23], 0, v[132:133]
	s_mov_b32 m0, s45
	ds_read_b128 v[200:203], v151
	ds_read_b128 v[204:207], v151 offset:1024
	ds_read_b128 v[208:211], v151 offset:2048
	ds_read_b128 v[212:215], v151 offset:3072
	global_load_lds_dwordx4 v[144:145], off
	v_lshl_add_u64 v[176:177], s[22:23], 0, v[128:129]
	s_add_i32 m0, s45, 0x2000
	s_nop 0
	global_load_lds_dwordx4 v[176:177], off
	s_barrier
	s_waitcnt lgkmcnt(0)
	v_mfma_f32_16x16x32_bf16 v[116:119], v[200:203], v[164:167], v[116:119]
	v_mfma_f32_16x16x32_bf16 v[108:111], v[208:211], v[164:167], v[108:111]
	v_mfma_f32_16x16x32_bf16 v[100:103], v[200:203], v[172:175], v[100:103]
	v_mfma_f32_16x16x32_bf16 v[92:95], v[208:211], v[172:175], v[92:95]
	v_mfma_f32_16x16x32_bf16 v[84:87], v[200:203], v[184:187], v[84:87]
	v_mfma_f32_16x16x32_bf16 v[76:79], v[208:211], v[184:187], v[76:79]
	v_mfma_f32_16x16x32_bf16 v[68:71], v[200:203], v[192:195], v[68:71]
	v_mfma_f32_16x16x32_bf16 v[64:67], v[208:211], v[192:195], v[64:67]
	v_mfma_f32_16x16x32_bf16 v[116:119], v[204:207], v[168:171], v[116:119]
	v_mfma_f32_16x16x32_bf16 v[108:111], v[212:215], v[168:171], v[108:111]
	v_mfma_f32_16x16x32_bf16 v[100:103], v[204:207], v[180:183], v[100:103]
	v_mfma_f32_16x16x32_bf16 v[92:95], v[212:215], v[180:183], v[92:95]
	v_mfma_f32_16x16x32_bf16 v[84:87], v[204:207], v[188:191], v[84:87]
	v_mfma_f32_16x16x32_bf16 v[76:79], v[212:215], v[188:191], v[76:79]
	v_mfma_f32_16x16x32_bf16 v[68:71], v[204:207], v[196:199], v[68:71]
	v_mfma_f32_16x16x32_bf16 v[64:67], v[212:215], v[196:199], v[64:67]
	s_mov_b32 m0, s1
	v_lshl_add_u64 v[216:217], s[24:25], 0, v[134:135]
	s_barrier
	ds_read_b128 v[164:167], v150 offset:16384
	ds_read_b128 v[168:171], v150 offset:17408
	ds_read_b128 v[172:175], v150 offset:18432
	ds_read_b128 v[180:183], v150 offset:19456
	ds_read_b128 v[184:187], v150 offset:20480
	ds_read_b128 v[188:191], v150 offset:21504
	ds_read_b128 v[192:195], v150 offset:22528
	ds_read_b128 v[196:199], v150 offset:23552
	global_load_lds_dwordx4 v[216:217], off
	v_lshl_add_u64 v[218:219], s[24:25], 0, v[130:131]
	s_mov_b32 m0, s7
	s_nop 0
	global_load_lds_dwordx4 v[218:219], off
	s_barrier
	s_waitcnt lgkmcnt(0)
	v_mfma_f32_16x16x32_bf16 v[60:63], v[140:143], v[164:167], v[60:63]
	v_mfma_f32_16x16x32_bf16 v[56:59], v[156:159], v[164:167], v[56:59]
	v_mfma_f32_16x16x32_bf16 v[48:51], v[140:143], v[172:175], v[48:51]
	v_mfma_f32_16x16x32_bf16 v[40:43], v[156:159], v[172:175], v[40:43]
	v_mfma_f32_16x16x32_bf16 v[32:35], v[140:143], v[184:187], v[32:35]
	v_mfma_f32_16x16x32_bf16 v[24:27], v[156:159], v[184:187], v[24:27]
	v_mfma_f32_16x16x32_bf16 v[16:19], v[140:143], v[192:195], v[16:19]
	v_mfma_f32_16x16x32_bf16 v[8:11], v[156:159], v[192:195], v[8:11]
	v_mfma_f32_16x16x32_bf16 v[60:63], v[152:155], v[168:171], v[60:63]
	v_mfma_f32_16x16x32_bf16 v[56:59], v[160:163], v[168:171], v[56:59]
	v_mfma_f32_16x16x32_bf16 v[48:51], v[152:155], v[180:183], v[48:51]
	v_mfma_f32_16x16x32_bf16 v[40:43], v[160:163], v[180:183], v[40:43]
	v_mfma_f32_16x16x32_bf16 v[32:35], v[152:155], v[188:191], v[32:35]
	v_mfma_f32_16x16x32_bf16 v[24:27], v[160:163], v[188:191], v[24:27]
	v_mfma_f32_16x16x32_bf16 v[16:19], v[152:155], v[196:199], v[16:19]
	v_mfma_f32_16x16x32_bf16 v[8:11], v[160:163], v[196:199], v[8:11]
	s_barrier
	s_add_u32 s46, s22, 0x20000
	s_addc_u32 s47, s23, 0
	s_add_i32 s45, s36, s27
	v_lshl_add_u64 v[140:141], s[46:47], 0, v[132:133]
	s_mov_b32 m0, s45
	s_nop 0
	global_load_lds_dwordx4 v[140:141], off
	v_lshl_add_u64 v[140:141], s[46:47], 0, v[128:129]
	s_add_i32 m0, s45, 0x2000
	s_nop 0
	global_load_lds_dwordx4 v[140:141], off
	s_waitcnt vmcnt(6)
	s_barrier
	v_mfma_f32_16x16x32_bf16 v[52:55], v[200:203], v[164:167], v[52:55]
	v_mfma_f32_16x16x32_bf16 v[44:47], v[208:211], v[164:167], v[44:47]
	v_mfma_f32_16x16x32_bf16 v[36:39], v[200:203], v[172:175], v[36:39]
	v_mfma_f32_16x16x32_bf16 v[28:31], v[208:211], v[172:175], v[28:31]
	v_mfma_f32_16x16x32_bf16 v[20:23], v[200:203], v[184:187], v[20:23]
	v_mfma_f32_16x16x32_bf16 v[12:15], v[208:211], v[184:187], v[12:15]
	v_mfma_f32_16x16x32_bf16 v[4:7], v[200:203], v[192:195], v[4:7]
	v_mfma_f32_16x16x32_bf16 v[0:3], v[208:211], v[192:195], v[0:3]
	v_mfma_f32_16x16x32_bf16 v[52:55], v[204:207], v[168:171], v[52:55]
	v_mfma_f32_16x16x32_bf16 v[44:47], v[212:215], v[168:171], v[44:47]
	v_mfma_f32_16x16x32_bf16 v[36:39], v[204:207], v[180:183], v[36:39]
	v_mfma_f32_16x16x32_bf16 v[28:31], v[212:215], v[180:183], v[28:31]
	v_mfma_f32_16x16x32_bf16 v[20:23], v[204:207], v[188:191], v[20:23]
	v_mfma_f32_16x16x32_bf16 v[12:15], v[212:215], v[188:191], v[12:15]
	v_mfma_f32_16x16x32_bf16 v[4:7], v[204:207], v[196:199], v[4:7]
	v_mfma_f32_16x16x32_bf16 v[0:3], v[212:215], v[196:199], v[0:3]
	s_add_i32 s45, 0, 0x18000
	v_add_u32_e32 v160, s45, v147
	s_barrier
	ds_read_b128 v[164:167], v150 offset:32768
	ds_read_b128 v[168:171], v150 offset:33792
	ds_read_b128 v[172:175], v150 offset:34816
	ds_read_b128 v[180:183], v150 offset:35840
	ds_read_b128 v[184:187], v150 offset:36864
	ds_read_b128 v[188:191], v150 offset:37888
	ds_read_b128 v[192:195], v150 offset:38912
	ds_read_b128 v[196:199], v150 offset:39936
	ds_read_b128 v[140:143], v160
	ds_read_b128 v[152:155], v160 offset:1024
	ds_read_b128 v[156:159], v160 offset:2048
	ds_read_b128 v[160:163], v160 offset:3072
	s_add_u32 s24, s24, 0x20000
	s_addc_u32 s25, s25, 0
	s_mov_b32 m0, s28
	v_lshl_add_u64 v[200:201], s[24:25], 0, v[134:135]
	global_load_lds_dwordx4 v[200:201], off
	v_lshl_add_u64 v[200:201], s[24:25], 0, v[130:131]
	s_mov_b32 m0, s29
	s_nop 0
	global_load_lds_dwordx4 v[200:201], off
	s_waitcnt lgkmcnt(0)
	s_barrier
	s_waitcnt lgkmcnt(0)
	v_mfma_f32_16x16x32_bf16 v[124:127], v[140:143], v[164:167], v[124:127]
	v_mfma_f32_16x16x32_bf16 v[120:123], v[156:159], v[164:167], v[120:123]
	v_mfma_f32_16x16x32_bf16 v[112:115], v[140:143], v[172:175], v[112:115]
	v_mfma_f32_16x16x32_bf16 v[104:107], v[156:159], v[172:175], v[104:107]
	v_mfma_f32_16x16x32_bf16 v[96:99], v[140:143], v[184:187], v[96:99]
	v_mfma_f32_16x16x32_bf16 v[88:91], v[156:159], v[184:187], v[88:91]
	v_mfma_f32_16x16x32_bf16 v[80:83], v[140:143], v[192:195], v[80:83]
	v_mfma_f32_16x16x32_bf16 v[72:75], v[156:159], v[192:195], v[72:75]
	v_mfma_f32_16x16x32_bf16 v[124:127], v[152:155], v[168:171], v[124:127]
	v_mfma_f32_16x16x32_bf16 v[120:123], v[160:163], v[168:171], v[120:123]
	v_mfma_f32_16x16x32_bf16 v[112:115], v[152:155], v[180:183], v[112:115]
	v_mfma_f32_16x16x32_bf16 v[104:107], v[160:163], v[180:183], v[104:107]
	v_mfma_f32_16x16x32_bf16 v[96:99], v[152:155], v[188:191], v[96:99]
	v_mfma_f32_16x16x32_bf16 v[88:91], v[160:163], v[188:191], v[88:91]
	v_mfma_f32_16x16x32_bf16 v[80:83], v[152:155], v[196:199], v[80:83]
	v_mfma_f32_16x16x32_bf16 v[72:75], v[160:163], v[196:199], v[72:75]
	s_barrier
	s_add_i32 s24, 0, 0x1c000
	s_add_i32 s25, s45, s27
	v_add_u32_e32 v179, s24, v147
	v_lshl_add_u64 v[144:145], v[144:145], 0, s[2:3]
	s_mov_b32 m0, s25
	ds_read_b128 v[200:203], v179
	ds_read_b128 v[204:207], v179 offset:1024
	ds_read_b128 v[208:211], v179 offset:2048
	ds_read_b128 v[212:215], v179 offset:3072
	global_load_lds_dwordx4 v[144:145], off
	v_lshl_add_u64 v[144:145], v[176:177], 0, s[2:3]
	s_add_i32 m0, s25, 0x2000
	s_nop 0
	global_load_lds_dwordx4 v[144:145], off
	s_barrier
	s_waitcnt lgkmcnt(0)
	v_mfma_f32_16x16x32_bf16 v[116:119], v[200:203], v[164:167], v[116:119]
	v_mfma_f32_16x16x32_bf16 v[108:111], v[208:211], v[164:167], v[108:111]
	v_mfma_f32_16x16x32_bf16 v[100:103], v[200:203], v[172:175], v[100:103]
	v_mfma_f32_16x16x32_bf16 v[92:95], v[208:211], v[172:175], v[92:95]
	v_mfma_f32_16x16x32_bf16 v[84:87], v[200:203], v[184:187], v[84:87]
	v_mfma_f32_16x16x32_bf16 v[76:79], v[208:211], v[184:187], v[76:79]
	v_mfma_f32_16x16x32_bf16 v[68:71], v[200:203], v[192:195], v[68:71]
	v_mfma_f32_16x16x32_bf16 v[64:67], v[208:211], v[192:195], v[64:67]
	v_mfma_f32_16x16x32_bf16 v[116:119], v[204:207], v[168:171], v[116:119]
	v_mfma_f32_16x16x32_bf16 v[108:111], v[212:215], v[168:171], v[108:111]
	v_mfma_f32_16x16x32_bf16 v[100:103], v[204:207], v[180:183], v[100:103]
	v_mfma_f32_16x16x32_bf16 v[92:95], v[212:215], v[180:183], v[92:95]
	v_mfma_f32_16x16x32_bf16 v[84:87], v[204:207], v[188:191], v[84:87]
	v_mfma_f32_16x16x32_bf16 v[76:79], v[212:215], v[188:191], v[76:79]
	v_mfma_f32_16x16x32_bf16 v[68:71], v[204:207], v[196:199], v[68:71]
	v_mfma_f32_16x16x32_bf16 v[64:67], v[212:215], v[196:199], v[64:67]
	s_mov_b32 m0, s31
	v_lshl_add_u64 v[144:145], v[216:217], 0, s[2:3]
	s_barrier
	ds_read_b128 v[164:167], v150 offset:49152
	ds_read_b128 v[168:171], v150 offset:50176
	ds_read_b128 v[172:175], v150 offset:51200
	ds_read_b128 v[180:183], v150 offset:52224
	ds_read_b128 v[184:187], v150 offset:53248
	ds_read_b128 v[188:191], v150 offset:54272
	ds_read_b128 v[192:195], v150 offset:55296
	ds_read_b128 v[196:199], v150 offset:56320
	global_load_lds_dwordx4 v[144:145], off
	v_lshl_add_u64 v[144:145], v[218:219], 0, s[2:3]
	s_mov_b32 m0, s33
	s_nop 0
	global_load_lds_dwordx4 v[144:145], off
	s_barrier
	s_waitcnt lgkmcnt(0)
	v_mfma_f32_16x16x32_bf16 v[60:63], v[140:143], v[164:167], v[60:63]
	v_mfma_f32_16x16x32_bf16 v[56:59], v[156:159], v[164:167], v[56:59]
	v_mfma_f32_16x16x32_bf16 v[48:51], v[140:143], v[172:175], v[48:51]
	v_mfma_f32_16x16x32_bf16 v[40:43], v[156:159], v[172:175], v[40:43]
	v_mfma_f32_16x16x32_bf16 v[32:35], v[140:143], v[184:187], v[32:35]
	v_mfma_f32_16x16x32_bf16 v[24:27], v[156:159], v[184:187], v[24:27]
	v_mfma_f32_16x16x32_bf16 v[16:19], v[140:143], v[192:195], v[16:19]
	v_mfma_f32_16x16x32_bf16 v[8:11], v[156:159], v[192:195], v[8:11]
	v_mfma_f32_16x16x32_bf16 v[60:63], v[152:155], v[168:171], v[60:63]
	v_mfma_f32_16x16x32_bf16 v[56:59], v[160:163], v[168:171], v[56:59]
	v_mfma_f32_16x16x32_bf16 v[48:51], v[152:155], v[180:183], v[48:51]
	v_mfma_f32_16x16x32_bf16 v[40:43], v[160:163], v[180:183], v[40:43]
	v_mfma_f32_16x16x32_bf16 v[32:35], v[152:155], v[188:191], v[32:35]
	v_mfma_f32_16x16x32_bf16 v[24:27], v[160:163], v[188:191], v[24:27]
	v_mfma_f32_16x16x32_bf16 v[16:19], v[152:155], v[196:199], v[16:19]
	v_mfma_f32_16x16x32_bf16 v[8:11], v[160:163], v[196:199], v[8:11]
	s_barrier
	s_add_u32 s22, s22, 0x20080
	s_addc_u32 s23, s23, 0
	s_add_i32 s24, s24, s27
	v_lshl_add_u64 v[140:141], s[22:23], 0, v[132:133]
	s_mov_b32 m0, s24
	s_nop 0
	global_load_lds_dwordx4 v[140:141], off
	v_lshl_add_u64 v[140:141], s[22:23], 0, v[128:129]
	s_add_i32 m0, s24, 0x2000
	s_nop 0
	global_load_lds_dwordx4 v[140:141], off
	s_waitcnt vmcnt(6)
	s_barrier
	v_mfma_f32_16x16x32_bf16 v[52:55], v[200:203], v[164:167], v[52:55]
	v_mfma_f32_16x16x32_bf16 v[44:47], v[208:211], v[164:167], v[44:47]
	v_mfma_f32_16x16x32_bf16 v[36:39], v[200:203], v[172:175], v[36:39]
	v_mfma_f32_16x16x32_bf16 v[28:31], v[208:211], v[172:175], v[28:31]
	v_mfma_f32_16x16x32_bf16 v[20:23], v[200:203], v[184:187], v[20:23]
	v_mfma_f32_16x16x32_bf16 v[12:15], v[208:211], v[184:187], v[12:15]
	v_mfma_f32_16x16x32_bf16 v[4:7], v[200:203], v[192:195], v[4:7]
	v_mfma_f32_16x16x32_bf16 v[0:3], v[208:211], v[192:195], v[0:3]
	v_mfma_f32_16x16x32_bf16 v[52:55], v[204:207], v[168:171], v[52:55]
	v_mfma_f32_16x16x32_bf16 v[44:47], v[212:215], v[168:171], v[44:47]
	v_mfma_f32_16x16x32_bf16 v[36:39], v[204:207], v[180:183], v[36:39]
	v_mfma_f32_16x16x32_bf16 v[28:31], v[212:215], v[180:183], v[28:31]
	v_mfma_f32_16x16x32_bf16 v[20:23], v[204:207], v[188:191], v[20:23]
	v_mfma_f32_16x16x32_bf16 v[12:15], v[212:215], v[188:191], v[12:15]
	v_mfma_f32_16x16x32_bf16 v[4:7], v[204:207], v[196:199], v[4:7]
	v_mfma_f32_16x16x32_bf16 v[0:3], v[212:215], v[196:199], v[0:3]
	s_add_i32 s44, s44, 2
	s_add_u32 s10, s10, 0x100
	s_addc_u32 s11, s11, 0
	s_add_u32 s42, s42, 0x100
	s_addc_u32 s43, s43, 0
	s_cmp_gt_u32 s44, 5
	s_barrier
	s_cbranch_scc0 .LBB0_1268
	v_lshl_add_u32 v142, s39, 8, v146
	s_nop 0
	v_lshl_or_b32 v140, s38, 8, v148
	v_ashrrev_i32_e32 v143, 31, v142
	s_nop 1
	v_readlane_b32 s46, v252, 13
	v_readlane_b32 s47, v252, 14
	v_ashrrev_i32_e32 v141, 31, v140
	v_lshlrev_b64 v[144:145], 12, v[142:143]
	s_mov_b64 s[42:43], s[46:47]
	v_lshl_add_u64 v[144:145], s[42:43], 0, v[144:145]
	v_lshlrev_b64 v[140:141], 1, v[140:141]
	v_or_b32_e32 v172, 16, v142
	v_lshl_add_u64 v[144:145], v[144:145], 0, v[140:141]
	v_ashrrev_i32_e32 v173, 31, v172
	global_load_dwordx4 v[152:155], v[144:145], off
	global_load_dwordx4 v[156:159], v[144:145], off offset:256
	v_lshlrev_b64 v[144:145], 12, v[172:173]
	v_lshl_add_u64 v[144:145], s[42:43], 0, v[144:145]
	v_lshl_add_u64 v[144:145], v[144:145], 0, v[140:141]
	global_load_dwordx4 v[160:163], v[144:145], off
	global_load_dwordx4 v[164:167], v[144:145], off offset:256
	v_or_b32_e32 v176, 32, v142
	v_ashrrev_i32_e32 v177, 31, v176
	v_lshlrev_b64 v[168:169], 12, v[176:177]
	v_lshl_add_u64 v[168:169], s[42:43], 0, v[168:169]
	v_lshl_add_u64 v[182:183], v[168:169], 0, v[140:141]
	global_load_dwordx4 v[168:171], v[182:183], off
	v_or_b32_e32 v144, 48, v142
	v_ashrrev_i32_e32 v145, 31, v144
	v_lshlrev_b64 v[180:181], 12, v[144:145]
	v_lshlrev_b64 v[174:175], 11, v[142:143]
	v_lshlrev_b64 v[172:173], 11, v[172:173]
	v_lshl_add_u64 v[180:181], s[42:43], 0, v[180:181]
	v_lshl_add_u64 v[174:175], s[82:83], 0, v[174:175]
	v_lshl_add_u64 v[172:173], s[82:83], 0, v[172:173]
	v_lshl_add_u64 v[184:185], v[180:181], 0, v[140:141]
	v_lshl_add_u64 v[188:189], v[174:175], 0, v[140:141]
	v_lshl_add_u64 v[190:191], v[172:173], 0, v[140:141]
	global_load_dwordx4 v[172:175], v[182:183], off offset:256
	s_nop 0
	global_load_dwordx4 v[180:183], v[184:185], off
	s_nop 0
	global_load_dwordx4 v[184:187], v[184:185], off offset:256
	v_add_u32_e32 v234, 0x80, v142
	v_ashrrev_i32_e32 v235, 31, v234
	v_lshlrev_b64 v[236:237], 12, v[234:235]
	v_lshl_add_u64 v[236:237], s[42:43], 0, v[236:237]
	v_lshl_add_u64 v[236:237], v[236:237], 0, v[140:141]
	global_load_dwordx4 v[200:203], v[236:237], off
	global_load_dwordx4 v[204:207], v[236:237], off offset:256
	v_add_u32_e32 v234, 0x90, v142
	v_ashrrev_i32_e32 v235, 31, v234
	v_lshlrev_b64 v[236:237], 12, v[234:235]
	v_lshl_add_u64 v[236:237], s[42:43], 0, v[236:237]
	v_lshl_add_u64 v[236:237], v[236:237], 0, v[140:141]
	global_load_dwordx4 v[208:211], v[236:237], off
	global_load_dwordx4 v[212:215], v[236:237], off offset:256
	v_add_u32_e32 v234, 0xa0, v142
	v_ashrrev_i32_e32 v235, 31, v234
	v_lshlrev_b64 v[236:237], 12, v[234:235]
	v_lshl_add_u64 v[236:237], s[42:43], 0, v[236:237]
	v_lshl_add_u64 v[236:237], v[236:237], 0, v[140:141]
	global_load_dwordx4 v[216:219], v[236:237], off
	global_load_dwordx4 v[222:225], v[236:237], off offset:256
	v_add_u32_e32 v234, 0xb0, v142
	v_ashrrev_i32_e32 v235, 31, v234
	v_lshlrev_b64 v[236:237], 12, v[234:235]
	v_lshl_add_u64 v[236:237], s[42:43], 0, v[236:237]
	v_lshl_add_u64 v[236:237], v[236:237], 0, v[140:141]
	global_load_dwordx4 v[226:229], v[236:237], off
	global_load_dwordx4 v[230:233], v[236:237], off offset:256
	s_and_b64 vcc, exec, s[18:19]
	s_mov_b32 s38, s14
	s_mov_b32 s39, s12
	s_mov_b32 s15, s14
	s_mov_b32 s18, s12
	s_mov_b64 s[22:23], s[20:21]
	s_mov_b64 s[10:11], s[16:17]
	s_mov_b32 s13, s37
	s_nop 7
	s_nop 2
	s_waitcnt vmcnt(8)
	v_lshlrev_b32_e32 v194, 16, v154
	v_and_b32_e32 v195, 0xffff0000, v154
	v_lshlrev_b32_e32 v154, 16, v155
	v_and_b32_e32 v155, 0xffff0000, v155
	v_lshlrev_b32_e32 v196, 16, v156
	v_and_b32_e32 v197, 0xffff0000, v156
	v_lshlrev_b32_e32 v156, 16, v157
	v_and_b32_e32 v157, 0xffff0000, v157
	v_lshlrev_b32_e32 v198, 16, v158
	v_and_b32_e32 v199, 0xffff0000, v158
	v_lshlrev_b32_e32 v158, 16, v159
	v_and_b32_e32 v159, 0xffff0000, v159
	v_lshlrev_b32_e32 v192, 16, v152
	v_and_b32_e32 v193, 0xffff0000, v152
	v_lshlrev_b32_e32 v152, 16, v153
	v_and_b32_e32 v153, 0xffff0000, v153
	v_pk_mul_f32 v[120:121], v[120:121], v[194:195]
	v_pk_mul_f32 v[122:123], v[122:123], v[154:155]
	v_pk_mul_f32 v[118:119], v[118:119], v[156:157]
	v_pk_mul_f32 v[154:155], v[110:111], v[158:159]
	v_lshlrev_b32_e32 v156, 16, v160
	v_and_b32_e32 v157, 0xffff0000, v160
	v_lshlrev_b32_e32 v158, 16, v161
	v_and_b32_e32 v159, 0xffff0000, v161
	v_lshlrev_b32_e32 v160, 16, v162
	v_and_b32_e32 v161, 0xffff0000, v162
	v_lshlrev_b32_e32 v162, 16, v163
	v_and_b32_e32 v163, 0xffff0000, v163
	v_pk_mul_f32 v[124:125], v[124:125], v[192:193]
	v_pk_mul_f32 v[126:127], v[126:127], v[152:153]
	v_cvt_pk_bf16_f32 v110, v120, v121
	v_cvt_pk_bf16_f32 v111, v122, v123
	v_pk_mul_f32 v[112:113], v[112:113], v[156:157]
	v_pk_mul_f32 v[114:115], v[114:115], v[158:159]
	v_pk_mul_f32 v[120:121], v[104:105], v[160:161]
	v_pk_mul_f32 v[122:123], v[106:107], v[162:163]
	v_pk_mul_f32 v[116:117], v[116:117], v[196:197]
	v_pk_mul_f32 v[152:153], v[108:109], v[198:199]
	v_cvt_pk_bf16_f32 v108, v124, v125
	v_cvt_pk_bf16_f32 v109, v126, v127
	v_cvt_pk_bf16_f32 v104, v112, v113
	v_cvt_pk_bf16_f32 v105, v114, v115
	v_cvt_pk_bf16_f32 v106, v120, v121
	v_cvt_pk_bf16_f32 v107, v122, v123
	v_cvt_pk_bf16_f32 v116, v116, v117
	v_cvt_pk_bf16_f32 v117, v118, v119
	v_cvt_pk_bf16_f32 v118, v152, v153
	v_cvt_pk_bf16_f32 v119, v154, v155
	global_store_dwordx4 v[188:189], v[108:111], off
	global_store_dwordx4 v[188:189], v[116:119], off offset:256
	global_store_dwordx4 v[190:191], v[104:107], off
	v_lshlrev_b32_e32 v192, 16, v164
	v_and_b32_e32 v193, 0xffff0000, v164
	v_lshlrev_b32_e32 v104, 16, v165
	v_and_b32_e32 v105, 0xffff0000, v165
	v_pk_mul_f32 v[102:103], v[102:103], v[104:105]
	v_lshlrev_b32_e32 v104, 16, v166
	v_and_b32_e32 v105, 0xffff0000, v166
	v_pk_mul_f32 v[104:105], v[92:93], v[104:105]
	v_lshlrev_b32_e32 v92, 16, v167
	v_and_b32_e32 v93, 0xffff0000, v167
	v_pk_mul_f32 v[100:101], v[100:101], v[192:193]
	v_pk_mul_f32 v[106:107], v[94:95], v[92:93]
	v_cvt_pk_bf16_f32 v92, v100, v101
	v_cvt_pk_bf16_f32 v93, v102, v103
	v_cvt_pk_bf16_f32 v94, v104, v105
	v_cvt_pk_bf16_f32 v95, v106, v107
	global_store_dwordx4 v[190:191], v[92:95], off offset:256
	v_add_u32_e32 v102, 0xb0, v142
	v_ashrrev_i32_e32 v103, 31, v102
	v_lshlrev_b32_e32 v94, 16, v168
	v_and_b32_e32 v95, 0xffff0000, v168
	v_pk_mul_f32 v[94:95], v[96:97], v[94:95]
	v_lshlrev_b32_e32 v96, 16, v169
	v_and_b32_e32 v97, 0xffff0000, v169
	v_pk_mul_f32 v[96:97], v[98:99], v[96:97]
	v_lshlrev_b32_e32 v98, 16, v170
	v_and_b32_e32 v99, 0xffff0000, v170
	v_lshlrev_b64 v[92:93], 11, v[176:177]
	v_pk_mul_f32 v[98:99], v[88:89], v[98:99]
	v_lshlrev_b32_e32 v88, 16, v171
	v_and_b32_e32 v89, 0xffff0000, v171
	v_pk_mul_f32 v[100:101], v[90:91], v[88:89]
	v_lshl_add_u64 v[92:93], s[82:83], 0, v[92:93]
	v_cvt_pk_bf16_f32 v88, v94, v95
	v_cvt_pk_bf16_f32 v89, v96, v97
	v_cvt_pk_bf16_f32 v90, v98, v99
	v_cvt_pk_bf16_f32 v91, v100, v101
	v_lshl_add_u64 v[92:93], v[92:93], 0, v[140:141]
	global_store_dwordx4 v[92:93], v[88:91], off
	v_add_u32_e32 v96, 0x80, v142
	v_ashrrev_i32_e32 v97, 31, v96
	v_lshlrev_b32_e32 v88, 16, v172
	v_and_b32_e32 v89, 0xffff0000, v172
	v_pk_mul_f32 v[84:85], v[84:85], v[88:89]
	v_lshlrev_b32_e32 v88, 16, v173
	v_and_b32_e32 v89, 0xffff0000, v173
	v_pk_mul_f32 v[86:87], v[86:87], v[88:89]
	v_lshlrev_b32_e32 v88, 16, v174
	v_and_b32_e32 v89, 0xffff0000, v174
	v_pk_mul_f32 v[88:89], v[76:77], v[88:89]
	v_lshlrev_b32_e32 v76, 16, v175
	v_and_b32_e32 v77, 0xffff0000, v175
	v_pk_mul_f32 v[90:91], v[78:79], v[76:77]
	v_cvt_pk_bf16_f32 v76, v84, v85
	v_cvt_pk_bf16_f32 v77, v86, v87
	v_cvt_pk_bf16_f32 v78, v88, v89
	v_cvt_pk_bf16_f32 v79, v90, v91
	global_store_dwordx4 v[92:93], v[76:79], off offset:256
	v_add_u32_e32 v98, 0x90, v142
	v_ashrrev_i32_e32 v99, 31, v98
	v_lshlrev_b32_e32 v78, 16, v180
	v_and_b32_e32 v79, 0xffff0000, v180
	v_pk_mul_f32 v[78:79], v[80:81], v[78:79]
	v_lshlrev_b32_e32 v80, 16, v181
	v_and_b32_e32 v81, 0xffff0000, v181
	v_pk_mul_f32 v[80:81], v[82:83], v[80:81]
	v_lshlrev_b32_e32 v82, 16, v182
	v_and_b32_e32 v83, 0xffff0000, v182
	v_lshlrev_b64 v[76:77], 11, v[144:145]
	v_pk_mul_f32 v[82:83], v[72:73], v[82:83]
	v_lshlrev_b32_e32 v72, 16, v183
	v_and_b32_e32 v73, 0xffff0000, v183
	v_pk_mul_f32 v[84:85], v[74:75], v[72:73]
	v_lshl_add_u64 v[76:77], s[82:83], 0, v[76:77]
	v_cvt_pk_bf16_f32 v72, v78, v79
	v_cvt_pk_bf16_f32 v73, v80, v81
	v_cvt_pk_bf16_f32 v74, v82, v83
	v_cvt_pk_bf16_f32 v75, v84, v85
	v_lshl_add_u64 v[76:77], v[76:77], 0, v[140:141]
	global_store_dwordx4 v[76:77], v[72:75], off
	v_add_u32_e32 v100, 0xa0, v142
	v_ashrrev_i32_e32 v101, 31, v100
	v_lshlrev_b32_e32 v72, 16, v184
	v_and_b32_e32 v73, 0xffff0000, v184
	v_pk_mul_f32 v[68:69], v[68:69], v[72:73]
	v_lshlrev_b32_e32 v72, 16, v185
	v_and_b32_e32 v73, 0xffff0000, v185
	v_pk_mul_f32 v[70:71], v[70:71], v[72:73]
	v_lshlrev_b32_e32 v72, 16, v186
	v_and_b32_e32 v73, 0xffff0000, v186
	v_pk_mul_f32 v[72:73], v[64:65], v[72:73]
	v_lshlrev_b32_e32 v64, 16, v187
	v_and_b32_e32 v65, 0xffff0000, v187
	v_pk_mul_f32 v[74:75], v[66:67], v[64:65]
	v_cvt_pk_bf16_f32 v64, v68, v69
	v_cvt_pk_bf16_f32 v65, v70, v71
	v_cvt_pk_bf16_f32 v66, v72, v73
	v_cvt_pk_bf16_f32 v67, v74, v75
	global_store_dwordx4 v[76:77], v[64:67], off offset:256
	s_nop 1
	v_lshlrev_b64 v[64:65], 12, v[96:97]
	v_lshl_add_u64 v[64:65], s[42:43], 0, v[64:65]
	v_lshl_add_u64 v[64:65], v[64:65], 0, v[140:141]
	v_lshlrev_b64 v[64:65], 12, v[98:99]
	v_lshl_add_u64 v[64:65], s[42:43], 0, v[64:65]
	v_lshl_add_u64 v[64:65], v[64:65], 0, v[140:141]
	v_lshlrev_b64 v[64:65], 12, v[100:101]
	v_lshl_add_u64 v[64:65], s[42:43], 0, v[64:65]
	v_lshl_add_u64 v[64:65], v[64:65], 0, v[140:141]
	v_lshlrev_b64 v[64:65], 12, v[102:103]
	v_lshl_add_u64 v[64:65], s[42:43], 0, v[64:65]
	v_lshl_add_u64 v[64:65], v[64:65], 0, v[140:141]
	s_nop 0
	v_lshlrev_b64 v[96:97], 11, v[96:97]
	s_waitcnt vmcnt(8)
	v_lshlrev_b32_e32 v104, 16, v200
	v_and_b32_e32 v105, 0xffff0000, v200
	v_lshlrev_b32_e32 v68, 16, v201
	v_and_b32_e32 v69, 0xffff0000, v201
	v_pk_mul_f32 v[62:63], v[62:63], v[68:69]
	v_lshlrev_b32_e32 v68, 16, v202
	v_and_b32_e32 v69, 0xffff0000, v202
	v_pk_mul_f32 v[60:61], v[60:61], v[104:105]
	v_pk_mul_f32 v[68:69], v[56:57], v[68:69]
	v_lshlrev_b32_e32 v56, 16, v203
	v_and_b32_e32 v57, 0xffff0000, v203
	v_pk_mul_f32 v[70:71], v[58:59], v[56:57]
	v_cvt_pk_bf16_f32 v56, v60, v61
	v_lshl_add_u64 v[60:61], s[82:83], 0, v[96:97]
	v_cvt_pk_bf16_f32 v57, v62, v63
	v_cvt_pk_bf16_f32 v58, v68, v69
	v_cvt_pk_bf16_f32 v59, v70, v71
	v_lshl_add_u64 v[60:61], v[60:61], 0, v[140:141]
	global_store_dwordx4 v[60:61], v[56:59], off
	s_nop 1
	v_lshlrev_b32_e32 v56, 16, v204
	v_and_b32_e32 v57, 0xffff0000, v204
	v_pk_mul_f32 v[52:53], v[52:53], v[56:57]
	v_lshlrev_b32_e32 v56, 16, v205
	v_and_b32_e32 v57, 0xffff0000, v205
	v_pk_mul_f32 v[54:55], v[54:55], v[56:57]
	v_lshlrev_b32_e32 v56, 16, v206
	v_and_b32_e32 v57, 0xffff0000, v206
	v_pk_mul_f32 v[56:57], v[44:45], v[56:57]
	v_lshlrev_b32_e32 v44, 16, v207
	v_and_b32_e32 v45, 0xffff0000, v207
	v_pk_mul_f32 v[58:59], v[46:47], v[44:45]
	v_cvt_pk_bf16_f32 v44, v52, v53
	v_cvt_pk_bf16_f32 v45, v54, v55
	v_cvt_pk_bf16_f32 v46, v56, v57
	v_cvt_pk_bf16_f32 v47, v58, v59
	global_store_dwordx4 v[60:61], v[44:47], off offset:256
	s_nop 1
	v_lshlrev_b32_e32 v46, 16, v208
	v_and_b32_e32 v47, 0xffff0000, v208
	v_pk_mul_f32 v[46:47], v[48:49], v[46:47]
	v_lshlrev_b32_e32 v48, 16, v209
	v_and_b32_e32 v49, 0xffff0000, v209
	v_pk_mul_f32 v[48:49], v[50:51], v[48:49]
	v_lshlrev_b32_e32 v50, 16, v210
	v_and_b32_e32 v51, 0xffff0000, v210
	v_lshlrev_b64 v[44:45], 11, v[98:99]
	v_pk_mul_f32 v[50:51], v[40:41], v[50:51]
	v_lshlrev_b32_e32 v40, 16, v211
	v_and_b32_e32 v41, 0xffff0000, v211
	v_pk_mul_f32 v[52:53], v[42:43], v[40:41]
	v_lshl_add_u64 v[44:45], s[82:83], 0, v[44:45]
	v_cvt_pk_bf16_f32 v40, v46, v47
	v_cvt_pk_bf16_f32 v41, v48, v49
	v_cvt_pk_bf16_f32 v42, v50, v51
	v_cvt_pk_bf16_f32 v43, v52, v53
	v_lshl_add_u64 v[44:45], v[44:45], 0, v[140:141]
	global_store_dwordx4 v[44:45], v[40:43], off
	s_nop 1
	v_lshlrev_b32_e32 v40, 16, v212
	v_and_b32_e32 v41, 0xffff0000, v212
	v_pk_mul_f32 v[36:37], v[36:37], v[40:41]
	v_lshlrev_b32_e32 v40, 16, v213
	v_and_b32_e32 v41, 0xffff0000, v213
	v_pk_mul_f32 v[38:39], v[38:39], v[40:41]
	v_lshlrev_b32_e32 v40, 16, v214
	v_and_b32_e32 v41, 0xffff0000, v214
	v_pk_mul_f32 v[40:41], v[28:29], v[40:41]
	v_lshlrev_b32_e32 v28, 16, v215
	v_and_b32_e32 v29, 0xffff0000, v215
	v_pk_mul_f32 v[42:43], v[30:31], v[28:29]
	v_cvt_pk_bf16_f32 v28, v36, v37
	v_cvt_pk_bf16_f32 v29, v38, v39
	v_cvt_pk_bf16_f32 v30, v40, v41
	v_cvt_pk_bf16_f32 v31, v42, v43
	global_store_dwordx4 v[44:45], v[28:31], off offset:256
	s_nop 1
	v_lshlrev_b32_e32 v30, 16, v216
	v_and_b32_e32 v31, 0xffff0000, v216
	v_pk_mul_f32 v[30:31], v[32:33], v[30:31]
	v_lshlrev_b32_e32 v32, 16, v217
	v_and_b32_e32 v33, 0xffff0000, v217
	v_pk_mul_f32 v[32:33], v[34:35], v[32:33]
	v_lshlrev_b32_e32 v34, 16, v218
	v_and_b32_e32 v35, 0xffff0000, v218
	v_lshlrev_b64 v[28:29], 11, v[100:101]
	v_pk_mul_f32 v[34:35], v[24:25], v[34:35]
	v_lshlrev_b32_e32 v24, 16, v219
	v_and_b32_e32 v25, 0xffff0000, v219
	v_pk_mul_f32 v[36:37], v[26:27], v[24:25]
	v_lshl_add_u64 v[28:29], s[82:83], 0, v[28:29]
	v_cvt_pk_bf16_f32 v24, v30, v31
	v_cvt_pk_bf16_f32 v25, v32, v33
	v_cvt_pk_bf16_f32 v26, v34, v35
	v_cvt_pk_bf16_f32 v27, v36, v37
	v_lshl_add_u64 v[28:29], v[28:29], 0, v[140:141]
	global_store_dwordx4 v[28:29], v[24:27], off
	s_nop 1
	v_lshlrev_b32_e32 v24, 16, v222
	v_and_b32_e32 v25, 0xffff0000, v222
	v_pk_mul_f32 v[20:21], v[20:21], v[24:25]
	v_lshlrev_b32_e32 v24, 16, v223
	v_and_b32_e32 v25, 0xffff0000, v223
	v_pk_mul_f32 v[22:23], v[22:23], v[24:25]
	v_lshlrev_b32_e32 v24, 16, v224
	v_and_b32_e32 v25, 0xffff0000, v224
	v_pk_mul_f32 v[24:25], v[12:13], v[24:25]
	v_lshlrev_b32_e32 v12, 16, v225
	v_and_b32_e32 v13, 0xffff0000, v225
	v_pk_mul_f32 v[26:27], v[14:15], v[12:13]
	v_cvt_pk_bf16_f32 v12, v20, v21
	v_cvt_pk_bf16_f32 v13, v22, v23
	v_cvt_pk_bf16_f32 v14, v24, v25
	v_cvt_pk_bf16_f32 v15, v26, v27
	global_store_dwordx4 v[28:29], v[12:15], off offset:256
	s_nop 1
	v_lshlrev_b32_e32 v14, 16, v226
	v_and_b32_e32 v15, 0xffff0000, v226
	v_pk_mul_f32 v[14:15], v[16:17], v[14:15]
	v_lshlrev_b32_e32 v16, 16, v227
	v_and_b32_e32 v17, 0xffff0000, v227
	v_pk_mul_f32 v[16:17], v[18:19], v[16:17]
	v_lshlrev_b32_e32 v18, 16, v228
	v_and_b32_e32 v19, 0xffff0000, v228
	v_lshlrev_b64 v[12:13], 11, v[102:103]
	v_pk_mul_f32 v[18:19], v[8:9], v[18:19]
	v_lshlrev_b32_e32 v8, 16, v229
	v_and_b32_e32 v9, 0xffff0000, v229
	v_pk_mul_f32 v[20:21], v[10:11], v[8:9]
	v_lshl_add_u64 v[12:13], s[82:83], 0, v[12:13]
	v_cvt_pk_bf16_f32 v8, v14, v15
	v_cvt_pk_bf16_f32 v9, v16, v17
	v_cvt_pk_bf16_f32 v10, v18, v19
	v_cvt_pk_bf16_f32 v11, v20, v21
	v_lshl_add_u64 v[12:13], v[12:13], 0, v[140:141]
	global_store_dwordx4 v[12:13], v[8:11], off
	s_nop 1
	v_lshlrev_b32_e32 v8, 16, v230
	v_and_b32_e32 v9, 0xffff0000, v230
	v_pk_mul_f32 v[4:5], v[4:5], v[8:9]
	v_lshlrev_b32_e32 v8, 16, v231
	v_and_b32_e32 v9, 0xffff0000, v231
	v_pk_mul_f32 v[6:7], v[6:7], v[8:9]
	v_lshlrev_b32_e32 v8, 16, v232
	v_and_b32_e32 v9, 0xffff0000, v232
	v_pk_mul_f32 v[8:9], v[0:1], v[8:9]
	v_lshlrev_b32_e32 v0, 16, v233
	v_and_b32_e32 v1, 0xffff0000, v233
	v_pk_mul_f32 v[10:11], v[2:3], v[0:1]
	v_cvt_pk_bf16_f32 v0, v4, v5
	v_cvt_pk_bf16_f32 v1, v6, v7
	v_cvt_pk_bf16_f32 v2, v8, v9
	v_cvt_pk_bf16_f32 v3, v10, v11
	global_store_dwordx4 v[12:13], v[0:3], off offset:256
	s_cbranch_vccz .LBB0_1260
	s_waitcnt vmcnt(0)
	s_cmpk_gt_u32 s26, 0xff
	s_cbranch_scc1 .LBB0_1272
	s_barrier

.LBB0_1285:
	ds_read_b128 v[144:147], v176
	ds_read_b128 v[148:151], v176 offset:1024
	ds_read_b128 v[164:167], v176 offset:2048
	ds_read_b128 v[168:171], v176 offset:3072
	ds_read_b128 v[180:183], v176 offset:4096
	ds_read_b128 v[184:187], v176 offset:5120
	ds_read_b128 v[188:191], v176 offset:6144
	ds_read_b128 v[192:195], v176 offset:7168
	ds_read_b128 v[128:131], v175
	ds_read_b128 v[132:135], v175 offset:1024
	ds_read_b128 v[136:139], v175 offset:2048
	ds_read_b128 v[140:143], v175 offset:3072
	s_add_u32 s22, s10, 0xfffe0080
	s_addc_u32 s23, s11, -1
	s_cmp_eq_u32 s43, 4
	s_cselect_b32 s25, s13, s23
	s_cselect_b32 s24, s39, s22
	s_cselect_b32 s23, s15, s42
	s_cselect_b32 s22, s40, s41
	v_lshl_add_u64 v[196:197], s[10:11], 0, v[160:161]
	s_add_i32 m0, s1, 0xc000
	s_nop 0
	global_load_lds_dwordx4 v[196:197], off
	v_lshl_add_u64 v[196:197], s[10:11], 0, v[162:163]
	s_add_i32 m0, s1, 0xe000
	s_nop 0
	global_load_lds_dwordx4 v[196:197], off
	s_waitcnt lgkmcnt(0)
	s_barrier
	s_waitcnt lgkmcnt(0)
	v_mfma_f32_16x16x32_bf16 v[124:127], v[128:131], v[144:147], v[124:127]
	v_mfma_f32_16x16x32_bf16 v[120:123], v[136:139], v[144:147], v[120:123]
	v_mfma_f32_16x16x32_bf16 v[108:111], v[128:131], v[164:167], v[108:111]
	v_mfma_f32_16x16x32_bf16 v[104:107], v[136:139], v[164:167], v[104:107]
	v_mfma_f32_16x16x32_bf16 v[92:95], v[128:131], v[180:183], v[92:95]
	v_mfma_f32_16x16x32_bf16 v[88:91], v[136:139], v[180:183], v[88:91]
	v_mfma_f32_16x16x32_bf16 v[76:79], v[128:131], v[188:191], v[76:79]
	v_mfma_f32_16x16x32_bf16 v[72:75], v[136:139], v[188:191], v[72:75]
	v_mfma_f32_16x16x32_bf16 v[124:127], v[132:135], v[148:151], v[124:127]
	v_mfma_f32_16x16x32_bf16 v[120:123], v[140:143], v[148:151], v[120:123]
	v_mfma_f32_16x16x32_bf16 v[108:111], v[132:135], v[168:171], v[108:111]
	v_mfma_f32_16x16x32_bf16 v[104:107], v[140:143], v[168:171], v[104:107]
	v_mfma_f32_16x16x32_bf16 v[92:95], v[132:135], v[184:187], v[92:95]
	v_mfma_f32_16x16x32_bf16 v[88:91], v[140:143], v[184:187], v[88:91]
	v_mfma_f32_16x16x32_bf16 v[76:79], v[132:135], v[192:195], v[76:79]
	v_mfma_f32_16x16x32_bf16 v[72:75], v[140:143], v[192:195], v[72:75]
	s_barrier
	s_add_i32 s44, s35, s27
	v_lshl_add_u64 v[212:213], s[22:23], 0, v[156:157]
	s_mov_b32 m0, s44
	ds_read_b128 v[196:199], v177
	ds_read_b128 v[200:203], v177 offset:1024
	ds_read_b128 v[204:207], v177 offset:2048
	ds_read_b128 v[208:211], v177 offset:3072
	global_load_lds_dwordx4 v[212:213], off
	v_lshl_add_u64 v[214:215], s[22:23], 0, v[152:153]
	s_add_i32 m0, s44, 0x2000
	s_nop 0
	global_load_lds_dwordx4 v[214:215], off
	s_barrier
	s_waitcnt lgkmcnt(0)
	v_mfma_f32_16x16x32_bf16 v[116:119], v[196:199], v[144:147], v[116:119]
	v_mfma_f32_16x16x32_bf16 v[112:115], v[204:207], v[144:147], v[112:115]
	v_mfma_f32_16x16x32_bf16 v[100:103], v[196:199], v[164:167], v[100:103]
	v_mfma_f32_16x16x32_bf16 v[96:99], v[204:207], v[164:167], v[96:99]
	v_mfma_f32_16x16x32_bf16 v[84:87], v[196:199], v[180:183], v[84:87]
	v_mfma_f32_16x16x32_bf16 v[80:83], v[204:207], v[180:183], v[80:83]
	v_mfma_f32_16x16x32_bf16 v[68:71], v[196:199], v[188:191], v[68:71]
	v_mfma_f32_16x16x32_bf16 v[64:67], v[204:207], v[188:191], v[64:67]
	v_mfma_f32_16x16x32_bf16 v[116:119], v[200:203], v[148:151], v[116:119]
	v_mfma_f32_16x16x32_bf16 v[112:115], v[208:211], v[148:151], v[112:115]
	v_mfma_f32_16x16x32_bf16 v[100:103], v[200:203], v[168:171], v[100:103]
	v_mfma_f32_16x16x32_bf16 v[96:99], v[208:211], v[168:171], v[96:99]
	v_mfma_f32_16x16x32_bf16 v[84:87], v[200:203], v[184:187], v[84:87]
	v_mfma_f32_16x16x32_bf16 v[80:83], v[208:211], v[184:187], v[80:83]
	v_mfma_f32_16x16x32_bf16 v[68:71], v[200:203], v[192:195], v[68:71]
	v_mfma_f32_16x16x32_bf16 v[64:67], v[208:211], v[192:195], v[64:67]
	s_mov_b32 m0, s1
	v_lshl_add_u64 v[216:217], s[24:25], 0, v[158:159]
	s_barrier
	ds_read_b128 v[144:147], v176 offset:16384
	ds_read_b128 v[148:151], v176 offset:17408
	ds_read_b128 v[164:167], v176 offset:18432
	ds_read_b128 v[168:171], v176 offset:19456
	ds_read_b128 v[180:183], v176 offset:20480
	ds_read_b128 v[184:187], v176 offset:21504
	ds_read_b128 v[188:191], v176 offset:22528
	ds_read_b128 v[192:195], v176 offset:23552
	global_load_lds_dwordx4 v[216:217], off
	v_lshl_add_u64 v[218:219], s[24:25], 0, v[154:155]
	s_mov_b32 m0, s7
	s_nop 0
	global_load_lds_dwordx4 v[218:219], off
	s_barrier
	s_waitcnt lgkmcnt(0)
	v_mfma_f32_16x16x32_bf16 v[60:63], v[128:131], v[144:147], v[60:63]
	v_mfma_f32_16x16x32_bf16 v[56:59], v[136:139], v[144:147], v[56:59]
	v_mfma_f32_16x16x32_bf16 v[44:47], v[128:131], v[164:167], v[44:47]
	v_mfma_f32_16x16x32_bf16 v[40:43], v[136:139], v[164:167], v[40:43]
	v_mfma_f32_16x16x32_bf16 v[28:31], v[128:131], v[180:183], v[28:31]
	v_mfma_f32_16x16x32_bf16 v[24:27], v[136:139], v[180:183], v[24:27]
	v_mfma_f32_16x16x32_bf16 v[12:15], v[128:131], v[188:191], v[12:15]
	v_mfma_f32_16x16x32_bf16 v[8:11], v[136:139], v[188:191], v[8:11]
	v_mfma_f32_16x16x32_bf16 v[60:63], v[132:135], v[148:151], v[60:63]
	v_mfma_f32_16x16x32_bf16 v[56:59], v[140:143], v[148:151], v[56:59]
	v_mfma_f32_16x16x32_bf16 v[44:47], v[132:135], v[168:171], v[44:47]
	v_mfma_f32_16x16x32_bf16 v[40:43], v[140:143], v[168:171], v[40:43]
	v_mfma_f32_16x16x32_bf16 v[28:31], v[132:135], v[184:187], v[28:31]
	v_mfma_f32_16x16x32_bf16 v[24:27], v[140:143], v[184:187], v[24:27]
	v_mfma_f32_16x16x32_bf16 v[12:15], v[132:135], v[192:195], v[12:15]
	v_mfma_f32_16x16x32_bf16 v[8:11], v[140:143], v[192:195], v[8:11]
	s_barrier
	s_add_u32 s44, s22, 0x20000
	s_addc_u32 s45, s23, 0
	s_add_i32 s46, s36, s27
	v_lshl_add_u64 v[128:129], s[44:45], 0, v[156:157]
	s_mov_b32 m0, s46
	s_nop 0
	global_load_lds_dwordx4 v[128:129], off
	v_lshl_add_u64 v[128:129], s[44:45], 0, v[152:153]
	s_add_i32 m0, s46, 0x2000
	s_nop 0
	global_load_lds_dwordx4 v[128:129], off
	s_waitcnt vmcnt(6)
	s_barrier
	v_mfma_f32_16x16x32_bf16 v[52:55], v[196:199], v[144:147], v[52:55]
	v_mfma_f32_16x16x32_bf16 v[48:51], v[204:207], v[144:147], v[48:51]
	v_mfma_f32_16x16x32_bf16 v[36:39], v[196:199], v[164:167], v[36:39]
	v_mfma_f32_16x16x32_bf16 v[32:35], v[204:207], v[164:167], v[32:35]
	v_mfma_f32_16x16x32_bf16 v[20:23], v[196:199], v[180:183], v[20:23]
	v_mfma_f32_16x16x32_bf16 v[16:19], v[204:207], v[180:183], v[16:19]
	v_mfma_f32_16x16x32_bf16 v[4:7], v[196:199], v[188:191], v[4:7]
	v_mfma_f32_16x16x32_bf16 v[0:3], v[204:207], v[188:191], v[0:3]
	v_mfma_f32_16x16x32_bf16 v[52:55], v[200:203], v[148:151], v[52:55]
	v_mfma_f32_16x16x32_bf16 v[48:51], v[208:211], v[148:151], v[48:51]
	v_mfma_f32_16x16x32_bf16 v[36:39], v[200:203], v[168:171], v[36:39]
	v_mfma_f32_16x16x32_bf16 v[32:35], v[208:211], v[168:171], v[32:35]
	v_mfma_f32_16x16x32_bf16 v[20:23], v[200:203], v[184:187], v[20:23]
	v_mfma_f32_16x16x32_bf16 v[16:19], v[208:211], v[184:187], v[16:19]
	v_mfma_f32_16x16x32_bf16 v[4:7], v[200:203], v[192:195], v[4:7]
	v_mfma_f32_16x16x32_bf16 v[0:3], v[208:211], v[192:195], v[0:3]
	s_add_i32 s44, 0, 0x18000
	v_add_u32_e32 v140, s44, v173
	s_barrier
	ds_read_b128 v[144:147], v176 offset:32768
	ds_read_b128 v[148:151], v176 offset:33792
	ds_read_b128 v[164:167], v176 offset:34816
	ds_read_b128 v[168:171], v176 offset:35840
	ds_read_b128 v[180:183], v176 offset:36864
	ds_read_b128 v[184:187], v176 offset:37888
	ds_read_b128 v[188:191], v176 offset:38912
	ds_read_b128 v[192:195], v176 offset:39936
	ds_read_b128 v[128:131], v140
	ds_read_b128 v[132:135], v140 offset:1024
	ds_read_b128 v[136:139], v140 offset:2048
	ds_read_b128 v[140:143], v140 offset:3072
	s_add_u32 s24, s24, 0x20000
	s_addc_u32 s25, s25, 0
	s_mov_b32 m0, s28
	v_lshl_add_u64 v[196:197], s[24:25], 0, v[158:159]
	global_load_lds_dwordx4 v[196:197], off
	v_lshl_add_u64 v[196:197], s[24:25], 0, v[154:155]
	s_mov_b32 m0, s29
	s_nop 0
	global_load_lds_dwordx4 v[196:197], off
	s_waitcnt lgkmcnt(0)
	s_barrier
	s_waitcnt lgkmcnt(0)
	v_mfma_f32_16x16x32_bf16 v[124:127], v[128:131], v[144:147], v[124:127]
	v_mfma_f32_16x16x32_bf16 v[120:123], v[136:139], v[144:147], v[120:123]
	v_mfma_f32_16x16x32_bf16 v[108:111], v[128:131], v[164:167], v[108:111]
	v_mfma_f32_16x16x32_bf16 v[104:107], v[136:139], v[164:167], v[104:107]
	v_mfma_f32_16x16x32_bf16 v[92:95], v[128:131], v[180:183], v[92:95]
	v_mfma_f32_16x16x32_bf16 v[88:91], v[136:139], v[180:183], v[88:91]
	v_mfma_f32_16x16x32_bf16 v[76:79], v[128:131], v[188:191], v[76:79]
	v_mfma_f32_16x16x32_bf16 v[72:75], v[136:139], v[188:191], v[72:75]
	v_mfma_f32_16x16x32_bf16 v[124:127], v[132:135], v[148:151], v[124:127]
	v_mfma_f32_16x16x32_bf16 v[120:123], v[140:143], v[148:151], v[120:123]
	v_mfma_f32_16x16x32_bf16 v[108:111], v[132:135], v[168:171], v[108:111]
	v_mfma_f32_16x16x32_bf16 v[104:107], v[140:143], v[168:171], v[104:107]
	v_mfma_f32_16x16x32_bf16 v[92:95], v[132:135], v[184:187], v[92:95]
	v_mfma_f32_16x16x32_bf16 v[88:91], v[140:143], v[184:187], v[88:91]
	v_mfma_f32_16x16x32_bf16 v[76:79], v[132:135], v[192:195], v[76:79]
	v_mfma_f32_16x16x32_bf16 v[72:75], v[140:143], v[192:195], v[72:75]
	s_barrier
	s_add_i32 s24, 0, 0x1c000
	s_add_i32 s25, s44, s27
	v_add_u32_e32 v179, s24, v173
	v_lshl_add_u64 v[212:213], v[212:213], 0, s[4:5]
	s_mov_b32 m0, s25
	ds_read_b128 v[196:199], v179
	ds_read_b128 v[200:203], v179 offset:1024
	ds_read_b128 v[204:207], v179 offset:2048
	ds_read_b128 v[208:211], v179 offset:3072
	global_load_lds_dwordx4 v[212:213], off
	v_lshl_add_u64 v[212:213], v[214:215], 0, s[4:5]
	s_add_i32 m0, s25, 0x2000
	s_nop 0
	global_load_lds_dwordx4 v[212:213], off
	s_barrier
	s_waitcnt lgkmcnt(0)
	v_mfma_f32_16x16x32_bf16 v[116:119], v[196:199], v[144:147], v[116:119]
	v_mfma_f32_16x16x32_bf16 v[112:115], v[204:207], v[144:147], v[112:115]
	v_mfma_f32_16x16x32_bf16 v[100:103], v[196:199], v[164:167], v[100:103]
	v_mfma_f32_16x16x32_bf16 v[96:99], v[204:207], v[164:167], v[96:99]
	v_mfma_f32_16x16x32_bf16 v[84:87], v[196:199], v[180:183], v[84:87]
	v_mfma_f32_16x16x32_bf16 v[80:83], v[204:207], v[180:183], v[80:83]
	v_mfma_f32_16x16x32_bf16 v[68:71], v[196:199], v[188:191], v[68:71]
	v_mfma_f32_16x16x32_bf16 v[64:67], v[204:207], v[188:191], v[64:67]
	v_mfma_f32_16x16x32_bf16 v[116:119], v[200:203], v[148:151], v[116:119]
	v_mfma_f32_16x16x32_bf16 v[112:115], v[208:211], v[148:151], v[112:115]
	v_mfma_f32_16x16x32_bf16 v[100:103], v[200:203], v[168:171], v[100:103]
	v_mfma_f32_16x16x32_bf16 v[96:99], v[208:211], v[168:171], v[96:99]
	v_mfma_f32_16x16x32_bf16 v[84:87], v[200:203], v[184:187], v[84:87]
	v_mfma_f32_16x16x32_bf16 v[80:83], v[208:211], v[184:187], v[80:83]
	v_mfma_f32_16x16x32_bf16 v[68:71], v[200:203], v[192:195], v[68:71]
	v_mfma_f32_16x16x32_bf16 v[64:67], v[208:211], v[192:195], v[64:67]
	s_mov_b32 m0, s31
	v_lshl_add_u64 v[212:213], v[216:217], 0, s[4:5]
	s_barrier
	ds_read_b128 v[144:147], v176 offset:49152
	ds_read_b128 v[148:151], v176 offset:50176
	ds_read_b128 v[164:167], v176 offset:51200
	ds_read_b128 v[168:171], v176 offset:52224
	ds_read_b128 v[180:183], v176 offset:53248
	ds_read_b128 v[184:187], v176 offset:54272
	ds_read_b128 v[188:191], v176 offset:55296
	ds_read_b128 v[192:195], v176 offset:56320
	global_load_lds_dwordx4 v[212:213], off
	v_lshl_add_u64 v[212:213], v[218:219], 0, s[4:5]
	s_mov_b32 m0, s33
	s_nop 0
	global_load_lds_dwordx4 v[212:213], off
	s_barrier
	s_waitcnt lgkmcnt(0)
	v_mfma_f32_16x16x32_bf16 v[60:63], v[128:131], v[144:147], v[60:63]
	v_mfma_f32_16x16x32_bf16 v[56:59], v[136:139], v[144:147], v[56:59]
	v_mfma_f32_16x16x32_bf16 v[44:47], v[128:131], v[164:167], v[44:47]
	v_mfma_f32_16x16x32_bf16 v[40:43], v[136:139], v[164:167], v[40:43]
	v_mfma_f32_16x16x32_bf16 v[28:31], v[128:131], v[180:183], v[28:31]
	v_mfma_f32_16x16x32_bf16 v[24:27], v[136:139], v[180:183], v[24:27]
	v_mfma_f32_16x16x32_bf16 v[12:15], v[128:131], v[188:191], v[12:15]
	v_mfma_f32_16x16x32_bf16 v[8:11], v[136:139], v[188:191], v[8:11]
	v_mfma_f32_16x16x32_bf16 v[60:63], v[132:135], v[148:151], v[60:63]
	v_mfma_f32_16x16x32_bf16 v[56:59], v[140:143], v[148:151], v[56:59]
	v_mfma_f32_16x16x32_bf16 v[44:47], v[132:135], v[168:171], v[44:47]
	v_mfma_f32_16x16x32_bf16 v[40:43], v[140:143], v[168:171], v[40:43]
	v_mfma_f32_16x16x32_bf16 v[28:31], v[132:135], v[184:187], v[28:31]
	v_mfma_f32_16x16x32_bf16 v[24:27], v[140:143], v[184:187], v[24:27]
	v_mfma_f32_16x16x32_bf16 v[12:15], v[132:135], v[192:195], v[12:15]
	v_mfma_f32_16x16x32_bf16 v[8:11], v[140:143], v[192:195], v[8:11]
	s_barrier
	s_add_u32 s22, s22, 0x20080
	s_addc_u32 s23, s23, 0
	s_add_i32 s24, s24, s27
	v_lshl_add_u64 v[128:129], s[22:23], 0, v[156:157]
	s_mov_b32 m0, s24
	s_nop 0
	global_load_lds_dwordx4 v[128:129], off
	v_lshl_add_u64 v[128:129], s[22:23], 0, v[152:153]
	s_add_i32 m0, s24, 0x2000
	s_nop 0
	global_load_lds_dwordx4 v[128:129], off
	s_waitcnt vmcnt(6)
	s_barrier
	v_mfma_f32_16x16x32_bf16 v[52:55], v[196:199], v[144:147], v[52:55]
	v_mfma_f32_16x16x32_bf16 v[48:51], v[204:207], v[144:147], v[48:51]
	v_mfma_f32_16x16x32_bf16 v[36:39], v[196:199], v[164:167], v[36:39]
	v_mfma_f32_16x16x32_bf16 v[32:35], v[204:207], v[164:167], v[32:35]
	v_mfma_f32_16x16x32_bf16 v[20:23], v[196:199], v[180:183], v[20:23]
	v_mfma_f32_16x16x32_bf16 v[16:19], v[204:207], v[180:183], v[16:19]
	v_mfma_f32_16x16x32_bf16 v[4:7], v[196:199], v[188:191], v[4:7]
	v_mfma_f32_16x16x32_bf16 v[0:3], v[204:207], v[188:191], v[0:3]
	v_mfma_f32_16x16x32_bf16 v[52:55], v[200:203], v[148:151], v[52:55]
	v_mfma_f32_16x16x32_bf16 v[48:51], v[208:211], v[148:151], v[48:51]
	v_mfma_f32_16x16x32_bf16 v[36:39], v[200:203], v[168:171], v[36:39]
	v_mfma_f32_16x16x32_bf16 v[32:35], v[208:211], v[168:171], v[32:35]
	v_mfma_f32_16x16x32_bf16 v[20:23], v[200:203], v[184:187], v[20:23]
	v_mfma_f32_16x16x32_bf16 v[16:19], v[208:211], v[184:187], v[16:19]
	v_mfma_f32_16x16x32_bf16 v[4:7], v[200:203], v[192:195], v[4:7]
	v_mfma_f32_16x16x32_bf16 v[0:3], v[208:211], v[192:195], v[0:3]
	s_add_i32 s43, s43, 2
	s_add_u32 s10, s10, 0x100
	s_addc_u32 s11, s11, 0
	s_add_u32 s41, s41, 0x100
	s_addc_u32 s42, s42, 0
	s_cmp_gt_u32 s43, 5
	s_barrier
	s_cbranch_scc0 .LBB0_1285
	v_lshl_add_u32 v164, s38, 8, v172
	s_nop 0
	v_lshl_or_b32 v128, s0, 8, v174
	v_ashrrev_i32_e32 v165, 31, v164
	s_nop 1
	v_readlane_b32 s46, v252, 13
	v_readlane_b32 s47, v252, 14
	v_ashrrev_i32_e32 v129, 31, v128
	v_lshlrev_b64 v[130:131], 12, v[164:165]
	s_mov_b64 s[42:43], s[46:47]
	v_lshl_add_u64 v[130:131], s[42:43], 0, v[130:131]
	v_lshlrev_b64 v[132:133], 11, v[164:165]
	v_lshlrev_b64 v[166:167], 1, v[128:129]
	v_lshl_add_u64 v[132:133], s[82:83], 0, v[132:133]
	v_lshl_add_u64 v[128:129], v[130:131], 0, v[166:167]
	global_load_dwordx4 v[180:183], v[128:129], off offset:2048
	v_lshl_add_u64 v[222:223], v[132:133], 0, v[166:167]
	global_load_dwordx4 v[184:187], v[222:223], off
	global_load_dwordx4 v[188:191], v[128:129], off offset:2304
	global_load_dwordx4 v[192:195], v[222:223], off offset:256
	v_or_b32_e32 v128, 16, v164
	v_ashrrev_i32_e32 v129, 31, v128
	v_lshlrev_b64 v[130:131], 12, v[128:129]
	v_lshlrev_b64 v[128:129], 11, v[128:129]
	v_lshl_add_u64 v[130:131], s[42:43], 0, v[130:131]
	v_lshl_add_u64 v[128:129], s[82:83], 0, v[128:129]
	v_lshl_add_u64 v[130:131], v[130:131], 0, v[166:167]
	v_lshl_add_u64 v[224:225], v[128:129], 0, v[166:167]
	global_load_dwordx4 v[196:199], v[130:131], off offset:2048
	global_load_dwordx4 v[200:203], v[224:225], off
	v_or_b32_e32 v128, 32, v164
	v_or_b32_e32 v132, 48, v164
	v_ashrrev_i32_e32 v129, 31, v128
	v_ashrrev_i32_e32 v133, 31, v132
	v_lshlrev_b64 v[134:135], 12, v[128:129]
	v_lshlrev_b64 v[128:129], 11, v[128:129]
	v_lshlrev_b64 v[136:137], 12, v[132:133]
	v_lshlrev_b64 v[132:133], 11, v[132:133]
	v_lshl_add_u64 v[134:135], s[42:43], 0, v[134:135]
	v_lshl_add_u64 v[128:129], s[82:83], 0, v[128:129]
	v_lshl_add_u64 v[136:137], s[42:43], 0, v[136:137]
	v_lshl_add_u64 v[132:133], s[82:83], 0, v[132:133]
	v_lshl_add_u64 v[134:135], v[134:135], 0, v[166:167]
	v_lshl_add_u64 v[170:171], v[128:129], 0, v[166:167]
	v_lshl_add_u64 v[128:129], v[136:137], 0, v[166:167]
	v_lshl_add_u64 v[168:169], v[132:133], 0, v[166:167]
	global_load_dwordx4 v[204:207], v[130:131], off offset:2304
	global_load_dwordx4 v[208:211], v[224:225], off offset:256
	global_load_dwordx4 v[212:215], v[134:135], off offset:2048
	global_load_dwordx4 v[148:151], v[134:135], off offset:2304
	global_load_dwordx4 v[216:219], v[170:171], off
	global_load_dwordx4 v[144:147], v[170:171], off offset:256
	global_load_dwordx4 v[140:143], v[128:129], off offset:2048
	s_nop 0
	global_load_dwordx4 v[132:135], v[128:129], off offset:2304
	global_load_dwordx4 v[136:139], v[168:169], off
	s_nop 0
	global_load_dwordx4 v[128:131], v[168:169], off offset:256
	s_and_b64 vcc, exec, s[18:19]
	s_mov_b32 s0, s14
	s_mov_b32 s38, s12
	s_mov_b32 s15, s14
	s_mov_b32 s18, s12
	s_mov_b64 s[22:23], s[20:21]
	s_mov_b64 s[10:11], s[16:17]
	s_mov_b32 s13, s37
	s_nop 7
	s_nop 2
	s_waitcnt vmcnt(0)
	v_lshlrev_b32_e32 v228, 16, v184
	v_lshlrev_b32_e32 v226, 16, v180
	v_and_b32_e32 v227, 0xffff0000, v180
	v_and_b32_e32 v229, 0xffff0000, v184
	v_lshlrev_b32_e32 v180, 16, v181
	v_and_b32_e32 v181, 0xffff0000, v181
	v_lshlrev_b32_e32 v184, 16, v185
	v_and_b32_e32 v185, 0xffff0000, v185
	v_lshlrev_b32_e32 v230, 16, v182
	v_and_b32_e32 v231, 0xffff0000, v182
	v_lshlrev_b32_e32 v232, 16, v186
	v_and_b32_e32 v233, 0xffff0000, v186
	v_lshlrev_b32_e32 v182, 16, v183
	v_and_b32_e32 v183, 0xffff0000, v183
	v_lshlrev_b32_e32 v186, 16, v187
	v_and_b32_e32 v187, 0xffff0000, v187
	v_lshlrev_b32_e32 v234, 16, v188
	v_and_b32_e32 v235, 0xffff0000, v188
	v_lshlrev_b32_e32 v236, 16, v192
	v_and_b32_e32 v237, 0xffff0000, v192
	v_lshlrev_b32_e32 v188, 16, v189
	v_and_b32_e32 v189, 0xffff0000, v189
	v_lshlrev_b32_e32 v192, 16, v193
	v_and_b32_e32 v193, 0xffff0000, v193
	v_pk_fma_f32 v[124:125], v[124:125], v[226:227], v[228:229]
	v_pk_fma_f32 v[126:127], v[126:127], v[180:181], v[184:185]
	v_pk_fma_f32 v[120:121], v[120:121], v[230:231], v[232:233]
	v_pk_fma_f32 v[122:123], v[122:123], v[182:183], v[186:187]
	v_lshlrev_b32_e32 v238, 16, v190
	v_and_b32_e32 v239, 0xffff0000, v190
	v_lshlrev_b32_e32 v240, 16, v194
	v_pk_fma_f32 v[180:181], v[116:117], v[234:235], v[236:237]
	v_pk_fma_f32 v[182:183], v[118:119], v[188:189], v[192:193]
	v_cvt_pk_bf16_f32 v116, v124, v125
	v_cvt_pk_bf16_f32 v117, v126, v127
	v_cvt_pk_bf16_f32 v118, v120, v121
	v_cvt_pk_bf16_f32 v119, v122, v123
	v_and_b32_e32 v241, 0xffff0000, v194
	global_store_dwordx4 v[222:223], v[116:119], off
	s_nop 1
	v_pk_fma_f32 v[116:117], v[112:113], v[238:239], v[240:241]
	v_lshlrev_b32_e32 v112, 16, v191
	v_and_b32_e32 v113, 0xffff0000, v191
	v_lshlrev_b32_e32 v118, 16, v195
	v_and_b32_e32 v119, 0xffff0000, v195
	v_pk_fma_f32 v[118:119], v[114:115], v[112:113], v[118:119]
	v_cvt_pk_bf16_f32 v112, v180, v181
	v_cvt_pk_bf16_f32 v113, v182, v183
	v_cvt_pk_bf16_f32 v114, v116, v117
	v_cvt_pk_bf16_f32 v115, v118, v119
	global_store_dwordx4 v[222:223], v[112:115], off offset:256
	s_nop 1
	v_lshlrev_b32_e32 v112, 16, v196
	v_and_b32_e32 v113, 0xffff0000, v196
	v_lshlrev_b32_e32 v114, 16, v200
	v_and_b32_e32 v115, 0xffff0000, v200
	v_pk_fma_f32 v[108:109], v[108:109], v[112:113], v[114:115]
	v_lshlrev_b32_e32 v112, 16, v197
	v_and_b32_e32 v113, 0xffff0000, v197
	v_lshlrev_b32_e32 v114, 16, v201
	v_and_b32_e32 v115, 0xffff0000, v201
	v_pk_fma_f32 v[110:111], v[110:111], v[112:113], v[114:115]
	v_lshlrev_b32_e32 v112, 16, v198
	v_and_b32_e32 v113, 0xffff0000, v198
	v_lshlrev_b32_e32 v114, 16, v202
	v_and_b32_e32 v115, 0xffff0000, v202
	v_pk_fma_f32 v[112:113], v[104:105], v[112:113], v[114:115]
	v_lshlrev_b32_e32 v104, 16, v199
	v_and_b32_e32 v105, 0xffff0000, v199
	v_lshlrev_b32_e32 v114, 16, v203
	v_and_b32_e32 v115, 0xffff0000, v203
	v_pk_fma_f32 v[114:115], v[106:107], v[104:105], v[114:115]
	v_cvt_pk_bf16_f32 v104, v108, v109
	v_cvt_pk_bf16_f32 v105, v110, v111
	v_cvt_pk_bf16_f32 v106, v112, v113
	v_cvt_pk_bf16_f32 v107, v114, v115
	global_store_dwordx4 v[224:225], v[104:107], off
	s_nop 1
	v_lshlrev_b32_e32 v104, 16, v204
	v_and_b32_e32 v105, 0xffff0000, v204
	v_lshlrev_b32_e32 v106, 16, v208
	v_and_b32_e32 v107, 0xffff0000, v208
	v_pk_fma_f32 v[100:101], v[100:101], v[104:105], v[106:107]
	v_lshlrev_b32_e32 v104, 16, v205
	v_and_b32_e32 v105, 0xffff0000, v205
	v_lshlrev_b32_e32 v106, 16, v209
	v_and_b32_e32 v107, 0xffff0000, v209
	v_pk_fma_f32 v[102:103], v[102:103], v[104:105], v[106:107]
	v_lshlrev_b32_e32 v104, 16, v206
	v_and_b32_e32 v105, 0xffff0000, v206
	v_lshlrev_b32_e32 v106, 16, v210
	v_and_b32_e32 v107, 0xffff0000, v210
	v_pk_fma_f32 v[104:105], v[96:97], v[104:105], v[106:107]
	v_lshlrev_b32_e32 v96, 16, v207
	v_and_b32_e32 v97, 0xffff0000, v207
	v_lshlrev_b32_e32 v106, 16, v211
	v_and_b32_e32 v107, 0xffff0000, v211
	v_pk_fma_f32 v[106:107], v[98:99], v[96:97], v[106:107]
	v_cvt_pk_bf16_f32 v96, v100, v101
	v_cvt_pk_bf16_f32 v97, v102, v103
	v_cvt_pk_bf16_f32 v98, v104, v105
	v_cvt_pk_bf16_f32 v99, v106, v107
	global_store_dwordx4 v[224:225], v[96:99], off offset:256
	s_nop 1
	v_lshlrev_b32_e32 v96, 16, v212
	v_and_b32_e32 v97, 0xffff0000, v212
	v_lshlrev_b32_e32 v98, 16, v216
	v_and_b32_e32 v99, 0xffff0000, v216
	v_pk_fma_f32 v[92:93], v[92:93], v[96:97], v[98:99]
	v_lshlrev_b32_e32 v96, 16, v213
	v_and_b32_e32 v97, 0xffff0000, v213
	v_lshlrev_b32_e32 v98, 16, v217
	v_and_b32_e32 v99, 0xffff0000, v217
	v_pk_fma_f32 v[94:95], v[94:95], v[96:97], v[98:99]
	v_lshlrev_b32_e32 v96, 16, v214
	v_and_b32_e32 v97, 0xffff0000, v214
	v_lshlrev_b32_e32 v98, 16, v218
	v_and_b32_e32 v99, 0xffff0000, v218
	v_pk_fma_f32 v[96:97], v[88:89], v[96:97], v[98:99]
	v_lshlrev_b32_e32 v88, 16, v215
	v_and_b32_e32 v89, 0xffff0000, v215
	v_lshlrev_b32_e32 v98, 16, v219
	v_and_b32_e32 v99, 0xffff0000, v219
	v_pk_fma_f32 v[98:99], v[90:91], v[88:89], v[98:99]
	v_cvt_pk_bf16_f32 v88, v92, v93
	v_cvt_pk_bf16_f32 v89, v94, v95
	v_cvt_pk_bf16_f32 v90, v96, v97
	v_cvt_pk_bf16_f32 v91, v98, v99
	global_store_dwordx4 v[170:171], v[88:91], off
	s_nop 1
	v_lshlrev_b32_e32 v88, 16, v148
	v_and_b32_e32 v89, 0xffff0000, v148
	v_lshlrev_b32_e32 v90, 16, v144
	v_and_b32_e32 v91, 0xffff0000, v144
	v_pk_fma_f32 v[84:85], v[84:85], v[88:89], v[90:91]
	v_lshlrev_b32_e32 v88, 16, v149
	v_and_b32_e32 v89, 0xffff0000, v149
	v_lshlrev_b32_e32 v90, 16, v145
	v_and_b32_e32 v91, 0xffff0000, v145
	v_pk_fma_f32 v[86:87], v[86:87], v[88:89], v[90:91]
	v_lshlrev_b32_e32 v88, 16, v150
	v_and_b32_e32 v89, 0xffff0000, v150
	v_lshlrev_b32_e32 v90, 16, v146
	v_and_b32_e32 v91, 0xffff0000, v146
	v_pk_fma_f32 v[88:89], v[80:81], v[88:89], v[90:91]
	v_lshlrev_b32_e32 v80, 16, v151
	v_and_b32_e32 v81, 0xffff0000, v151
	v_lshlrev_b32_e32 v90, 16, v147
	v_and_b32_e32 v91, 0xffff0000, v147
	v_pk_fma_f32 v[90:91], v[82:83], v[80:81], v[90:91]
	v_cvt_pk_bf16_f32 v80, v84, v85
	v_cvt_pk_bf16_f32 v81, v86, v87
	v_cvt_pk_bf16_f32 v82, v88, v89
	v_cvt_pk_bf16_f32 v83, v90, v91
	global_store_dwordx4 v[170:171], v[80:83], off offset:256
	s_nop 1
	v_lshlrev_b32_e32 v80, 16, v140
	v_and_b32_e32 v81, 0xffff0000, v140
	v_lshlrev_b32_e32 v82, 16, v136
	v_and_b32_e32 v83, 0xffff0000, v136
	v_pk_fma_f32 v[76:77], v[76:77], v[80:81], v[82:83]
	v_lshlrev_b32_e32 v80, 16, v141
	v_and_b32_e32 v81, 0xffff0000, v141
	v_lshlrev_b32_e32 v82, 16, v137
	v_and_b32_e32 v83, 0xffff0000, v137
	v_pk_fma_f32 v[78:79], v[78:79], v[80:81], v[82:83]
	v_lshlrev_b32_e32 v80, 16, v142
	v_and_b32_e32 v81, 0xffff0000, v142
	v_lshlrev_b32_e32 v82, 16, v138
	v_and_b32_e32 v83, 0xffff0000, v138
	v_pk_fma_f32 v[80:81], v[72:73], v[80:81], v[82:83]
	v_lshlrev_b32_e32 v72, 16, v143
	v_and_b32_e32 v73, 0xffff0000, v143
	v_lshlrev_b32_e32 v82, 16, v139
	v_and_b32_e32 v83, 0xffff0000, v139
	v_pk_fma_f32 v[82:83], v[74:75], v[72:73], v[82:83]
	v_cvt_pk_bf16_f32 v72, v76, v77
	v_cvt_pk_bf16_f32 v73, v78, v79
	v_cvt_pk_bf16_f32 v74, v80, v81
	v_cvt_pk_bf16_f32 v75, v82, v83
	global_store_dwordx4 v[168:169], v[72:75], off
	s_nop 1
	v_lshlrev_b32_e32 v72, 16, v132
	v_and_b32_e32 v73, 0xffff0000, v132
	v_lshlrev_b32_e32 v74, 16, v128
	v_and_b32_e32 v75, 0xffff0000, v128
	v_pk_fma_f32 v[68:69], v[68:69], v[72:73], v[74:75]
	v_lshlrev_b32_e32 v72, 16, v133
	v_and_b32_e32 v73, 0xffff0000, v133
	v_lshlrev_b32_e32 v74, 16, v129
	v_and_b32_e32 v75, 0xffff0000, v129
	v_pk_fma_f32 v[70:71], v[70:71], v[72:73], v[74:75]
	v_lshlrev_b32_e32 v72, 16, v134
	v_and_b32_e32 v73, 0xffff0000, v134
	v_lshlrev_b32_e32 v74, 16, v130
	v_and_b32_e32 v75, 0xffff0000, v130
	v_pk_fma_f32 v[72:73], v[64:65], v[72:73], v[74:75]
	v_lshlrev_b32_e32 v64, 16, v135
	v_and_b32_e32 v65, 0xffff0000, v135
	v_lshlrev_b32_e32 v74, 16, v131
	v_and_b32_e32 v75, 0xffff0000, v131
	v_pk_fma_f32 v[74:75], v[66:67], v[64:65], v[74:75]
	v_cvt_pk_bf16_f32 v64, v68, v69
	v_cvt_pk_bf16_f32 v65, v70, v71
	v_cvt_pk_bf16_f32 v66, v72, v73
	v_cvt_pk_bf16_f32 v67, v74, v75
	global_store_dwordx4 v[168:169], v[64:67], off offset:256
	s_nop 1
	v_add_u32_e32 v64, 0x80, v164
	v_ashrrev_i32_e32 v65, 31, v64
	v_lshlrev_b64 v[66:67], 12, v[64:65]
	v_lshl_add_u64 v[66:67], s[42:43], 0, v[66:67]
	v_lshlrev_b64 v[64:65], 11, v[64:65]
	v_lshl_add_u64 v[66:67], v[66:67], 0, v[166:167]
	v_lshl_add_u64 v[64:65], s[82:83], 0, v[64:65]
	global_load_dwordx4 v[92:95], v[66:67], off offset:2048
	v_lshl_add_u64 v[132:133], v[64:65], 0, v[166:167]
	global_load_dwordx4 v[96:99], v[132:133], off
	global_load_dwordx4 v[100:103], v[66:67], off offset:2304
	global_load_dwordx4 v[104:107], v[132:133], off offset:256
	v_add_u32_e32 v64, 0x90, v164
	v_ashrrev_i32_e32 v65, 31, v64
	v_lshlrev_b64 v[66:67], 12, v[64:65]
	v_lshl_add_u64 v[66:67], s[42:43], 0, v[66:67]
	v_lshlrev_b64 v[64:65], 11, v[64:65]
	v_lshl_add_u64 v[66:67], v[66:67], 0, v[166:167]
	v_lshl_add_u64 v[64:65], s[82:83], 0, v[64:65]
	global_load_dwordx4 v[108:111], v[66:67], off offset:2048
	v_lshl_add_u64 v[134:135], v[64:65], 0, v[166:167]
	global_load_dwordx4 v[112:115], v[134:135], off
	global_load_dwordx4 v[116:119], v[66:67], off offset:2304
	global_load_dwordx4 v[120:123], v[134:135], off offset:256
	v_add_u32_e32 v64, 0xa0, v164
	v_ashrrev_i32_e32 v65, 31, v64
	v_lshlrev_b64 v[66:67], 12, v[64:65]
	v_lshl_add_u64 v[66:67], s[42:43], 0, v[66:67]
	v_lshlrev_b64 v[64:65], 11, v[64:65]
	v_lshl_add_u64 v[64:65], s[82:83], 0, v[64:65]
	v_lshl_add_u64 v[66:67], v[66:67], 0, v[166:167]
	v_lshl_add_u64 v[90:91], v[64:65], 0, v[166:167]
	global_load_dwordx4 v[124:127], v[66:67], off offset:2048
	global_load_dwordx4 v[84:87], v[66:67], off offset:2304
	global_load_dwordx4 v[128:131], v[90:91], off
	global_load_dwordx4 v[80:83], v[90:91], off offset:256
	v_add_u32_e32 v64, 0xb0, v164
	v_ashrrev_i32_e32 v65, 31, v64
	v_lshlrev_b64 v[66:67], 12, v[64:65]
	v_lshl_add_u64 v[66:67], s[42:43], 0, v[66:67]
	v_lshlrev_b64 v[64:65], 11, v[64:65]
	v_lshl_add_u64 v[64:65], s[82:83], 0, v[64:65]
	v_lshl_add_u64 v[66:67], v[66:67], 0, v[166:167]
	v_lshl_add_u64 v[88:89], v[64:65], 0, v[166:167]
	global_load_dwordx4 v[76:79], v[66:67], off offset:2048
	global_load_dwordx4 v[68:71], v[66:67], off offset:2304
	global_load_dwordx4 v[72:75], v[88:89], off
	s_nop 0
	global_load_dwordx4 v[64:67], v[88:89], off offset:256
	s_waitcnt vmcnt(0)
	v_lshlrev_b32_e32 v136, 16, v92
	v_and_b32_e32 v137, 0xffff0000, v92
	v_lshlrev_b32_e32 v138, 16, v96
	v_and_b32_e32 v139, 0xffff0000, v96
	v_lshlrev_b32_e32 v92, 16, v93
	v_and_b32_e32 v93, 0xffff0000, v93
	v_lshlrev_b32_e32 v96, 16, v97
	v_and_b32_e32 v97, 0xffff0000, v97
	v_pk_fma_f32 v[62:63], v[62:63], v[92:93], v[96:97]
	v_lshlrev_b32_e32 v92, 16, v94
	v_and_b32_e32 v93, 0xffff0000, v94
	v_lshlrev_b32_e32 v96, 16, v98
	v_and_b32_e32 v97, 0xffff0000, v98
	v_pk_fma_f32 v[92:93], v[56:57], v[92:93], v[96:97]
	v_lshlrev_b32_e32 v56, 16, v95
	v_and_b32_e32 v57, 0xffff0000, v95
	v_lshlrev_b32_e32 v94, 16, v99
	v_and_b32_e32 v95, 0xffff0000, v99
	v_pk_fma_f32 v[60:61], v[60:61], v[136:137], v[138:139]
	v_pk_fma_f32 v[94:95], v[58:59], v[56:57], v[94:95]
	v_cvt_pk_bf16_f32 v56, v60, v61
	v_cvt_pk_bf16_f32 v57, v62, v63
	v_cvt_pk_bf16_f32 v58, v92, v93
	v_cvt_pk_bf16_f32 v59, v94, v95
	global_store_dwordx4 v[132:133], v[56:59], off
	s_nop 1
	v_lshlrev_b32_e32 v56, 16, v100
	v_and_b32_e32 v57, 0xffff0000, v100
	v_lshlrev_b32_e32 v58, 16, v104
	v_and_b32_e32 v59, 0xffff0000, v104
	v_pk_fma_f32 v[52:53], v[52:53], v[56:57], v[58:59]
	v_lshlrev_b32_e32 v56, 16, v101
	v_and_b32_e32 v57, 0xffff0000, v101
	v_lshlrev_b32_e32 v58, 16, v105
	v_and_b32_e32 v59, 0xffff0000, v105
	v_pk_fma_f32 v[54:55], v[54:55], v[56:57], v[58:59]
	v_lshlrev_b32_e32 v56, 16, v102
	v_and_b32_e32 v57, 0xffff0000, v102
	v_lshlrev_b32_e32 v58, 16, v106
	v_and_b32_e32 v59, 0xffff0000, v106
	v_pk_fma_f32 v[56:57], v[48:49], v[56:57], v[58:59]
	v_lshlrev_b32_e32 v48, 16, v103
	v_and_b32_e32 v49, 0xffff0000, v103
	v_lshlrev_b32_e32 v58, 16, v107
	v_and_b32_e32 v59, 0xffff0000, v107
	v_pk_fma_f32 v[58:59], v[50:51], v[48:49], v[58:59]
	v_cvt_pk_bf16_f32 v48, v52, v53
	v_cvt_pk_bf16_f32 v49, v54, v55
	v_cvt_pk_bf16_f32 v50, v56, v57
	v_cvt_pk_bf16_f32 v51, v58, v59
	global_store_dwordx4 v[132:133], v[48:51], off offset:256
	s_nop 1
	v_lshlrev_b32_e32 v48, 16, v108
	v_and_b32_e32 v49, 0xffff0000, v108
	v_lshlrev_b32_e32 v50, 16, v112
	v_and_b32_e32 v51, 0xffff0000, v112
	v_pk_fma_f32 v[44:45], v[44:45], v[48:49], v[50:51]
	v_lshlrev_b32_e32 v48, 16, v109
	v_and_b32_e32 v49, 0xffff0000, v109
	v_lshlrev_b32_e32 v50, 16, v113
	v_and_b32_e32 v51, 0xffff0000, v113
	v_pk_fma_f32 v[46:47], v[46:47], v[48:49], v[50:51]
	v_lshlrev_b32_e32 v48, 16, v110
	v_and_b32_e32 v49, 0xffff0000, v110
	v_lshlrev_b32_e32 v50, 16, v114
	v_and_b32_e32 v51, 0xffff0000, v114
	v_pk_fma_f32 v[48:49], v[40:41], v[48:49], v[50:51]
	v_lshlrev_b32_e32 v40, 16, v111
	v_and_b32_e32 v41, 0xffff0000, v111
	v_lshlrev_b32_e32 v50, 16, v115
	v_and_b32_e32 v51, 0xffff0000, v115
	v_pk_fma_f32 v[50:51], v[42:43], v[40:41], v[50:51]
	v_cvt_pk_bf16_f32 v40, v44, v45
	v_cvt_pk_bf16_f32 v41, v46, v47
	v_cvt_pk_bf16_f32 v42, v48, v49
	v_cvt_pk_bf16_f32 v43, v50, v51
	global_store_dwordx4 v[134:135], v[40:43], off
	s_nop 1
	v_lshlrev_b32_e32 v40, 16, v116
	v_and_b32_e32 v41, 0xffff0000, v116
	v_lshlrev_b32_e32 v42, 16, v120
	v_and_b32_e32 v43, 0xffff0000, v120
	v_pk_fma_f32 v[36:37], v[36:37], v[40:41], v[42:43]
	v_lshlrev_b32_e32 v40, 16, v117
	v_and_b32_e32 v41, 0xffff0000, v117
	v_lshlrev_b32_e32 v42, 16, v121
	v_and_b32_e32 v43, 0xffff0000, v121
	v_pk_fma_f32 v[38:39], v[38:39], v[40:41], v[42:43]
	v_lshlrev_b32_e32 v40, 16, v118
	v_and_b32_e32 v41, 0xffff0000, v118
	v_lshlrev_b32_e32 v42, 16, v122
	v_and_b32_e32 v43, 0xffff0000, v122
	v_pk_fma_f32 v[40:41], v[32:33], v[40:41], v[42:43]
	v_lshlrev_b32_e32 v32, 16, v119
	v_and_b32_e32 v33, 0xffff0000, v119
	v_lshlrev_b32_e32 v42, 16, v123
	v_and_b32_e32 v43, 0xffff0000, v123
	v_pk_fma_f32 v[42:43], v[34:35], v[32:33], v[42:43]
	v_cvt_pk_bf16_f32 v32, v36, v37
	v_cvt_pk_bf16_f32 v33, v38, v39
	v_cvt_pk_bf16_f32 v34, v40, v41
	v_cvt_pk_bf16_f32 v35, v42, v43
	global_store_dwordx4 v[134:135], v[32:35], off offset:256
	s_nop 1
	v_lshlrev_b32_e32 v32, 16, v124
	v_and_b32_e32 v33, 0xffff0000, v124
	v_lshlrev_b32_e32 v34, 16, v128
	v_and_b32_e32 v35, 0xffff0000, v128
	v_pk_fma_f32 v[28:29], v[28:29], v[32:33], v[34:35]
	v_lshlrev_b32_e32 v32, 16, v125
	v_and_b32_e32 v33, 0xffff0000, v125
	v_lshlrev_b32_e32 v34, 16, v129
	v_and_b32_e32 v35, 0xffff0000, v129
	v_pk_fma_f32 v[30:31], v[30:31], v[32:33], v[34:35]
	v_lshlrev_b32_e32 v32, 16, v126
	v_and_b32_e32 v33, 0xffff0000, v126
	v_lshlrev_b32_e32 v34, 16, v130
	v_and_b32_e32 v35, 0xffff0000, v130
	v_pk_fma_f32 v[32:33], v[24:25], v[32:33], v[34:35]
	v_lshlrev_b32_e32 v24, 16, v127
	v_and_b32_e32 v25, 0xffff0000, v127
	v_lshlrev_b32_e32 v34, 16, v131
	v_and_b32_e32 v35, 0xffff0000, v131
	v_pk_fma_f32 v[34:35], v[26:27], v[24:25], v[34:35]
	v_cvt_pk_bf16_f32 v24, v28, v29
	v_cvt_pk_bf16_f32 v25, v30, v31
	v_cvt_pk_bf16_f32 v26, v32, v33
	v_cvt_pk_bf16_f32 v27, v34, v35
	global_store_dwordx4 v[90:91], v[24:27], off
	s_nop 1
	v_lshlrev_b32_e32 v24, 16, v84
	v_and_b32_e32 v25, 0xffff0000, v84
	v_lshlrev_b32_e32 v26, 16, v80
	v_and_b32_e32 v27, 0xffff0000, v80
	v_pk_fma_f32 v[20:21], v[20:21], v[24:25], v[26:27]
	v_lshlrev_b32_e32 v24, 16, v85
	v_and_b32_e32 v25, 0xffff0000, v85
	v_lshlrev_b32_e32 v26, 16, v81
	v_and_b32_e32 v27, 0xffff0000, v81
	v_pk_fma_f32 v[22:23], v[22:23], v[24:25], v[26:27]
	v_lshlrev_b32_e32 v24, 16, v86
	v_and_b32_e32 v25, 0xffff0000, v86
	v_lshlrev_b32_e32 v26, 16, v82
	v_and_b32_e32 v27, 0xffff0000, v82
	v_pk_fma_f32 v[24:25], v[16:17], v[24:25], v[26:27]
	v_lshlrev_b32_e32 v16, 16, v87
	v_and_b32_e32 v17, 0xffff0000, v87
	v_lshlrev_b32_e32 v26, 16, v83
	v_and_b32_e32 v27, 0xffff0000, v83
	v_pk_fma_f32 v[26:27], v[18:19], v[16:17], v[26:27]
	v_cvt_pk_bf16_f32 v16, v20, v21
	v_cvt_pk_bf16_f32 v17, v22, v23
	v_cvt_pk_bf16_f32 v18, v24, v25
	v_cvt_pk_bf16_f32 v19, v26, v27
	global_store_dwordx4 v[90:91], v[16:19], off offset:256
	s_nop 1
	v_lshlrev_b32_e32 v16, 16, v76
	v_and_b32_e32 v17, 0xffff0000, v76
	v_lshlrev_b32_e32 v18, 16, v72
	v_and_b32_e32 v19, 0xffff0000, v72
	v_pk_fma_f32 v[12:13], v[12:13], v[16:17], v[18:19]
	v_lshlrev_b32_e32 v16, 16, v77
	v_and_b32_e32 v17, 0xffff0000, v77
	v_lshlrev_b32_e32 v18, 16, v73
	v_and_b32_e32 v19, 0xffff0000, v73
	v_pk_fma_f32 v[14:15], v[14:15], v[16:17], v[18:19]
	v_lshlrev_b32_e32 v16, 16, v78
	v_and_b32_e32 v17, 0xffff0000, v78
	v_lshlrev_b32_e32 v18, 16, v74
	v_and_b32_e32 v19, 0xffff0000, v74
	v_pk_fma_f32 v[16:17], v[8:9], v[16:17], v[18:19]
	v_lshlrev_b32_e32 v8, 16, v79
	v_and_b32_e32 v9, 0xffff0000, v79
	v_lshlrev_b32_e32 v18, 16, v75
	v_and_b32_e32 v19, 0xffff0000, v75
	v_pk_fma_f32 v[18:19], v[10:11], v[8:9], v[18:19]
	v_cvt_pk_bf16_f32 v8, v12, v13
	v_cvt_pk_bf16_f32 v9, v14, v15
	v_cvt_pk_bf16_f32 v10, v16, v17
	v_cvt_pk_bf16_f32 v11, v18, v19
	global_store_dwordx4 v[88:89], v[8:11], off
	s_nop 1
	v_lshlrev_b32_e32 v8, 16, v68
	v_and_b32_e32 v9, 0xffff0000, v68
	v_lshlrev_b32_e32 v10, 16, v64
	v_and_b32_e32 v11, 0xffff0000, v64
	v_pk_fma_f32 v[4:5], v[4:5], v[8:9], v[10:11]
	v_lshlrev_b32_e32 v8, 16, v69
	v_and_b32_e32 v9, 0xffff0000, v69
	v_lshlrev_b32_e32 v10, 16, v65
	v_and_b32_e32 v11, 0xffff0000, v65
	v_pk_fma_f32 v[6:7], v[6:7], v[8:9], v[10:11]
	v_lshlrev_b32_e32 v8, 16, v70
	v_and_b32_e32 v9, 0xffff0000, v70
	v_lshlrev_b32_e32 v10, 16, v66
	v_and_b32_e32 v11, 0xffff0000, v66
	v_pk_fma_f32 v[8:9], v[0:1], v[8:9], v[10:11]
	v_lshlrev_b32_e32 v0, 16, v71
	v_and_b32_e32 v1, 0xffff0000, v71
	v_lshlrev_b32_e32 v10, 16, v67
	v_and_b32_e32 v11, 0xffff0000, v67
	v_pk_fma_f32 v[10:11], v[2:3], v[0:1], v[10:11]
	v_cvt_pk_bf16_f32 v0, v4, v5
	v_cvt_pk_bf16_f32 v1, v6, v7
	v_cvt_pk_bf16_f32 v2, v8, v9
	v_cvt_pk_bf16_f32 v3, v10, v11
	global_store_dwordx4 v[88:89], v[0:3], off offset:256
	s_cbranch_vccz .LBB0_1277
	s_waitcnt vmcnt(0)
	s_cmpk_gt_u32 s26, 0xff
	s_cbranch_scc1 .LBB0_1289
	s_barrier

.LBB0_1356:
	ds_read_b128 v[144:147], v190
	ds_read_b128 v[148:151], v190 offset:1024
	ds_read_b128 v[166:169], v190 offset:2048
	ds_read_b128 v[170:173], v190 offset:3072
	ds_read_b128 v[174:177], v190 offset:4096
	ds_read_b128 v[180:183], v190 offset:5120
	ds_read_b128 v[184:187], v190 offset:6144
	ds_read_b128 v[194:197], v190 offset:7168
	ds_read_b128 v[128:131], v189
	ds_read_b128 v[132:135], v189 offset:1024
	ds_read_b128 v[136:139], v189 offset:2048
	ds_read_b128 v[140:143], v189 offset:3072
	s_add_u32 s24, s10, 0xfffc0080
	s_addc_u32 s25, s11, -1
	s_cmp_eq_u32 s47, 12
	s_cselect_b32 s27, s15, s25
	s_cselect_b32 s26, s29, s24
	s_cselect_b32 s25, s17, s46
	s_cselect_b32 s24, s44, s45
	v_lshl_add_u64 v[198:199], s[10:11], 0, v[162:163]
	s_add_i32 m0, s7, 0xc000
	s_nop 0
	global_load_lds_dwordx4 v[198:199], off
	v_lshl_add_u64 v[198:199], s[10:11], 0, v[164:165]
	s_add_i32 m0, s7, 0xe000
	s_nop 0
	global_load_lds_dwordx4 v[198:199], off
	s_waitcnt lgkmcnt(0)
	s_barrier
	s_waitcnt lgkmcnt(0)
	v_mfma_f32_16x16x32_bf16 v[124:127], v[128:131], v[144:147], v[124:127]
	v_mfma_f32_16x16x32_bf16 v[120:123], v[136:139], v[144:147], v[120:123]
	v_mfma_f32_16x16x32_bf16 v[108:111], v[128:131], v[166:169], v[108:111]
	v_mfma_f32_16x16x32_bf16 v[104:107], v[136:139], v[166:169], v[104:107]
	v_mfma_f32_16x16x32_bf16 v[92:95], v[128:131], v[174:177], v[92:95]
	v_mfma_f32_16x16x32_bf16 v[88:91], v[136:139], v[174:177], v[88:91]
	v_mfma_f32_16x16x32_bf16 v[76:79], v[128:131], v[184:187], v[76:79]
	v_mfma_f32_16x16x32_bf16 v[72:75], v[136:139], v[184:187], v[72:75]
	v_mfma_f32_16x16x32_bf16 v[124:127], v[132:135], v[148:151], v[124:127]
	v_mfma_f32_16x16x32_bf16 v[120:123], v[140:143], v[148:151], v[120:123]
	v_mfma_f32_16x16x32_bf16 v[108:111], v[132:135], v[170:173], v[108:111]
	v_mfma_f32_16x16x32_bf16 v[104:107], v[140:143], v[170:173], v[104:107]
	v_mfma_f32_16x16x32_bf16 v[92:95], v[132:135], v[180:183], v[92:95]
	v_mfma_f32_16x16x32_bf16 v[88:91], v[140:143], v[180:183], v[88:91]
	v_mfma_f32_16x16x32_bf16 v[76:79], v[132:135], v[194:197], v[76:79]
	v_mfma_f32_16x16x32_bf16 v[72:75], v[140:143], v[194:197], v[72:75]
	s_barrier
	s_add_i32 s48, s41, s33
	v_lshl_add_u64 v[214:215], s[24:25], 0, v[156:157]
	s_mov_b32 m0, s48
	ds_read_b128 v[198:201], v191
	ds_read_b128 v[202:205], v191 offset:1024
	ds_read_b128 v[206:209], v191 offset:2048
	ds_read_b128 v[210:213], v191 offset:3072
	global_load_lds_dwordx4 v[214:215], off
	v_lshl_add_u64 v[216:217], s[24:25], 0, v[152:153]
	s_add_i32 m0, s48, 0x2000
	s_nop 0
	global_load_lds_dwordx4 v[216:217], off
	s_barrier
	s_waitcnt lgkmcnt(0)
	v_mfma_f32_16x16x32_bf16 v[116:119], v[198:201], v[144:147], v[116:119]
	v_mfma_f32_16x16x32_bf16 v[112:115], v[206:209], v[144:147], v[112:115]
	v_mfma_f32_16x16x32_bf16 v[100:103], v[198:201], v[166:169], v[100:103]
	v_mfma_f32_16x16x32_bf16 v[96:99], v[206:209], v[166:169], v[96:99]
	v_mfma_f32_16x16x32_bf16 v[84:87], v[198:201], v[174:177], v[84:87]
	v_mfma_f32_16x16x32_bf16 v[80:83], v[206:209], v[174:177], v[80:83]
	v_mfma_f32_16x16x32_bf16 v[68:71], v[198:201], v[184:187], v[68:71]
	v_mfma_f32_16x16x32_bf16 v[64:67], v[206:209], v[184:187], v[64:67]
	v_mfma_f32_16x16x32_bf16 v[116:119], v[202:205], v[148:151], v[116:119]
	v_mfma_f32_16x16x32_bf16 v[112:115], v[210:213], v[148:151], v[112:115]
	v_mfma_f32_16x16x32_bf16 v[100:103], v[202:205], v[170:173], v[100:103]
	v_mfma_f32_16x16x32_bf16 v[96:99], v[210:213], v[170:173], v[96:99]
	v_mfma_f32_16x16x32_bf16 v[84:87], v[202:205], v[180:183], v[84:87]
	v_mfma_f32_16x16x32_bf16 v[80:83], v[210:213], v[180:183], v[80:83]
	v_mfma_f32_16x16x32_bf16 v[68:71], v[202:205], v[194:197], v[68:71]
	v_mfma_f32_16x16x32_bf16 v[64:67], v[210:213], v[194:197], v[64:67]
	s_mov_b32 m0, s7
	v_lshl_add_u64 v[218:219], s[26:27], 0, v[158:159]
	s_barrier
	ds_read_b128 v[144:147], v190 offset:16384
	ds_read_b128 v[148:151], v190 offset:17408
	ds_read_b128 v[166:169], v190 offset:18432
	ds_read_b128 v[170:173], v190 offset:19456
	ds_read_b128 v[174:177], v190 offset:20480
	ds_read_b128 v[180:183], v190 offset:21504
	ds_read_b128 v[184:187], v190 offset:22528
	ds_read_b128 v[194:197], v190 offset:23552
	global_load_lds_dwordx4 v[218:219], off
	v_lshl_add_u64 v[222:223], s[26:27], 0, v[154:155]
	s_mov_b32 m0, s35
	s_nop 0
	global_load_lds_dwordx4 v[222:223], off
	s_barrier
	s_waitcnt lgkmcnt(0)
	v_mfma_f32_16x16x32_bf16 v[60:63], v[128:131], v[144:147], v[60:63]
	v_mfma_f32_16x16x32_bf16 v[56:59], v[136:139], v[144:147], v[56:59]
	v_mfma_f32_16x16x32_bf16 v[44:47], v[128:131], v[166:169], v[44:47]
	v_mfma_f32_16x16x32_bf16 v[40:43], v[136:139], v[166:169], v[40:43]
	v_mfma_f32_16x16x32_bf16 v[28:31], v[128:131], v[174:177], v[28:31]
	v_mfma_f32_16x16x32_bf16 v[24:27], v[136:139], v[174:177], v[24:27]
	v_mfma_f32_16x16x32_bf16 v[12:15], v[128:131], v[184:187], v[12:15]
	v_mfma_f32_16x16x32_bf16 v[8:11], v[136:139], v[184:187], v[8:11]
	v_mfma_f32_16x16x32_bf16 v[60:63], v[132:135], v[148:151], v[60:63]
	v_mfma_f32_16x16x32_bf16 v[56:59], v[140:143], v[148:151], v[56:59]
	v_mfma_f32_16x16x32_bf16 v[44:47], v[132:135], v[170:173], v[44:47]
	v_mfma_f32_16x16x32_bf16 v[40:43], v[140:143], v[170:173], v[40:43]
	v_mfma_f32_16x16x32_bf16 v[28:31], v[132:135], v[180:183], v[28:31]
	v_mfma_f32_16x16x32_bf16 v[24:27], v[140:143], v[180:183], v[24:27]
	v_mfma_f32_16x16x32_bf16 v[12:15], v[132:135], v[194:197], v[12:15]
	v_mfma_f32_16x16x32_bf16 v[8:11], v[140:143], v[194:197], v[8:11]
	s_barrier
	s_add_u32 s48, s24, 0x40000
	s_addc_u32 s49, s25, 0
	s_add_i32 s50, s42, s33
	v_lshl_add_u64 v[128:129], s[48:49], 0, v[156:157]
	s_mov_b32 m0, s50
	s_nop 0
	global_load_lds_dwordx4 v[128:129], off
	v_lshl_add_u64 v[128:129], s[48:49], 0, v[152:153]
	s_add_i32 m0, s50, 0x2000
	s_nop 0
	global_load_lds_dwordx4 v[128:129], off
	s_waitcnt vmcnt(6)
	s_barrier
	v_mfma_f32_16x16x32_bf16 v[52:55], v[198:201], v[144:147], v[52:55]
	v_mfma_f32_16x16x32_bf16 v[48:51], v[206:209], v[144:147], v[48:51]
	v_mfma_f32_16x16x32_bf16 v[36:39], v[198:201], v[166:169], v[36:39]
	v_mfma_f32_16x16x32_bf16 v[32:35], v[206:209], v[166:169], v[32:35]
	v_mfma_f32_16x16x32_bf16 v[20:23], v[198:201], v[174:177], v[20:23]
	v_mfma_f32_16x16x32_bf16 v[16:19], v[206:209], v[174:177], v[16:19]
	v_mfma_f32_16x16x32_bf16 v[4:7], v[198:201], v[184:187], v[4:7]
	v_mfma_f32_16x16x32_bf16 v[0:3], v[206:209], v[184:187], v[0:3]
	v_mfma_f32_16x16x32_bf16 v[52:55], v[202:205], v[148:151], v[52:55]
	v_mfma_f32_16x16x32_bf16 v[48:51], v[210:213], v[148:151], v[48:51]
	v_mfma_f32_16x16x32_bf16 v[36:39], v[202:205], v[170:173], v[36:39]
	v_mfma_f32_16x16x32_bf16 v[32:35], v[210:213], v[170:173], v[32:35]
	v_mfma_f32_16x16x32_bf16 v[20:23], v[202:205], v[180:183], v[20:23]
	v_mfma_f32_16x16x32_bf16 v[16:19], v[210:213], v[180:183], v[16:19]
	v_mfma_f32_16x16x32_bf16 v[4:7], v[202:205], v[194:197], v[4:7]
	v_mfma_f32_16x16x32_bf16 v[0:3], v[210:213], v[194:197], v[0:3]
	s_add_i32 s48, 0, 0x18000
	v_add_u32_e32 v140, s48, v188
	s_barrier
	ds_read_b128 v[144:147], v190 offset:32768
	ds_read_b128 v[148:151], v190 offset:33792
	ds_read_b128 v[166:169], v190 offset:34816
	ds_read_b128 v[170:173], v190 offset:35840
	ds_read_b128 v[174:177], v190 offset:36864
	ds_read_b128 v[180:183], v190 offset:37888
	ds_read_b128 v[184:187], v190 offset:38912
	ds_read_b128 v[194:197], v190 offset:39936
	ds_read_b128 v[128:131], v140
	ds_read_b128 v[132:135], v140 offset:1024
	ds_read_b128 v[136:139], v140 offset:2048
	ds_read_b128 v[140:143], v140 offset:3072
	s_add_u32 s26, s26, 0x40000
	s_addc_u32 s27, s27, 0
	s_mov_b32 m0, s36
	v_lshl_add_u64 v[198:199], s[26:27], 0, v[158:159]
	global_load_lds_dwordx4 v[198:199], off
	v_lshl_add_u64 v[198:199], s[26:27], 0, v[154:155]
	s_mov_b32 m0, s37
	s_nop 0
	global_load_lds_dwordx4 v[198:199], off
	s_waitcnt lgkmcnt(0)
	s_barrier
	s_waitcnt lgkmcnt(0)
	v_mfma_f32_16x16x32_bf16 v[124:127], v[128:131], v[144:147], v[124:127]
	v_mfma_f32_16x16x32_bf16 v[120:123], v[136:139], v[144:147], v[120:123]
	v_mfma_f32_16x16x32_bf16 v[108:111], v[128:131], v[166:169], v[108:111]
	v_mfma_f32_16x16x32_bf16 v[104:107], v[136:139], v[166:169], v[104:107]
	v_mfma_f32_16x16x32_bf16 v[92:95], v[128:131], v[174:177], v[92:95]
	v_mfma_f32_16x16x32_bf16 v[88:91], v[136:139], v[174:177], v[88:91]
	v_mfma_f32_16x16x32_bf16 v[76:79], v[128:131], v[184:187], v[76:79]
	v_mfma_f32_16x16x32_bf16 v[72:75], v[136:139], v[184:187], v[72:75]
	v_mfma_f32_16x16x32_bf16 v[124:127], v[132:135], v[148:151], v[124:127]
	v_mfma_f32_16x16x32_bf16 v[120:123], v[140:143], v[148:151], v[120:123]
	v_mfma_f32_16x16x32_bf16 v[108:111], v[132:135], v[170:173], v[108:111]
	v_mfma_f32_16x16x32_bf16 v[104:107], v[140:143], v[170:173], v[104:107]
	v_mfma_f32_16x16x32_bf16 v[92:95], v[132:135], v[180:183], v[92:95]
	v_mfma_f32_16x16x32_bf16 v[88:91], v[140:143], v[180:183], v[88:91]
	v_mfma_f32_16x16x32_bf16 v[76:79], v[132:135], v[194:197], v[76:79]
	v_mfma_f32_16x16x32_bf16 v[72:75], v[140:143], v[194:197], v[72:75]
	s_barrier
	s_add_i32 s26, 0, 0x1c000
	s_add_i32 s27, s48, s33
	v_add_u32_e32 v193, s26, v188
	v_lshl_add_u64 v[214:215], v[214:215], 0, s[12:13]
	s_mov_b32 m0, s27
	ds_read_b128 v[198:201], v193
	ds_read_b128 v[202:205], v193 offset:1024
	ds_read_b128 v[206:209], v193 offset:2048
	ds_read_b128 v[210:213], v193 offset:3072
	global_load_lds_dwordx4 v[214:215], off
	v_lshl_add_u64 v[214:215], v[216:217], 0, s[12:13]
	s_add_i32 m0, s27, 0x2000
	s_nop 0
	global_load_lds_dwordx4 v[214:215], off
	s_barrier
	s_waitcnt lgkmcnt(0)
	v_mfma_f32_16x16x32_bf16 v[116:119], v[198:201], v[144:147], v[116:119]
	v_mfma_f32_16x16x32_bf16 v[112:115], v[206:209], v[144:147], v[112:115]
	v_mfma_f32_16x16x32_bf16 v[100:103], v[198:201], v[166:169], v[100:103]
	v_mfma_f32_16x16x32_bf16 v[96:99], v[206:209], v[166:169], v[96:99]
	v_mfma_f32_16x16x32_bf16 v[84:87], v[198:201], v[174:177], v[84:87]
	v_mfma_f32_16x16x32_bf16 v[80:83], v[206:209], v[174:177], v[80:83]
	v_mfma_f32_16x16x32_bf16 v[68:71], v[198:201], v[184:187], v[68:71]
	v_mfma_f32_16x16x32_bf16 v[64:67], v[206:209], v[184:187], v[64:67]
	v_mfma_f32_16x16x32_bf16 v[116:119], v[202:205], v[148:151], v[116:119]
	v_mfma_f32_16x16x32_bf16 v[112:115], v[210:213], v[148:151], v[112:115]
	v_mfma_f32_16x16x32_bf16 v[100:103], v[202:205], v[170:173], v[100:103]
	v_mfma_f32_16x16x32_bf16 v[96:99], v[210:213], v[170:173], v[96:99]
	v_mfma_f32_16x16x32_bf16 v[84:87], v[202:205], v[180:183], v[84:87]
	v_mfma_f32_16x16x32_bf16 v[80:83], v[210:213], v[180:183], v[80:83]
	v_mfma_f32_16x16x32_bf16 v[68:71], v[202:205], v[194:197], v[68:71]
	v_mfma_f32_16x16x32_bf16 v[64:67], v[210:213], v[194:197], v[64:67]
	s_mov_b32 m0, s39
	v_lshl_add_u64 v[214:215], v[218:219], 0, s[12:13]
	s_barrier
	ds_read_b128 v[144:147], v190 offset:49152
	ds_read_b128 v[148:151], v190 offset:50176
	ds_read_b128 v[166:169], v190 offset:51200
	ds_read_b128 v[170:173], v190 offset:52224
	ds_read_b128 v[174:177], v190 offset:53248
	ds_read_b128 v[180:183], v190 offset:54272
	ds_read_b128 v[184:187], v190 offset:55296
	ds_read_b128 v[194:197], v190 offset:56320
	global_load_lds_dwordx4 v[214:215], off
	v_lshl_add_u64 v[214:215], v[222:223], 0, s[12:13]
	s_mov_b32 m0, s40
	s_nop 0
	global_load_lds_dwordx4 v[214:215], off
	s_barrier
	s_waitcnt lgkmcnt(0)
	v_mfma_f32_16x16x32_bf16 v[60:63], v[128:131], v[144:147], v[60:63]
	v_mfma_f32_16x16x32_bf16 v[56:59], v[136:139], v[144:147], v[56:59]
	v_mfma_f32_16x16x32_bf16 v[44:47], v[128:131], v[166:169], v[44:47]
	v_mfma_f32_16x16x32_bf16 v[40:43], v[136:139], v[166:169], v[40:43]
	v_mfma_f32_16x16x32_bf16 v[28:31], v[128:131], v[174:177], v[28:31]
	v_mfma_f32_16x16x32_bf16 v[24:27], v[136:139], v[174:177], v[24:27]
	v_mfma_f32_16x16x32_bf16 v[12:15], v[128:131], v[184:187], v[12:15]
	v_mfma_f32_16x16x32_bf16 v[8:11], v[136:139], v[184:187], v[8:11]
	v_mfma_f32_16x16x32_bf16 v[60:63], v[132:135], v[148:151], v[60:63]
	v_mfma_f32_16x16x32_bf16 v[56:59], v[140:143], v[148:151], v[56:59]
	v_mfma_f32_16x16x32_bf16 v[44:47], v[132:135], v[170:173], v[44:47]
	v_mfma_f32_16x16x32_bf16 v[40:43], v[140:143], v[170:173], v[40:43]
	v_mfma_f32_16x16x32_bf16 v[28:31], v[132:135], v[180:183], v[28:31]
	v_mfma_f32_16x16x32_bf16 v[24:27], v[140:143], v[180:183], v[24:27]
	v_mfma_f32_16x16x32_bf16 v[12:15], v[132:135], v[194:197], v[12:15]
	v_mfma_f32_16x16x32_bf16 v[8:11], v[140:143], v[194:197], v[8:11]
	s_barrier
	s_add_u32 s24, s24, 0x40080
	s_addc_u32 s25, s25, 0
	s_add_i32 s26, s26, s33
	v_lshl_add_u64 v[128:129], s[24:25], 0, v[156:157]
	s_mov_b32 m0, s26
	s_nop 0
	global_load_lds_dwordx4 v[128:129], off
	v_lshl_add_u64 v[128:129], s[24:25], 0, v[152:153]
	s_add_i32 m0, s26, 0x2000
	s_nop 0
	global_load_lds_dwordx4 v[128:129], off
	s_waitcnt vmcnt(6)
	s_barrier
	v_mfma_f32_16x16x32_bf16 v[52:55], v[198:201], v[144:147], v[52:55]
	v_mfma_f32_16x16x32_bf16 v[48:51], v[206:209], v[144:147], v[48:51]
	v_mfma_f32_16x16x32_bf16 v[36:39], v[198:201], v[166:169], v[36:39]
	v_mfma_f32_16x16x32_bf16 v[32:35], v[206:209], v[166:169], v[32:35]
	v_mfma_f32_16x16x32_bf16 v[20:23], v[198:201], v[174:177], v[20:23]
	v_mfma_f32_16x16x32_bf16 v[16:19], v[206:209], v[174:177], v[16:19]
	v_mfma_f32_16x16x32_bf16 v[4:7], v[198:201], v[184:187], v[4:7]
	v_mfma_f32_16x16x32_bf16 v[0:3], v[206:209], v[184:187], v[0:3]
	v_mfma_f32_16x16x32_bf16 v[52:55], v[202:205], v[148:151], v[52:55]
	v_mfma_f32_16x16x32_bf16 v[48:51], v[210:213], v[148:151], v[48:51]
	v_mfma_f32_16x16x32_bf16 v[36:39], v[202:205], v[170:173], v[36:39]
	v_mfma_f32_16x16x32_bf16 v[32:35], v[210:213], v[170:173], v[32:35]
	v_mfma_f32_16x16x32_bf16 v[20:23], v[202:205], v[180:183], v[20:23]
	v_mfma_f32_16x16x32_bf16 v[16:19], v[210:213], v[180:183], v[16:19]
	v_mfma_f32_16x16x32_bf16 v[4:7], v[202:205], v[194:197], v[4:7]
	v_mfma_f32_16x16x32_bf16 v[0:3], v[210:213], v[194:197], v[0:3]
	s_add_i32 s47, s47, 2
	s_add_u32 s10, s10, 0x100
	s_addc_u32 s11, s11, 0
	s_add_u32 s45, s45, 0x100
	s_addc_u32 s46, s46, 0
	s_cmp_gt_u32 s47, 13
	s_barrier
	s_cbranch_scc0 .LBB0_1356
	s_lshl_b32 s24, s4, 8
	s_ashr_i32 s25, s24, 31
	s_lshl_b32 s10, s4, 2
	s_nop 0
	v_lshl_add_u32 v166, s28, 8, v179
	s_ashr_i32 s11, s10, 31
	s_lshl_b64 s[28:29], s[24:25], 1
	v_readlane_b32 s50, v253, 40
	v_readlane_b32 s51, v253, 41
	s_add_u32 s26, s50, s28
	v_ashrrev_i32_e32 v167, 31, v166
	s_addc_u32 s27, s51, s29
	v_lshlrev_b64 v[204:205], 11, v[166:167]
	v_lshl_add_u64 v[128:129], s[26:27], 0, v[204:205]
	v_lshl_add_u64 v[206:207], v[128:129], 0, v[160:161]
	global_load_dwordx4 v[196:199], v[206:207], off
	global_load_dwordx4 v[200:203], v[206:207], off offset:256
	v_or_b32_e32 v182, 16, v166
	v_or_b32_e32 v174, 32, v166
	v_or_b32_e32 v168, 48, v166
	v_ashrrev_i32_e32 v183, 31, v182
	v_ashrrev_i32_e32 v175, 31, v174
	v_ashrrev_i32_e32 v169, 31, v168
	v_lshlrev_b64 v[186:187], 11, v[182:183]
	v_lshlrev_b64 v[180:181], 11, v[174:175]
	v_lshlrev_b64 v[172:173], 11, v[168:169]
	v_lshl_add_u64 v[128:129], s[26:27], 0, v[186:187]
	v_lshl_add_u64 v[130:131], s[26:27], 0, v[180:181]
	v_lshl_add_u64 v[132:133], s[26:27], 0, v[172:173]
	v_lshl_add_u64 v[184:185], v[128:129], 0, v[160:161]
	v_lshl_add_u64 v[176:177], v[130:131], 0, v[160:161]
	v_lshl_add_u64 v[170:171], v[132:133], 0, v[160:161]
	global_load_dwordx4 v[148:151], v[184:185], off
	global_load_dwordx4 v[144:147], v[184:185], off offset:256
	global_load_dwordx4 v[140:143], v[176:177], off
	global_load_dwordx4 v[136:139], v[176:177], off offset:256
	global_load_dwordx4 v[132:135], v[170:171], off
	global_load_dwordx4 v[128:131], v[170:171], off offset:256
	v_and_b32_e32 v194, 64, v192
	v_xor_b32_e32 v193, 16, v192
	v_add_u32_e32 v194, 64, v194
	v_cmp_lt_i32_e32 vcc, v193, v194
	v_xor_b32_e32 v195, 32, v192
	v_lshl_add_u64 v[204:205], s[50:51], 0, v[204:205]
	v_cndmask_b32_e32 v193, v192, v193, vcc
	v_cmp_lt_i32_e32 vcc, v195, v194
	v_lshlrev_b32_e32 v194, 2, v193
	s_nop 0
	v_cndmask_b32_e32 v195, v192, v195, vcc
	v_lshlrev_b32_e32 v193, 2, v195
	s_nop 7
	s_nop 3
	s_waitcnt vmcnt(0)
	v_lshlrev_b32_e32 v210, 16, v198
	v_and_b32_e32 v211, 0xffff0000, v198
	v_lshlrev_b32_e32 v208, 16, v196
	v_and_b32_e32 v209, 0xffff0000, v196
	v_lshlrev_b32_e32 v198, 16, v199
	v_and_b32_e32 v199, 0xffff0000, v199
	v_lshlrev_b32_e32 v214, 16, v202
	v_and_b32_e32 v215, 0xffff0000, v202
	v_lshlrev_b32_e32 v202, 16, v203
	v_and_b32_e32 v203, 0xffff0000, v203
	v_pk_add_f32 v[120:121], v[120:121], v[210:211]
	v_lshlrev_b32_e32 v196, 16, v197
	v_and_b32_e32 v197, 0xffff0000, v197
	v_pk_add_f32 v[124:125], v[124:125], v[208:209]
	v_pk_add_f32 v[122:123], v[122:123], v[198:199]
	v_pk_add_f32 v[198:199], v[114:115], v[202:203]
	v_cvt_pk_bf16_f32 v114, v120, v121
	v_pk_mul_f32 v[120:121], v[120:121], v[120:121]
	v_pk_add_f32 v[126:127], v[126:127], v[196:197]
	v_cvt_pk_bf16_f32 v115, v122, v123
	v_pk_mul_f32 v[122:123], v[122:123], v[122:123]
	v_pk_fma_f32 v[120:121], v[124:125], v[124:125], v[120:121]
	v_lshlrev_b32_e32 v212, 16, v200
	v_and_b32_e32 v213, 0xffff0000, v200
	v_lshlrev_b32_e32 v200, 16, v201
	v_and_b32_e32 v201, 0xffff0000, v201
	v_pk_add_f32 v[196:197], v[112:113], v[214:215]
	v_pk_fma_f32 v[122:123], v[126:127], v[126:127], v[122:123]
	v_add_f32_e32 v120, v120, v121
	v_pk_add_f32 v[116:117], v[116:117], v[212:213]
	v_pk_add_f32 v[118:119], v[118:119], v[200:201]
	v_pk_mul_f32 v[200:201], v[196:197], v[196:197]
	v_add_f32_e32 v120, v122, v120
	v_cvt_pk_bf16_f32 v112, v124, v125
	v_pk_fma_f32 v[124:125], v[116:117], v[116:117], v[200:201]
	v_add_f32_e32 v120, v123, v120
	v_pk_mul_f32 v[202:203], v[198:199], v[198:199]
	v_add_f32_e32 v120, v124, v120
	v_cvt_pk_bf16_f32 v113, v126, v127
	v_pk_fma_f32 v[126:127], v[118:119], v[118:119], v[202:203]
	v_add_f32_e32 v120, v125, v120
	v_add_f32_e32 v120, v126, v120
	v_add_f32_e32 v122, v127, v120
	ds_bpermute_b32 v123, v194, v122
	global_store_dwordx4 v[206:207], v[112:115], off
	v_lshl_add_u64 v[120:121], v[204:205], 0, s[28:29]
	s_nop 0
	v_cvt_pk_bf16_f32 v114, v116, v117
	s_waitcnt lgkmcnt(0)
	v_add_f32_e32 v112, v122, v123
	ds_bpermute_b32 v113, v193, v112
	v_cvt_pk_bf16_f32 v115, v118, v119
	v_cvt_pk_bf16_f32 v116, v196, v197
	v_cvt_pk_bf16_f32 v117, v198, v199
	v_lshl_add_u64 v[118:119], v[120:121], 0, v[160:161]
	global_store_dwordx4 v[118:119], v[114:117], off offset:256
	s_and_saveexec_b64 s[28:29], s[0:1]
	s_cbranch_execz .LBB0_1359
	s_waitcnt lgkmcnt(0)
	v_add_f32_e32 v114, v112, v113
	v_lshlrev_b64 v[112:113], 6, v[166:167]
	v_lshl_add_u64 v[112:113], s[86:87], 0, v[112:113]
	v_lshl_add_u64 v[112:113], s[10:11], 2, v[112:113]
	s_lshl_b32 s4, s38, 2
	v_lshl_add_u64 v[112:113], v[112:113], 0, s[4:5]
	global_store_dword v[112:113], v114, off

.LBB0_1441:
	ds_read_b128 v[184:187], v165
	ds_read_b128 v[188:191], v165 offset:1024
	ds_read_b128 v[192:195], v165 offset:2048
	ds_read_b128 v[196:199], v165 offset:3072
	ds_read_b128 v[200:203], v165 offset:4096
	ds_read_b128 v[204:207], v165 offset:5120
	ds_read_b128 v[208:211], v165 offset:6144
	ds_read_b128 v[212:215], v165 offset:7168
	ds_read_b128 v[144:147], v161
	ds_read_b128 v[148:151], v161 offset:1024
	ds_read_b128 v[172:175], v161 offset:2048
	ds_read_b128 v[180:183], v161 offset:3072
	s_add_u32 s4, s0, 0xfffc0080
	s_addc_u32 s5, s1, -1
	s_cmp_eq_u32 s45, 12
	s_cselect_b32 s11, s19, s5
	s_cselect_b32 s10, s41, s4
	s_cselect_b32 s5, s21, s44
	s_cselect_b32 s4, s42, s43
	v_lshl_add_u64 v[154:155], s[0:1], 0, v[140:141]
	s_add_i32 m0, s17, 0xc000
	s_nop 0
	global_load_lds_dwordx4 v[154:155], off
	v_lshl_add_u64 v[154:155], s[0:1], 0, v[142:143]
	s_add_i32 m0, s17, 0xe000
	s_nop 0
	global_load_lds_dwordx4 v[154:155], off
	s_waitcnt lgkmcnt(0)
	s_barrier
	s_waitcnt lgkmcnt(0)
	v_mfma_f32_16x16x32_bf16 v[124:127], v[144:147], v[184:187], v[124:127]
	v_mfma_f32_16x16x32_bf16 v[120:123], v[172:175], v[184:187], v[120:123]
	v_mfma_f32_16x16x32_bf16 v[108:111], v[144:147], v[192:195], v[108:111]
	v_mfma_f32_16x16x32_bf16 v[104:107], v[172:175], v[192:195], v[104:107]
	v_mfma_f32_16x16x32_bf16 v[92:95], v[144:147], v[200:203], v[92:95]
	v_mfma_f32_16x16x32_bf16 v[88:91], v[172:175], v[200:203], v[88:91]
	v_mfma_f32_16x16x32_bf16 v[76:79], v[144:147], v[208:211], v[76:79]
	v_mfma_f32_16x16x32_bf16 v[72:75], v[172:175], v[208:211], v[72:75]
	v_mfma_f32_16x16x32_bf16 v[124:127], v[148:151], v[188:191], v[124:127]
	v_mfma_f32_16x16x32_bf16 v[120:123], v[180:183], v[188:191], v[120:123]
	v_mfma_f32_16x16x32_bf16 v[108:111], v[148:151], v[196:199], v[108:111]
	v_mfma_f32_16x16x32_bf16 v[104:107], v[180:183], v[196:199], v[104:107]
	v_mfma_f32_16x16x32_bf16 v[92:95], v[148:151], v[204:207], v[92:95]
	v_mfma_f32_16x16x32_bf16 v[88:91], v[180:183], v[204:207], v[88:91]
	v_mfma_f32_16x16x32_bf16 v[76:79], v[148:151], v[212:215], v[76:79]
	v_mfma_f32_16x16x32_bf16 v[72:75], v[180:183], v[212:215], v[72:75]
	s_barrier
	s_add_i32 s46, s37, s15
	v_lshl_add_u64 v[154:155], s[4:5], 0, v[132:133]
	s_mov_b32 m0, s46
	ds_read_b128 v[216:219], v167
	ds_read_b128 v[222:225], v167 offset:1024
	ds_read_b128 v[226:229], v167 offset:2048
	ds_read_b128 v[230:233], v167 offset:3072
	global_load_lds_dwordx4 v[154:155], off
	v_lshl_add_u64 v[158:159], s[4:5], 0, v[128:129]
	s_add_i32 m0, s46, 0x2000
	s_nop 0
	global_load_lds_dwordx4 v[158:159], off
	s_barrier
	s_waitcnt lgkmcnt(0)
	v_mfma_f32_16x16x32_bf16 v[116:119], v[216:219], v[184:187], v[116:119]
	v_mfma_f32_16x16x32_bf16 v[112:115], v[226:229], v[184:187], v[112:115]
	v_mfma_f32_16x16x32_bf16 v[100:103], v[216:219], v[192:195], v[100:103]
	v_mfma_f32_16x16x32_bf16 v[96:99], v[226:229], v[192:195], v[96:99]
	v_mfma_f32_16x16x32_bf16 v[84:87], v[216:219], v[200:203], v[84:87]
	v_mfma_f32_16x16x32_bf16 v[80:83], v[226:229], v[200:203], v[80:83]
	v_mfma_f32_16x16x32_bf16 v[68:71], v[216:219], v[208:211], v[68:71]
	v_mfma_f32_16x16x32_bf16 v[64:67], v[226:229], v[208:211], v[64:67]
	v_mfma_f32_16x16x32_bf16 v[116:119], v[222:225], v[188:191], v[116:119]
	v_mfma_f32_16x16x32_bf16 v[112:115], v[230:233], v[188:191], v[112:115]
	v_mfma_f32_16x16x32_bf16 v[100:103], v[222:225], v[196:199], v[100:103]
	v_mfma_f32_16x16x32_bf16 v[96:99], v[230:233], v[196:199], v[96:99]
	v_mfma_f32_16x16x32_bf16 v[84:87], v[222:225], v[204:207], v[84:87]
	v_mfma_f32_16x16x32_bf16 v[80:83], v[230:233], v[204:207], v[80:83]
	v_mfma_f32_16x16x32_bf16 v[68:71], v[222:225], v[212:215], v[68:71]
	v_mfma_f32_16x16x32_bf16 v[64:67], v[230:233], v[212:215], v[64:67]
	s_mov_b32 m0, s17
	v_lshl_add_u64 v[162:163], s[10:11], 0, v[134:135]
	s_barrier
	ds_read_b128 v[184:187], v165 offset:16384
	ds_read_b128 v[188:191], v165 offset:17408
	ds_read_b128 v[192:195], v165 offset:18432
	ds_read_b128 v[196:199], v165 offset:19456
	ds_read_b128 v[200:203], v165 offset:20480
	ds_read_b128 v[204:207], v165 offset:21504
	ds_read_b128 v[208:211], v165 offset:22528
	ds_read_b128 v[212:215], v165 offset:23552
	global_load_lds_dwordx4 v[162:163], off
	v_lshl_add_u64 v[168:169], s[10:11], 0, v[130:131]
	s_mov_b32 m0, s28
	s_nop 0
	global_load_lds_dwordx4 v[168:169], off
	s_barrier
	s_waitcnt lgkmcnt(0)
	v_mfma_f32_16x16x32_bf16 v[60:63], v[144:147], v[184:187], v[60:63]
	v_mfma_f32_16x16x32_bf16 v[56:59], v[172:175], v[184:187], v[56:59]
	v_mfma_f32_16x16x32_bf16 v[44:47], v[144:147], v[192:195], v[44:47]
	v_mfma_f32_16x16x32_bf16 v[40:43], v[172:175], v[192:195], v[40:43]
	v_mfma_f32_16x16x32_bf16 v[28:31], v[144:147], v[200:203], v[28:31]
	v_mfma_f32_16x16x32_bf16 v[24:27], v[172:175], v[200:203], v[24:27]
	v_mfma_f32_16x16x32_bf16 v[12:15], v[144:147], v[208:211], v[12:15]
	v_mfma_f32_16x16x32_bf16 v[8:11], v[172:175], v[208:211], v[8:11]
	v_mfma_f32_16x16x32_bf16 v[60:63], v[148:151], v[188:191], v[60:63]
	v_mfma_f32_16x16x32_bf16 v[56:59], v[180:183], v[188:191], v[56:59]
	v_mfma_f32_16x16x32_bf16 v[44:47], v[148:151], v[196:199], v[44:47]
	v_mfma_f32_16x16x32_bf16 v[40:43], v[180:183], v[196:199], v[40:43]
	v_mfma_f32_16x16x32_bf16 v[28:31], v[148:151], v[204:207], v[28:31]
	v_mfma_f32_16x16x32_bf16 v[24:27], v[180:183], v[204:207], v[24:27]
	v_mfma_f32_16x16x32_bf16 v[12:15], v[148:151], v[212:215], v[12:15]
	v_mfma_f32_16x16x32_bf16 v[8:11], v[180:183], v[212:215], v[8:11]
	s_barrier
	s_add_u32 s46, s4, 0x40000
	s_addc_u32 s47, s5, 0
	s_add_i32 s48, s38, s15
	v_lshl_add_u64 v[144:145], s[46:47], 0, v[132:133]
	s_mov_b32 m0, s48
	s_nop 0
	global_load_lds_dwordx4 v[144:145], off
	v_lshl_add_u64 v[144:145], s[46:47], 0, v[128:129]
	s_add_i32 m0, s48, 0x2000
	s_nop 0
	global_load_lds_dwordx4 v[144:145], off
	s_waitcnt vmcnt(6)
	s_barrier
	v_mfma_f32_16x16x32_bf16 v[52:55], v[216:219], v[184:187], v[52:55]
	v_mfma_f32_16x16x32_bf16 v[48:51], v[226:229], v[184:187], v[48:51]
	v_mfma_f32_16x16x32_bf16 v[36:39], v[216:219], v[192:195], v[36:39]
	v_mfma_f32_16x16x32_bf16 v[32:35], v[226:229], v[192:195], v[32:35]
	v_mfma_f32_16x16x32_bf16 v[20:23], v[216:219], v[200:203], v[20:23]
	v_mfma_f32_16x16x32_bf16 v[16:19], v[226:229], v[200:203], v[16:19]
	v_mfma_f32_16x16x32_bf16 v[4:7], v[216:219], v[208:211], v[4:7]
	v_mfma_f32_16x16x32_bf16 v[0:3], v[226:229], v[208:211], v[0:3]
	v_mfma_f32_16x16x32_bf16 v[52:55], v[222:225], v[188:191], v[52:55]
	v_mfma_f32_16x16x32_bf16 v[48:51], v[230:233], v[188:191], v[48:51]
	v_mfma_f32_16x16x32_bf16 v[36:39], v[222:225], v[196:199], v[36:39]
	v_mfma_f32_16x16x32_bf16 v[32:35], v[230:233], v[196:199], v[32:35]
	v_mfma_f32_16x16x32_bf16 v[20:23], v[222:225], v[204:207], v[20:23]
	v_mfma_f32_16x16x32_bf16 v[16:19], v[230:233], v[204:207], v[16:19]
	v_mfma_f32_16x16x32_bf16 v[4:7], v[222:225], v[212:215], v[4:7]
	v_mfma_f32_16x16x32_bf16 v[0:3], v[230:233], v[212:215], v[0:3]
	s_add_i32 s46, 0, 0x18000
	v_add_u32_e32 v152, s46, v157
	s_barrier
	ds_read_b128 v[184:187], v165 offset:32768
	ds_read_b128 v[188:191], v165 offset:33792
	ds_read_b128 v[192:195], v165 offset:34816
	ds_read_b128 v[196:199], v165 offset:35840
	ds_read_b128 v[200:203], v165 offset:36864
	ds_read_b128 v[204:207], v165 offset:37888
	ds_read_b128 v[208:211], v165 offset:38912
	ds_read_b128 v[212:215], v165 offset:39936
	ds_read_b128 v[144:147], v152
	ds_read_b128 v[148:151], v152 offset:1024
	ds_read_b128 v[172:175], v152 offset:2048
	ds_read_b128 v[180:183], v152 offset:3072
	s_add_u32 s10, s10, 0x40000
	s_addc_u32 s11, s11, 0
	s_mov_b32 m0, s29
	v_lshl_add_u64 v[176:177], s[10:11], 0, v[134:135]
	global_load_lds_dwordx4 v[176:177], off
	v_lshl_add_u64 v[176:177], s[10:11], 0, v[130:131]
	s_mov_b32 m0, s31
	s_nop 0
	global_load_lds_dwordx4 v[176:177], off
	s_waitcnt lgkmcnt(0)
	s_barrier
	s_waitcnt lgkmcnt(0)
	v_mfma_f32_16x16x32_bf16 v[124:127], v[144:147], v[184:187], v[124:127]
	v_mfma_f32_16x16x32_bf16 v[120:123], v[172:175], v[184:187], v[120:123]
	v_mfma_f32_16x16x32_bf16 v[108:111], v[144:147], v[192:195], v[108:111]
	v_mfma_f32_16x16x32_bf16 v[104:107], v[172:175], v[192:195], v[104:107]
	v_mfma_f32_16x16x32_bf16 v[92:95], v[144:147], v[200:203], v[92:95]
	v_mfma_f32_16x16x32_bf16 v[88:91], v[172:175], v[200:203], v[88:91]
	v_mfma_f32_16x16x32_bf16 v[76:79], v[144:147], v[208:211], v[76:79]
	v_mfma_f32_16x16x32_bf16 v[72:75], v[172:175], v[208:211], v[72:75]
	v_mfma_f32_16x16x32_bf16 v[124:127], v[148:151], v[188:191], v[124:127]
	v_mfma_f32_16x16x32_bf16 v[120:123], v[180:183], v[188:191], v[120:123]
	v_mfma_f32_16x16x32_bf16 v[108:111], v[148:151], v[196:199], v[108:111]
	v_mfma_f32_16x16x32_bf16 v[104:107], v[180:183], v[196:199], v[104:107]
	v_mfma_f32_16x16x32_bf16 v[92:95], v[148:151], v[204:207], v[92:95]
	v_mfma_f32_16x16x32_bf16 v[88:91], v[180:183], v[204:207], v[88:91]
	v_mfma_f32_16x16x32_bf16 v[76:79], v[148:151], v[212:215], v[76:79]
	v_mfma_f32_16x16x32_bf16 v[72:75], v[180:183], v[212:215], v[72:75]
	s_barrier
	s_add_i32 s10, 0, 0x1c000
	s_add_i32 s11, s46, s15
	v_add_u32_e32 v152, s10, v157
	v_lshl_add_u64 v[154:155], v[154:155], 0, s[12:13]
	s_mov_b32 m0, s11
	ds_read_b128 v[216:219], v152
	ds_read_b128 v[222:225], v152 offset:1024
	ds_read_b128 v[226:229], v152 offset:2048
	ds_read_b128 v[230:233], v152 offset:3072
	global_load_lds_dwordx4 v[154:155], off
	v_lshl_add_u64 v[154:155], v[158:159], 0, s[12:13]
	s_add_i32 m0, s11, 0x2000
	s_nop 0
	global_load_lds_dwordx4 v[154:155], off
	s_barrier
	s_waitcnt lgkmcnt(0)
	v_mfma_f32_16x16x32_bf16 v[116:119], v[216:219], v[184:187], v[116:119]
	v_mfma_f32_16x16x32_bf16 v[112:115], v[226:229], v[184:187], v[112:115]
	v_mfma_f32_16x16x32_bf16 v[100:103], v[216:219], v[192:195], v[100:103]
	v_mfma_f32_16x16x32_bf16 v[96:99], v[226:229], v[192:195], v[96:99]
	v_mfma_f32_16x16x32_bf16 v[84:87], v[216:219], v[200:203], v[84:87]
	v_mfma_f32_16x16x32_bf16 v[80:83], v[226:229], v[200:203], v[80:83]
	v_mfma_f32_16x16x32_bf16 v[68:71], v[216:219], v[208:211], v[68:71]
	v_mfma_f32_16x16x32_bf16 v[64:67], v[226:229], v[208:211], v[64:67]
	v_mfma_f32_16x16x32_bf16 v[116:119], v[222:225], v[188:191], v[116:119]
	v_mfma_f32_16x16x32_bf16 v[112:115], v[230:233], v[188:191], v[112:115]
	v_mfma_f32_16x16x32_bf16 v[100:103], v[222:225], v[196:199], v[100:103]
	v_mfma_f32_16x16x32_bf16 v[96:99], v[230:233], v[196:199], v[96:99]
	v_mfma_f32_16x16x32_bf16 v[84:87], v[222:225], v[204:207], v[84:87]
	v_mfma_f32_16x16x32_bf16 v[80:83], v[230:233], v[204:207], v[80:83]
	v_mfma_f32_16x16x32_bf16 v[68:71], v[222:225], v[212:215], v[68:71]
	v_mfma_f32_16x16x32_bf16 v[64:67], v[230:233], v[212:215], v[64:67]
	s_mov_b32 m0, s35
	v_lshl_add_u64 v[154:155], v[162:163], 0, s[12:13]
	s_barrier
	ds_read_b128 v[184:187], v165 offset:49152
	ds_read_b128 v[188:191], v165 offset:50176
	ds_read_b128 v[192:195], v165 offset:51200
	ds_read_b128 v[196:199], v165 offset:52224
	ds_read_b128 v[200:203], v165 offset:53248
	ds_read_b128 v[204:207], v165 offset:54272
	ds_read_b128 v[208:211], v165 offset:55296
	ds_read_b128 v[212:215], v165 offset:56320
	global_load_lds_dwordx4 v[154:155], off
	v_lshl_add_u64 v[154:155], v[168:169], 0, s[12:13]
	s_mov_b32 m0, s36
	s_nop 0
	global_load_lds_dwordx4 v[154:155], off
	s_barrier
	s_waitcnt lgkmcnt(0)
	v_mfma_f32_16x16x32_bf16 v[60:63], v[144:147], v[184:187], v[60:63]
	v_mfma_f32_16x16x32_bf16 v[56:59], v[172:175], v[184:187], v[56:59]
	v_mfma_f32_16x16x32_bf16 v[44:47], v[144:147], v[192:195], v[44:47]
	v_mfma_f32_16x16x32_bf16 v[40:43], v[172:175], v[192:195], v[40:43]
	v_mfma_f32_16x16x32_bf16 v[28:31], v[144:147], v[200:203], v[28:31]
	v_mfma_f32_16x16x32_bf16 v[24:27], v[172:175], v[200:203], v[24:27]
	v_mfma_f32_16x16x32_bf16 v[12:15], v[144:147], v[208:211], v[12:15]
	v_mfma_f32_16x16x32_bf16 v[8:11], v[172:175], v[208:211], v[8:11]
	v_mfma_f32_16x16x32_bf16 v[60:63], v[148:151], v[188:191], v[60:63]
	v_mfma_f32_16x16x32_bf16 v[56:59], v[180:183], v[188:191], v[56:59]
	v_mfma_f32_16x16x32_bf16 v[44:47], v[148:151], v[196:199], v[44:47]
	v_mfma_f32_16x16x32_bf16 v[40:43], v[180:183], v[196:199], v[40:43]
	v_mfma_f32_16x16x32_bf16 v[28:31], v[148:151], v[204:207], v[28:31]
	v_mfma_f32_16x16x32_bf16 v[24:27], v[180:183], v[204:207], v[24:27]
	v_mfma_f32_16x16x32_bf16 v[12:15], v[148:151], v[212:215], v[12:15]
	v_mfma_f32_16x16x32_bf16 v[8:11], v[180:183], v[212:215], v[8:11]
	s_barrier
	s_add_u32 s4, s4, 0x40080
	s_addc_u32 s5, s5, 0
	s_add_i32 s10, s10, s15
	v_lshl_add_u64 v[144:145], s[4:5], 0, v[132:133]
	s_mov_b32 m0, s10
	s_nop 0
	global_load_lds_dwordx4 v[144:145], off
	v_lshl_add_u64 v[144:145], s[4:5], 0, v[128:129]
	s_add_i32 m0, s10, 0x2000
	s_nop 0
	global_load_lds_dwordx4 v[144:145], off
	s_waitcnt vmcnt(6)
	s_barrier
	v_mfma_f32_16x16x32_bf16 v[52:55], v[216:219], v[184:187], v[52:55]
	v_mfma_f32_16x16x32_bf16 v[48:51], v[226:229], v[184:187], v[48:51]
	v_mfma_f32_16x16x32_bf16 v[36:39], v[216:219], v[192:195], v[36:39]
	v_mfma_f32_16x16x32_bf16 v[32:35], v[226:229], v[192:195], v[32:35]
	v_mfma_f32_16x16x32_bf16 v[20:23], v[216:219], v[200:203], v[20:23]
	v_mfma_f32_16x16x32_bf16 v[16:19], v[226:229], v[200:203], v[16:19]
	v_mfma_f32_16x16x32_bf16 v[4:7], v[216:219], v[208:211], v[4:7]
	v_mfma_f32_16x16x32_bf16 v[0:3], v[226:229], v[208:211], v[0:3]
	v_mfma_f32_16x16x32_bf16 v[52:55], v[222:225], v[188:191], v[52:55]
	v_mfma_f32_16x16x32_bf16 v[48:51], v[230:233], v[188:191], v[48:51]
	v_mfma_f32_16x16x32_bf16 v[36:39], v[222:225], v[196:199], v[36:39]
	v_mfma_f32_16x16x32_bf16 v[32:35], v[230:233], v[196:199], v[32:35]
	v_mfma_f32_16x16x32_bf16 v[20:23], v[222:225], v[204:207], v[20:23]
	v_mfma_f32_16x16x32_bf16 v[16:19], v[230:233], v[204:207], v[16:19]
	v_mfma_f32_16x16x32_bf16 v[4:7], v[222:225], v[212:215], v[4:7]
	v_mfma_f32_16x16x32_bf16 v[0:3], v[230:233], v[212:215], v[0:3]
	s_add_i32 s45, s45, 2
	s_add_u32 s0, s0, 0x100
	s_addc_u32 s1, s1, 0
	s_add_u32 s43, s43, 0x100
	s_addc_u32 s44, s44, 0
	s_cmp_gt_u32 s45, 13
	s_barrier
	s_cbranch_scc0 .LBB0_1441
	v_lshl_add_u32 v168, s72, 8, v153
	v_ashrrev_i32_e32 v169, 31, v168
	v_or_b32_e32 v162, 16, v168
	v_lshlrev_b64 v[144:145], 6, v[168:169]
	v_ashrrev_i32_e32 v163, 31, v162
	v_or_b32_e32 v158, 32, v168
	v_lshl_add_u64 v[144:145], v[138:139], 0, v[144:145]
	v_lshlrev_b64 v[146:147], 6, v[162:163]
	v_ashrrev_i32_e32 v159, 31, v158
	v_lshl_add_u64 v[146:147], v[138:139], 0, v[146:147]
	global_load_dwordx4 v[172:175], v[144:145], off
	global_load_dwordx4 v[180:183], v[146:147], off
	v_lshlrev_b64 v[144:145], 6, v[158:159]
	v_or_b32_e32 v154, 48, v168
	v_lshl_add_u64 v[144:145], v[138:139], 0, v[144:145]
	v_ashrrev_i32_e32 v155, 31, v154
	global_load_dwordx4 v[184:187], v[144:145], off
	v_lshlrev_b64 v[144:145], 6, v[154:155]
	v_lshl_add_u64 v[144:145], v[138:139], 0, v[144:145]
	global_load_dwordx4 v[188:191], v[144:145], off
	v_add_u32_e32 v150, 0x80, v168
	v_ashrrev_i32_e32 v151, 31, v150
	v_lshlrev_b64 v[144:145], 6, v[150:151]
	v_add_u32_e32 v148, 0x90, v168
	v_lshl_add_u64 v[144:145], v[138:139], 0, v[144:145]
	v_ashrrev_i32_e32 v149, 31, v148
	global_load_dwordx4 v[192:195], v[144:145], off
	v_lshlrev_b64 v[144:145], 6, v[148:149]
	v_lshl_add_u64 v[144:145], v[138:139], 0, v[144:145]
	global_load_dwordx4 v[196:199], v[144:145], off
	v_and_b32_e32 v145, 64, v171
	v_add_u32_e32 v146, 0xa0, v168
	v_add_u32_e32 v144, 0xb0, v168
	v_add_u32_e32 v160, 64, v145
	v_ashrrev_i32_e32 v147, 31, v146
	v_ashrrev_i32_e32 v145, 31, v144
	v_lshlrev_b64 v[200:201], 6, v[146:147]
	v_lshlrev_b64 v[202:203], 6, v[144:145]
	v_lshl_add_u64 v[200:201], v[138:139], 0, v[200:201]
	v_lshl_add_u64 v[204:205], v[138:139], 0, v[202:203]
	global_load_dwordx4 v[200:203], v[200:201], off
	s_nop 0
	global_load_dwordx4 v[204:207], v[204:205], off
	v_xor_b32_e32 v152, 16, v171
	v_cmp_lt_i32_e32 vcc, v152, v160
	v_xor_b32_e32 v156, 32, v171
	v_mov_b64_e32 v[176:177], s[16:17]
	v_cndmask_b32_e32 v152, v171, v152, vcc
	v_lshlrev_b32_e32 v152, 2, v152
	v_cmp_lt_i32_e32 vcc, v156, v160
	v_lshlrev_b64 v[168:169], 7, v[168:169]
	s_mov_b32 s72, s18
	v_cndmask_b32_e32 v156, v171, v156, vcc
	v_lshlrev_b32_e32 v156, 2, v156
	s_mov_b32 s21, s18
	s_mov_b32 s19, s40
	s_waitcnt vmcnt(0)
	v_mov_b32_e32 v208, v173
	v_mov_b32_e32 v209, v174
	v_mov_b32_e32 v173, v175
	v_mov_b32_e32 v174, v181
	v_mov_b32_e32 v175, v182
	v_mov_b32_e32 v181, v183
	v_pk_add_f32 v[172:173], v[208:209], v[172:173]
	v_pk_add_f32 v[174:175], v[174:175], v[180:181]
	v_mov_b32_e32 v181, v172
	v_mov_b32_e32 v180, v174
	v_mov_b32_e32 v172, v175
	v_mov_b32_e32 v182, v185
	v_mov_b32_e32 v183, v186
	v_mov_b32_e32 v185, v187
	v_mov_b32_e32 v186, v189
	v_mov_b32_e32 v187, v190
	v_mov_b32_e32 v189, v191
	v_pk_add_f32 v[172:173], v[180:181], v[172:173]
	v_pk_add_f32 v[182:183], v[182:183], v[184:185]
	v_pk_add_f32 v[184:185], v[186:187], v[188:189]
	ds_bpermute_b32 v181, v152, v173
	ds_bpermute_b32 v180, v152, v172
	v_mov_b32_e32 v174, v184
	v_mov_b32_e32 v175, v182
	v_mov_b32_e32 v182, v185
	v_pk_add_f32 v[174:175], v[174:175], v[182:183]
	ds_bpermute_b32 v183, v152, v175
	ds_bpermute_b32 v182, v152, v174
	s_waitcnt lgkmcnt(0)
	v_pk_add_f32 v[172:173], v[172:173], v[180:181]
	ds_bpermute_b32 v181, v156, v173
	ds_bpermute_b32 v180, v156, v172
	v_mov_b32_e32 v184, v193
	v_pk_add_f32 v[174:175], v[174:175], v[182:183]
	ds_bpermute_b32 v183, v156, v175
	ds_bpermute_b32 v182, v156, v174
	s_waitcnt lgkmcnt(2)
	v_pk_add_f32 v[172:173], v[172:173], v[180:181]
	v_mov_b32_e32 v185, v194
	v_mov_b32_e32 v193, v195
	v_mov_b32_e32 v186, v197
	v_mov_b32_e32 v187, v198
	v_pk_fma_f32 v[172:173], v[172:173], s[14:15], v[176:177] op_sel_hi:[1,0,0]
	v_mov_b32_e32 v197, v199
	v_pk_add_f32 v[184:185], v[184:185], v[192:193]
	v_mul_f32_e32 v160, 0x4b800000, v173
	v_cmp_gt_f32_e32 vcc, s39, v173
	v_pk_add_f32 v[180:181], v[186:187], v[196:197]
	s_waitcnt lgkmcnt(0)
	v_pk_add_f32 v[174:175], v[174:175], v[182:183]
	v_cndmask_b32_e32 v160, v173, v160, vcc
	v_mov_b32_e32 v182, v180
	v_mov_b32_e32 v183, v184
	v_mov_b32_e32 v184, v181
	v_rsq_f32_e32 v160, v160
	v_pk_add_f32 v[180:181], v[182:183], v[184:185]
	ds_bpermute_b32 v183, v152, v181
	ds_bpermute_b32 v182, v152, v180
	v_pk_fma_f32 v[174:175], v[174:175], s[14:15], v[176:177] op_sel_hi:[1,0,0]
	v_mul_f32_e32 v164, 0x4b800000, v172
	v_cmp_gt_f32_e64 s[0:1], s39, v172
	v_mul_f32_e32 v170, 0x45800000, v160
	v_mul_f32_e32 v166, 0x4b800000, v175
	v_cndmask_b32_e64 v164, v172, v164, s[0:1]
	v_cmp_gt_f32_e64 s[4:5], s39, v175
	v_cndmask_b32_e32 v172, v160, v170, vcc
	v_mul_f32_e32 v160, 0x4b800000, v174
	v_cmp_gt_f32_e32 vcc, s39, v174
	v_cndmask_b32_e64 v166, v175, v166, s[4:5]
	v_mov_b32_e32 v184, v205
	v_cndmask_b32_e32 v160, v174, v160, vcc
	s_waitcnt lgkmcnt(0)
	v_pk_add_f32 v[174:175], v[180:181], v[182:183]
	ds_bpermute_b32 v181, v156, v175
	ds_bpermute_b32 v180, v156, v174
	v_mov_b32_e32 v185, v206
	v_mov_b32_e32 v205, v207
	v_pk_add_f32 v[184:185], v[184:185], v[204:205]
	v_rsq_f32_e32 v164, v164
	s_waitcnt lgkmcnt(0)
	v_pk_add_f32 v[174:175], v[174:175], v[180:181]
	v_mov_b32_e32 v180, v201
	v_mov_b32_e32 v181, v202
	v_mov_b32_e32 v201, v203
	v_pk_add_f32 v[180:181], v[180:181], v[200:201]
	v_mov_b32_e32 v186, v184
	v_mov_b32_e32 v187, v180
	v_mov_b32_e32 v180, v185
	v_rsq_f32_e32 v166, v166
	v_pk_add_f32 v[180:181], v[186:187], v[180:181]
	ds_bpermute_b32 v185, v152, v181
	ds_bpermute_b32 v184, v152, v180
	v_mul_f32_e32 v173, 0x45800000, v164
	v_cndmask_b32_e64 v182, v164, v173, s[0:1]
	v_mul_f32_e32 v164, 0x45800000, v166
	v_pk_fma_f32 v[174:175], v[174:175], s[14:15], v[176:177] op_sel_hi:[1,0,0]
	v_cndmask_b32_e64 v170, v166, v164, s[4:5]
	v_mul_f32_e32 v166, 0x4b800000, v175
	v_cmp_gt_f32_e64 s[0:1], s39, v175
	v_mul_f32_e32 v152, 0x4b800000, v174
	v_cmp_gt_f32_e64 s[4:5], s39, v174
	v_cndmask_b32_e64 v166, v175, v166, s[0:1]
	v_rsq_f32_e32 v160, v160
	v_cndmask_b32_e64 v152, v174, v152, s[4:5]
	s_waitcnt lgkmcnt(0)
	v_pk_add_f32 v[174:175], v[180:181], v[184:185]
	ds_bpermute_b32 v181, v156, v175
	ds_bpermute_b32 v180, v156, v174
	v_rsq_f32_e32 v173, v166
	v_mul_f32_e32 v164, 0x45800000, v160
	v_cndmask_b32_e32 v166, v160, v164, vcc
	v_rsq_f32_e32 v152, v152
	s_waitcnt lgkmcnt(0)
	v_pk_add_f32 v[174:175], v[174:175], v[180:181]
	v_mul_f32_e32 v156, 0x45800000, v173
	v_pk_fma_f32 v[174:175], v[174:175], s[14:15], v[176:177] op_sel_hi:[1,0,0]
	v_cndmask_b32_e64 v164, v173, v156, s[0:1]
	v_mul_f32_e32 v160, 0x4b800000, v175
	v_cmp_gt_f32_e32 vcc, s39, v175
	v_cmp_gt_f32_e64 s[0:1], s39, v174
	v_mul_f32_e32 v156, 0x45800000, v152
	v_cndmask_b32_e32 v160, v175, v160, vcc
	v_rsq_f32_e32 v173, v160
	v_mul_f32_e32 v160, 0x4b800000, v174
	v_cndmask_b32_e64 v160, v174, v160, s[0:1]
	v_rsq_f32_e32 v174, v160
	v_cndmask_b32_e64 v160, v152, v156, s[4:5]
	v_mul_f32_e32 v152, 0x45800000, v173
	v_cndmask_b32_e32 v156, v173, v152, vcc
	v_mul_f32_e32 v152, 0x45800000, v174
	v_cndmask_b32_e64 v152, v174, v152, s[0:1]
	s_lshl_b32 s0, s70, 8
	s_or_b32 s0, s0, s33
	s_ashr_i32 s4, s0, 6
	s_ashr_i32 s5, s4, 31
	s_lshl_b64 s[0:1], s[4:5], 22
	v_pk_mul_f32 v[124:125], v[124:125], v[172:173] op_sel_hi:[1,0]
	v_pk_mul_f32 v[120:121], v[120:121], v[172:173] op_sel_hi:[1,0]
	s_add_u32 s0, s84, s0
	v_pk_mul_f32 v[126:127], v[126:127], v[172:173] op_sel_hi:[1,0]
	v_pk_mul_f32 v[122:123], v[122:123], v[172:173] op_sel_hi:[1,0]
	v_max_f32_e32 v124, 0, v124
	v_max_f32_e32 v120, 0, v120
	v_max_f32_e32 v125, 0, v125
	v_max_f32_e32 v121, 0, v121
	s_addc_u32 s1, s85, s1
	s_or_b32 s4, s4, 2
	v_pk_mul_f32 v[124:125], v[124:125], v[124:125]
	v_pk_mul_f32 v[174:175], v[120:121], v[120:121]
	v_max_f32_e32 v120, 0, v126
	v_max_f32_e32 v122, 0, v122
	v_max_f32_e32 v121, 0, v127
	v_max_f32_e32 v123, 0, v123
	s_ashr_i32 s5, s4, 31
	v_pk_mul_f32 v[126:127], v[120:121], v[120:121]
	v_pk_mul_f32 v[176:177], v[122:123], v[122:123]
	v_cvt_pk_bf16_f32 v120, v124, v125
	v_lshl_add_u64 v[124:125], s[0:1], 0, v[168:169]
	v_pk_mul_f32 v[116:117], v[116:117], v[172:173] op_sel_hi:[1,0]
	v_pk_mul_f32 v[112:113], v[112:113], v[172:173] op_sel_hi:[1,0]
	s_lshl_b64 s[4:5], s[4:5], 22
	v_cvt_pk_bf16_f32 v121, v126, v127
	v_cvt_pk_bf16_f32 v122, v174, v175
	v_cvt_pk_bf16_f32 v123, v176, v177
	v_lshl_add_u64 v[124:125], v[124:125], 0, v[136:137]
	v_pk_mul_f32 v[118:119], v[118:119], v[172:173] op_sel_hi:[1,0]
	v_pk_mul_f32 v[114:115], v[114:115], v[172:173] op_sel_hi:[1,0]
	v_max_f32_e32 v116, 0, v116
	v_max_f32_e32 v112, 0, v112
	v_max_f32_e32 v117, 0, v117
	v_max_f32_e32 v113, 0, v113
	s_add_u32 s4, s84, s4
	global_store_dwordx4 v[124:125], v[120:123], off nt
	v_pk_mul_f32 v[116:117], v[116:117], v[116:117]
	v_max_f32_e32 v114, 0, v114
	v_pk_mul_f32 v[120:121], v[112:113], v[112:113]
	v_max_f32_e32 v112, 0, v118
	v_max_f32_e32 v113, 0, v119
	v_max_f32_e32 v115, 0, v115
	s_addc_u32 s5, s85, s5
	v_pk_mul_f32 v[118:119], v[112:113], v[112:113]
	v_pk_mul_f32 v[122:123], v[114:115], v[114:115]
	v_cvt_pk_bf16_f32 v112, v116, v117
	v_lshl_add_u64 v[116:117], s[4:5], 0, v[168:169]
	v_pk_mul_f32 v[108:109], v[108:109], v[182:183] op_sel_hi:[1,0]
	v_pk_mul_f32 v[104:105], v[104:105], v[182:183] op_sel_hi:[1,0]
	v_cvt_pk_bf16_f32 v113, v118, v119
	v_cvt_pk_bf16_f32 v114, v120, v121
	v_cvt_pk_bf16_f32 v115, v122, v123
	v_lshl_add_u64 v[116:117], v[116:117], 0, v[136:137]
	v_pk_mul_f32 v[110:111], v[110:111], v[182:183] op_sel_hi:[1,0]
	v_pk_mul_f32 v[106:107], v[106:107], v[182:183] op_sel_hi:[1,0]
	v_max_f32_e32 v108, 0, v108
	v_max_f32_e32 v104, 0, v104
	v_max_f32_e32 v109, 0, v109
	v_max_f32_e32 v105, 0, v105
	global_store_dwordx4 v[116:117], v[112:115], off nt
	v_pk_mul_f32 v[108:109], v[108:109], v[108:109]
	v_max_f32_e32 v106, 0, v106
	v_lshlrev_b64 v[112:113], 7, v[162:163]
	v_pk_mul_f32 v[114:115], v[104:105], v[104:105]
	v_max_f32_e32 v104, 0, v110
	v_max_f32_e32 v105, 0, v111
	v_max_f32_e32 v107, 0, v107
	v_pk_mul_f32 v[110:111], v[104:105], v[104:105]
	v_pk_mul_f32 v[116:117], v[106:107], v[106:107]
	v_cvt_pk_bf16_f32 v104, v108, v109
	v_lshl_add_u64 v[108:109], s[0:1], 0, v[112:113]
	v_pk_mul_f32 v[100:101], v[100:101], v[182:183] op_sel_hi:[1,0]
	v_pk_mul_f32 v[96:97], v[96:97], v[182:183] op_sel_hi:[1,0]
	v_cvt_pk_bf16_f32 v105, v110, v111
	v_cvt_pk_bf16_f32 v106, v114, v115
	v_cvt_pk_bf16_f32 v107, v116, v117
	v_lshl_add_u64 v[108:109], v[108:109], 0, v[136:137]
	v_pk_mul_f32 v[102:103], v[102:103], v[182:183] op_sel_hi:[1,0]
	v_pk_mul_f32 v[98:99], v[98:99], v[182:183] op_sel_hi:[1,0]
	v_max_f32_e32 v100, 0, v100
	v_max_f32_e32 v96, 0, v96
	v_max_f32_e32 v101, 0, v101
	v_max_f32_e32 v97, 0, v97
	global_store_dwordx4 v[108:109], v[104:107], off nt
	v_pk_mul_f32 v[100:101], v[100:101], v[100:101]
	v_max_f32_e32 v98, 0, v98
	v_pk_mul_f32 v[104:105], v[96:97], v[96:97]
	v_max_f32_e32 v96, 0, v102
	v_max_f32_e32 v97, 0, v103
	v_max_f32_e32 v99, 0, v99
	v_pk_mul_f32 v[102:103], v[96:97], v[96:97]
	v_pk_mul_f32 v[106:107], v[98:99], v[98:99]
	v_cvt_pk_bf16_f32 v96, v100, v101
	v_lshl_add_u64 v[100:101], s[4:5], 0, v[112:113]
	v_pk_mul_f32 v[92:93], v[92:93], v[170:171] op_sel_hi:[1,0]
	v_pk_mul_f32 v[88:89], v[88:89], v[170:171] op_sel_hi:[1,0]
	v_cvt_pk_bf16_f32 v97, v102, v103
	v_cvt_pk_bf16_f32 v98, v104, v105
	v_cvt_pk_bf16_f32 v99, v106, v107
	v_lshl_add_u64 v[100:101], v[100:101], 0, v[136:137]
	v_pk_mul_f32 v[94:95], v[94:95], v[170:171] op_sel_hi:[1,0]
	v_pk_mul_f32 v[90:91], v[90:91], v[170:171] op_sel_hi:[1,0]
	v_max_f32_e32 v92, 0, v92
	v_max_f32_e32 v88, 0, v88
	v_max_f32_e32 v93, 0, v93
	v_max_f32_e32 v89, 0, v89
	global_store_dwordx4 v[100:101], v[96:99], off nt
	v_pk_mul_f32 v[92:93], v[92:93], v[92:93]
	v_max_f32_e32 v90, 0, v90
	v_lshlrev_b64 v[96:97], 7, v[158:159]
	v_pk_mul_f32 v[98:99], v[88:89], v[88:89]
	v_max_f32_e32 v88, 0, v94
	v_max_f32_e32 v89, 0, v95
	v_max_f32_e32 v91, 0, v91
	v_pk_mul_f32 v[94:95], v[88:89], v[88:89]
	v_pk_mul_f32 v[100:101], v[90:91], v[90:91]
	v_cvt_pk_bf16_f32 v88, v92, v93
	v_lshl_add_u64 v[92:93], s[0:1], 0, v[96:97]
	v_pk_mul_f32 v[84:85], v[84:85], v[170:171] op_sel_hi:[1,0]
	v_pk_mul_f32 v[80:81], v[80:81], v[170:171] op_sel_hi:[1,0]
	v_cvt_pk_bf16_f32 v89, v94, v95
	v_cvt_pk_bf16_f32 v90, v98, v99
	v_cvt_pk_bf16_f32 v91, v100, v101
	v_lshl_add_u64 v[92:93], v[92:93], 0, v[136:137]
	v_pk_mul_f32 v[86:87], v[86:87], v[170:171] op_sel_hi:[1,0]
	v_pk_mul_f32 v[82:83], v[82:83], v[170:171] op_sel_hi:[1,0]
	v_max_f32_e32 v84, 0, v84
	v_max_f32_e32 v80, 0, v80
	v_max_f32_e32 v85, 0, v85
	v_max_f32_e32 v81, 0, v81
	global_store_dwordx4 v[92:93], v[88:91], off nt
	v_pk_mul_f32 v[84:85], v[84:85], v[84:85]
	v_max_f32_e32 v82, 0, v82
	v_pk_mul_f32 v[88:89], v[80:81], v[80:81]
	v_max_f32_e32 v80, 0, v86
	v_max_f32_e32 v81, 0, v87
	v_max_f32_e32 v83, 0, v83
	v_pk_mul_f32 v[86:87], v[80:81], v[80:81]
	v_pk_mul_f32 v[90:91], v[82:83], v[82:83]
	v_cvt_pk_bf16_f32 v80, v84, v85
	v_lshl_add_u64 v[84:85], s[4:5], 0, v[96:97]
	v_pk_mul_f32 v[76:77], v[76:77], v[166:167] op_sel_hi:[1,0]
	v_pk_mul_f32 v[72:73], v[72:73], v[166:167] op_sel_hi:[1,0]
	v_cvt_pk_bf16_f32 v81, v86, v87
	v_cvt_pk_bf16_f32 v82, v88, v89
	v_cvt_pk_bf16_f32 v83, v90, v91
	v_lshl_add_u64 v[84:85], v[84:85], 0, v[136:137]
	v_pk_mul_f32 v[78:79], v[78:79], v[166:167] op_sel_hi:[1,0]
	v_pk_mul_f32 v[74:75], v[74:75], v[166:167] op_sel_hi:[1,0]
	v_max_f32_e32 v76, 0, v76
	v_max_f32_e32 v72, 0, v72
	v_max_f32_e32 v77, 0, v77
	v_max_f32_e32 v73, 0, v73
	global_store_dwordx4 v[84:85], v[80:83], off nt
	v_pk_mul_f32 v[76:77], v[76:77], v[76:77]
	v_max_f32_e32 v74, 0, v74
	v_lshlrev_b64 v[80:81], 7, v[154:155]
	v_pk_mul_f32 v[82:83], v[72:73], v[72:73]
	v_max_f32_e32 v72, 0, v78
	v_max_f32_e32 v73, 0, v79
	v_max_f32_e32 v75, 0, v75
	v_pk_mul_f32 v[78:79], v[72:73], v[72:73]
	v_pk_mul_f32 v[84:85], v[74:75], v[74:75]
	v_cvt_pk_bf16_f32 v72, v76, v77
	v_lshl_add_u64 v[76:77], s[0:1], 0, v[80:81]
	v_pk_mul_f32 v[68:69], v[68:69], v[166:167] op_sel_hi:[1,0]
	v_pk_mul_f32 v[64:65], v[64:65], v[166:167] op_sel_hi:[1,0]
	v_cvt_pk_bf16_f32 v73, v78, v79
	v_cvt_pk_bf16_f32 v74, v82, v83
	v_cvt_pk_bf16_f32 v75, v84, v85
	v_lshl_add_u64 v[76:77], v[76:77], 0, v[136:137]
	v_pk_mul_f32 v[70:71], v[70:71], v[166:167] op_sel_hi:[1,0]
	v_pk_mul_f32 v[66:67], v[66:67], v[166:167] op_sel_hi:[1,0]
	v_max_f32_e32 v68, 0, v68
	v_max_f32_e32 v64, 0, v64
	v_max_f32_e32 v69, 0, v69
	v_max_f32_e32 v65, 0, v65
	global_store_dwordx4 v[76:77], v[72:75], off nt
	v_pk_mul_f32 v[68:69], v[68:69], v[68:69]
	v_max_f32_e32 v66, 0, v66
	v_pk_mul_f32 v[72:73], v[64:65], v[64:65]
	v_max_f32_e32 v64, 0, v70
	v_max_f32_e32 v65, 0, v71
	v_max_f32_e32 v67, 0, v67
	v_pk_mul_f32 v[70:71], v[64:65], v[64:65]
	v_pk_mul_f32 v[74:75], v[66:67], v[66:67]
	v_cvt_pk_bf16_f32 v64, v68, v69
	v_lshl_add_u64 v[68:69], s[4:5], 0, v[80:81]
	v_pk_mul_f32 v[60:61], v[60:61], v[164:165] op_sel_hi:[1,0]
	v_pk_mul_f32 v[56:57], v[56:57], v[164:165] op_sel_hi:[1,0]
	v_cvt_pk_bf16_f32 v65, v70, v71
	v_cvt_pk_bf16_f32 v66, v72, v73
	v_cvt_pk_bf16_f32 v67, v74, v75
	v_lshl_add_u64 v[68:69], v[68:69], 0, v[136:137]
	v_pk_mul_f32 v[62:63], v[62:63], v[164:165] op_sel_hi:[1,0]
	v_pk_mul_f32 v[58:59], v[58:59], v[164:165] op_sel_hi:[1,0]
	v_max_f32_e32 v60, 0, v60
	v_max_f32_e32 v56, 0, v56
	v_max_f32_e32 v61, 0, v61
	v_max_f32_e32 v57, 0, v57
	global_store_dwordx4 v[68:69], v[64:67], off nt
	v_pk_mul_f32 v[60:61], v[60:61], v[60:61]
	v_max_f32_e32 v58, 0, v58
	v_lshlrev_b64 v[64:65], 7, v[150:151]
	v_pk_mul_f32 v[66:67], v[56:57], v[56:57]
	v_max_f32_e32 v56, 0, v62
	v_max_f32_e32 v57, 0, v63
	v_max_f32_e32 v59, 0, v59
	v_pk_mul_f32 v[62:63], v[56:57], v[56:57]
	v_pk_mul_f32 v[68:69], v[58:59], v[58:59]
	v_cvt_pk_bf16_f32 v56, v60, v61
	v_lshl_add_u64 v[60:61], s[0:1], 0, v[64:65]
	v_pk_mul_f32 v[52:53], v[52:53], v[164:165] op_sel_hi:[1,0]
	v_pk_mul_f32 v[48:49], v[48:49], v[164:165] op_sel_hi:[1,0]
	v_cvt_pk_bf16_f32 v57, v62, v63
	v_cvt_pk_bf16_f32 v58, v66, v67
	v_cvt_pk_bf16_f32 v59, v68, v69
	v_lshl_add_u64 v[60:61], v[60:61], 0, v[136:137]
	v_pk_mul_f32 v[54:55], v[54:55], v[164:165] op_sel_hi:[1,0]
	v_pk_mul_f32 v[50:51], v[50:51], v[164:165] op_sel_hi:[1,0]
	v_max_f32_e32 v52, 0, v52
	v_max_f32_e32 v48, 0, v48
	v_max_f32_e32 v53, 0, v53
	v_max_f32_e32 v49, 0, v49
	global_store_dwordx4 v[60:61], v[56:59], off nt
	v_pk_mul_f32 v[52:53], v[52:53], v[52:53]
	v_max_f32_e32 v50, 0, v50
	v_pk_mul_f32 v[56:57], v[48:49], v[48:49]
	v_max_f32_e32 v48, 0, v54
	v_max_f32_e32 v49, 0, v55
	v_max_f32_e32 v51, 0, v51
	v_pk_mul_f32 v[54:55], v[48:49], v[48:49]
	v_pk_mul_f32 v[58:59], v[50:51], v[50:51]
	v_cvt_pk_bf16_f32 v48, v52, v53
	v_lshl_add_u64 v[52:53], s[4:5], 0, v[64:65]
	v_pk_mul_f32 v[44:45], v[44:45], v[160:161] op_sel_hi:[1,0]
	v_pk_mul_f32 v[40:41], v[40:41], v[160:161] op_sel_hi:[1,0]
	v_cvt_pk_bf16_f32 v49, v54, v55
	v_cvt_pk_bf16_f32 v50, v56, v57
	v_cvt_pk_bf16_f32 v51, v58, v59
	v_lshl_add_u64 v[52:53], v[52:53], 0, v[136:137]
	v_pk_mul_f32 v[46:47], v[46:47], v[160:161] op_sel_hi:[1,0]
	v_pk_mul_f32 v[42:43], v[42:43], v[160:161] op_sel_hi:[1,0]
	v_max_f32_e32 v44, 0, v44
	v_max_f32_e32 v40, 0, v40
	v_max_f32_e32 v45, 0, v45
	v_max_f32_e32 v41, 0, v41
	global_store_dwordx4 v[52:53], v[48:51], off nt
	v_pk_mul_f32 v[44:45], v[44:45], v[44:45]
	v_max_f32_e32 v42, 0, v42
	v_lshlrev_b64 v[48:49], 7, v[148:149]
	v_pk_mul_f32 v[50:51], v[40:41], v[40:41]
	v_max_f32_e32 v40, 0, v46
	v_max_f32_e32 v41, 0, v47
	v_max_f32_e32 v43, 0, v43
	v_pk_mul_f32 v[46:47], v[40:41], v[40:41]
	v_pk_mul_f32 v[52:53], v[42:43], v[42:43]
	v_cvt_pk_bf16_f32 v40, v44, v45
	v_lshl_add_u64 v[44:45], s[0:1], 0, v[48:49]
	v_pk_mul_f32 v[36:37], v[36:37], v[160:161] op_sel_hi:[1,0]
	v_pk_mul_f32 v[32:33], v[32:33], v[160:161] op_sel_hi:[1,0]
	v_cvt_pk_bf16_f32 v41, v46, v47
	v_cvt_pk_bf16_f32 v42, v50, v51
	v_cvt_pk_bf16_f32 v43, v52, v53
	v_lshl_add_u64 v[44:45], v[44:45], 0, v[136:137]
	v_pk_mul_f32 v[38:39], v[38:39], v[160:161] op_sel_hi:[1,0]
	v_pk_mul_f32 v[34:35], v[34:35], v[160:161] op_sel_hi:[1,0]
	v_max_f32_e32 v36, 0, v36
	v_max_f32_e32 v32, 0, v32
	v_max_f32_e32 v37, 0, v37
	v_max_f32_e32 v33, 0, v33
	global_store_dwordx4 v[44:45], v[40:43], off nt
	v_pk_mul_f32 v[36:37], v[36:37], v[36:37]
	v_max_f32_e32 v34, 0, v34
	v_pk_mul_f32 v[40:41], v[32:33], v[32:33]
	v_max_f32_e32 v32, 0, v38
	v_max_f32_e32 v33, 0, v39
	v_max_f32_e32 v35, 0, v35
	v_pk_mul_f32 v[38:39], v[32:33], v[32:33]
	v_pk_mul_f32 v[42:43], v[34:35], v[34:35]
	v_cvt_pk_bf16_f32 v32, v36, v37
	v_lshl_add_u64 v[36:37], s[4:5], 0, v[48:49]
	v_pk_mul_f32 v[28:29], v[28:29], v[156:157] op_sel_hi:[1,0]
	v_pk_mul_f32 v[24:25], v[24:25], v[156:157] op_sel_hi:[1,0]
	v_cvt_pk_bf16_f32 v33, v38, v39
	v_cvt_pk_bf16_f32 v34, v40, v41
	v_cvt_pk_bf16_f32 v35, v42, v43
	v_lshl_add_u64 v[36:37], v[36:37], 0, v[136:137]
	v_pk_mul_f32 v[30:31], v[30:31], v[156:157] op_sel_hi:[1,0]
	v_pk_mul_f32 v[26:27], v[26:27], v[156:157] op_sel_hi:[1,0]
	v_max_f32_e32 v28, 0, v28
	v_max_f32_e32 v24, 0, v24
	v_max_f32_e32 v29, 0, v29
	v_max_f32_e32 v25, 0, v25
	global_store_dwordx4 v[36:37], v[32:35], off nt
	v_pk_mul_f32 v[28:29], v[28:29], v[28:29]
	v_max_f32_e32 v26, 0, v26
	v_lshlrev_b64 v[32:33], 7, v[146:147]
	v_pk_mul_f32 v[34:35], v[24:25], v[24:25]
	v_max_f32_e32 v24, 0, v30
	v_max_f32_e32 v25, 0, v31
	v_max_f32_e32 v27, 0, v27
	v_pk_mul_f32 v[30:31], v[24:25], v[24:25]
	v_pk_mul_f32 v[36:37], v[26:27], v[26:27]
	v_cvt_pk_bf16_f32 v24, v28, v29
	v_lshl_add_u64 v[28:29], s[0:1], 0, v[32:33]
	v_pk_mul_f32 v[20:21], v[20:21], v[156:157] op_sel_hi:[1,0]
	v_pk_mul_f32 v[16:17], v[16:17], v[156:157] op_sel_hi:[1,0]
	v_cvt_pk_bf16_f32 v25, v30, v31
	v_cvt_pk_bf16_f32 v26, v34, v35
	v_cvt_pk_bf16_f32 v27, v36, v37
	v_lshl_add_u64 v[28:29], v[28:29], 0, v[136:137]
	v_pk_mul_f32 v[22:23], v[22:23], v[156:157] op_sel_hi:[1,0]
	v_pk_mul_f32 v[18:19], v[18:19], v[156:157] op_sel_hi:[1,0]
	v_max_f32_e32 v20, 0, v20
	v_max_f32_e32 v16, 0, v16
	v_max_f32_e32 v21, 0, v21
	v_max_f32_e32 v17, 0, v17
	global_store_dwordx4 v[28:29], v[24:27], off nt
	v_pk_mul_f32 v[20:21], v[20:21], v[20:21]
	v_max_f32_e32 v18, 0, v18
	v_pk_mul_f32 v[24:25], v[16:17], v[16:17]
	v_max_f32_e32 v16, 0, v22
	v_max_f32_e32 v17, 0, v23
	v_max_f32_e32 v19, 0, v19
	v_pk_mul_f32 v[22:23], v[16:17], v[16:17]
	v_pk_mul_f32 v[26:27], v[18:19], v[18:19]
	v_cvt_pk_bf16_f32 v16, v20, v21
	v_lshl_add_u64 v[20:21], s[4:5], 0, v[32:33]
	v_pk_mul_f32 v[12:13], v[12:13], v[152:153] op_sel_hi:[1,0]
	v_pk_mul_f32 v[8:9], v[8:9], v[152:153] op_sel_hi:[1,0]
	v_cvt_pk_bf16_f32 v17, v22, v23
	v_cvt_pk_bf16_f32 v18, v24, v25
	v_cvt_pk_bf16_f32 v19, v26, v27
	v_lshl_add_u64 v[20:21], v[20:21], 0, v[136:137]
	v_pk_mul_f32 v[14:15], v[14:15], v[152:153] op_sel_hi:[1,0]
	v_pk_mul_f32 v[10:11], v[10:11], v[152:153] op_sel_hi:[1,0]
	v_max_f32_e32 v12, 0, v12
	v_max_f32_e32 v8, 0, v8
	v_max_f32_e32 v13, 0, v13
	v_max_f32_e32 v9, 0, v9
	global_store_dwordx4 v[20:21], v[16:19], off nt
	v_pk_mul_f32 v[12:13], v[12:13], v[12:13]
	v_max_f32_e32 v10, 0, v10
	v_lshlrev_b64 v[16:17], 7, v[144:145]
	v_pk_mul_f32 v[18:19], v[8:9], v[8:9]
	v_max_f32_e32 v8, 0, v14
	v_max_f32_e32 v9, 0, v15
	v_max_f32_e32 v11, 0, v11
	v_pk_mul_f32 v[14:15], v[8:9], v[8:9]
	v_pk_mul_f32 v[20:21], v[10:11], v[10:11]
	v_cvt_pk_bf16_f32 v8, v12, v13
	v_lshl_add_u64 v[12:13], s[0:1], 0, v[16:17]
	v_pk_mul_f32 v[4:5], v[4:5], v[152:153] op_sel_hi:[1,0]
	v_pk_mul_f32 v[0:1], v[0:1], v[152:153] op_sel_hi:[1,0]
	v_cvt_pk_bf16_f32 v9, v14, v15
	v_cvt_pk_bf16_f32 v10, v18, v19
	v_cvt_pk_bf16_f32 v11, v20, v21
	v_lshl_add_u64 v[12:13], v[12:13], 0, v[136:137]
	v_pk_mul_f32 v[6:7], v[6:7], v[152:153] op_sel_hi:[1,0]
	v_pk_mul_f32 v[2:3], v[2:3], v[152:153] op_sel_hi:[1,0]
	v_max_f32_e32 v4, 0, v4
	v_max_f32_e32 v0, 0, v0
	v_max_f32_e32 v5, 0, v5
	v_max_f32_e32 v1, 0, v1
	global_store_dwordx4 v[12:13], v[8:11], off nt
	v_pk_mul_f32 v[4:5], v[4:5], v[4:5]
	v_max_f32_e32 v2, 0, v2
	v_pk_mul_f32 v[8:9], v[0:1], v[0:1]
	v_max_f32_e32 v0, 0, v6
	v_max_f32_e32 v1, 0, v7
	v_max_f32_e32 v3, 0, v3
	v_pk_mul_f32 v[6:7], v[0:1], v[0:1]
	v_pk_mul_f32 v[10:11], v[2:3], v[2:3]
	v_cvt_pk_bf16_f32 v0, v4, v5
	v_lshl_add_u64 v[4:5], s[4:5], 0, v[16:17]
	v_cvt_pk_bf16_f32 v1, v6, v7
	v_cvt_pk_bf16_f32 v2, v8, v9
	v_cvt_pk_bf16_f32 v3, v10, v11
	v_lshl_add_u64 v[4:5], v[4:5], 0, v[136:137]
	s_and_b64 vcc, exec, s[24:25]
	s_mov_b32 s70, s20
	s_mov_b32 s24, s20
	s_mov_b64 s[4:5], s[26:27]
	s_mov_b64 s[0:1], s[22:23]
	global_store_dwordx4 v[4:5], v[0:3], off nt
	s_cbranch_vccz .LBB0_1433
	s_waitcnt vmcnt(0)
	s_cmpk_gt_u32 s7, 0xff
	s_cbranch_scc1 .LBB0_1445
	s_barrier

.LBB0_1512:
	ds_read_b128 v[144:147], v204
	ds_read_b128 v[148:151], v204 offset:1024
	ds_read_b128 v[172:175], v204 offset:2048
	ds_read_b128 v[176:179], v204 offset:3072
	ds_read_b128 v[180:183], v204 offset:4096
	ds_read_b128 v[184:187], v204 offset:5120
	ds_read_b128 v[188:191], v204 offset:6144
	ds_read_b128 v[192:195], v204 offset:7168
	ds_read_b128 v[128:131], v203
	ds_read_b128 v[132:135], v203 offset:1024
	ds_read_b128 v[136:139], v203 offset:2048
	ds_read_b128 v[140:143], v203 offset:3072
	s_add_u32 s26, s24, 0x3fc000
	s_addc_u32 s27, s25, 0
	s_cmp_eq_u32 s49, 60
	s_cselect_b32 s30, s7, s26
	s_cselect_b32 s31, s5, s27
	s_cselect_b32 s26, s15, s17
	s_cselect_b32 s27, s8, s48
	s_add_u32 s28, s30, 0x400000
	s_addc_u32 s29, s31, 0
	v_lshl_add_u64 v[196:197], s[24:25], 0, v[168:169]
	s_add_i32 m0, s33, 0xc000
	s_nop 0
	global_load_lds_dwordx4 v[196:197], off
	v_lshl_add_u64 v[196:197], s[24:25], 0, v[170:171]
	s_add_i32 m0, s33, 0xe000
	s_nop 0
	global_load_lds_dwordx4 v[196:197], off
	s_waitcnt lgkmcnt(0)
	s_barrier
	s_waitcnt lgkmcnt(0)
	v_mfma_f32_16x16x32_bf16 v[124:127], v[128:131], v[144:147], v[124:127]
	v_mfma_f32_16x16x32_bf16 v[120:123], v[136:139], v[144:147], v[120:123]
	v_mfma_f32_16x16x32_bf16 v[108:111], v[128:131], v[172:175], v[108:111]
	v_mfma_f32_16x16x32_bf16 v[104:107], v[136:139], v[172:175], v[104:107]
	v_mfma_f32_16x16x32_bf16 v[92:95], v[128:131], v[180:183], v[92:95]
	v_mfma_f32_16x16x32_bf16 v[88:91], v[136:139], v[180:183], v[88:91]
	v_mfma_f32_16x16x32_bf16 v[76:79], v[128:131], v[188:191], v[76:79]
	v_mfma_f32_16x16x32_bf16 v[72:75], v[136:139], v[188:191], v[72:75]
	v_mfma_f32_16x16x32_bf16 v[124:127], v[132:135], v[148:151], v[124:127]
	v_mfma_f32_16x16x32_bf16 v[120:123], v[140:143], v[148:151], v[120:123]
	v_mfma_f32_16x16x32_bf16 v[108:111], v[132:135], v[176:179], v[108:111]
	v_mfma_f32_16x16x32_bf16 v[104:107], v[140:143], v[176:179], v[104:107]
	v_mfma_f32_16x16x32_bf16 v[92:95], v[132:135], v[184:187], v[92:95]
	v_mfma_f32_16x16x32_bf16 v[88:91], v[140:143], v[184:187], v[88:91]
	v_mfma_f32_16x16x32_bf16 v[76:79], v[132:135], v[192:195], v[76:79]
	v_mfma_f32_16x16x32_bf16 v[72:75], v[140:143], v[192:195], v[72:75]
	s_barrier
	s_add_i32 s50, s44, s13
	v_lshl_add_u64 v[200:201], s[26:27], 0, v[156:157]
	s_mov_b32 m0, s50
	ds_read_b128 v[196:199], v205
	ds_read_b128 v[208:211], v205 offset:1024
	ds_read_b128 v[212:215], v205 offset:2048
	ds_read_b128 v[216:219], v205 offset:3072
	global_load_lds_dwordx4 v[200:201], off
	v_lshl_add_u64 v[200:201], s[26:27], 0, v[152:153]
	s_add_i32 m0, s50, 0x2000
	s_nop 0
	global_load_lds_dwordx4 v[200:201], off
	s_barrier
	s_waitcnt lgkmcnt(0)
	v_mfma_f32_16x16x32_bf16 v[116:119], v[196:199], v[144:147], v[116:119]
	v_mfma_f32_16x16x32_bf16 v[112:115], v[212:215], v[144:147], v[112:115]
	v_mfma_f32_16x16x32_bf16 v[100:103], v[196:199], v[172:175], v[100:103]
	v_mfma_f32_16x16x32_bf16 v[96:99], v[212:215], v[172:175], v[96:99]
	v_mfma_f32_16x16x32_bf16 v[84:87], v[196:199], v[180:183], v[84:87]
	v_mfma_f32_16x16x32_bf16 v[80:83], v[212:215], v[180:183], v[80:83]
	v_mfma_f32_16x16x32_bf16 v[68:71], v[196:199], v[188:191], v[68:71]
	v_mfma_f32_16x16x32_bf16 v[64:67], v[212:215], v[188:191], v[64:67]
	v_mfma_f32_16x16x32_bf16 v[116:119], v[208:211], v[148:151], v[116:119]
	v_mfma_f32_16x16x32_bf16 v[112:115], v[216:219], v[148:151], v[112:115]
	v_mfma_f32_16x16x32_bf16 v[100:103], v[208:211], v[176:179], v[100:103]
	v_mfma_f32_16x16x32_bf16 v[96:99], v[216:219], v[176:179], v[96:99]
	v_mfma_f32_16x16x32_bf16 v[84:87], v[208:211], v[184:187], v[84:87]
	v_mfma_f32_16x16x32_bf16 v[80:83], v[216:219], v[184:187], v[80:83]
	v_mfma_f32_16x16x32_bf16 v[68:71], v[208:211], v[192:195], v[68:71]
	v_mfma_f32_16x16x32_bf16 v[64:67], v[216:219], v[192:195], v[64:67]
	s_mov_b32 m0, s33
	v_lshl_add_u64 v[200:201], s[30:31], 0, v[158:159]
	s_barrier
	ds_read_b128 v[144:147], v204 offset:16384
	ds_read_b128 v[148:151], v204 offset:17408
	ds_read_b128 v[172:175], v204 offset:18432
	ds_read_b128 v[176:179], v204 offset:19456
	ds_read_b128 v[180:183], v204 offset:20480
	ds_read_b128 v[184:187], v204 offset:21504
	ds_read_b128 v[188:191], v204 offset:22528
	ds_read_b128 v[192:195], v204 offset:23552
	global_load_lds_dwordx4 v[200:201], off
	v_lshl_add_u64 v[200:201], s[30:31], 0, v[154:155]
	s_mov_b32 m0, s35
	s_nop 0
	global_load_lds_dwordx4 v[200:201], off
	s_barrier
	s_waitcnt lgkmcnt(0)
	v_mfma_f32_16x16x32_bf16 v[60:63], v[128:131], v[144:147], v[60:63]
	v_mfma_f32_16x16x32_bf16 v[56:59], v[136:139], v[144:147], v[56:59]
	v_mfma_f32_16x16x32_bf16 v[44:47], v[128:131], v[172:175], v[44:47]
	v_mfma_f32_16x16x32_bf16 v[40:43], v[136:139], v[172:175], v[40:43]
	v_mfma_f32_16x16x32_bf16 v[28:31], v[128:131], v[180:183], v[28:31]
	v_mfma_f32_16x16x32_bf16 v[24:27], v[136:139], v[180:183], v[24:27]
	v_mfma_f32_16x16x32_bf16 v[12:15], v[128:131], v[188:191], v[12:15]
	v_mfma_f32_16x16x32_bf16 v[8:11], v[136:139], v[188:191], v[8:11]
	v_mfma_f32_16x16x32_bf16 v[60:63], v[132:135], v[148:151], v[60:63]
	v_mfma_f32_16x16x32_bf16 v[56:59], v[140:143], v[148:151], v[56:59]
	v_mfma_f32_16x16x32_bf16 v[44:47], v[132:135], v[176:179], v[44:47]
	v_mfma_f32_16x16x32_bf16 v[40:43], v[140:143], v[176:179], v[40:43]
	v_mfma_f32_16x16x32_bf16 v[28:31], v[132:135], v[184:187], v[28:31]
	v_mfma_f32_16x16x32_bf16 v[24:27], v[140:143], v[184:187], v[24:27]
	v_mfma_f32_16x16x32_bf16 v[12:15], v[132:135], v[192:195], v[12:15]
	v_mfma_f32_16x16x32_bf16 v[8:11], v[140:143], v[192:195], v[8:11]
	s_barrier
	s_add_u32 s50, s26, 0x4000
	s_addc_u32 s51, s27, 0
	s_add_i32 s52, s45, s13
	v_lshl_add_u64 v[128:129], s[50:51], 0, v[156:157]
	s_mov_b32 m0, s52
	s_nop 0
	global_load_lds_dwordx4 v[128:129], off
	v_lshl_add_u64 v[128:129], s[50:51], 0, v[152:153]
	s_add_i32 m0, s52, 0x2000
	s_nop 0
	global_load_lds_dwordx4 v[128:129], off
	s_waitcnt vmcnt(6)
	s_barrier
	v_mfma_f32_16x16x32_bf16 v[52:55], v[196:199], v[144:147], v[52:55]
	v_mfma_f32_16x16x32_bf16 v[48:51], v[212:215], v[144:147], v[48:51]
	v_mfma_f32_16x16x32_bf16 v[36:39], v[196:199], v[172:175], v[36:39]
	v_mfma_f32_16x16x32_bf16 v[32:35], v[212:215], v[172:175], v[32:35]
	v_mfma_f32_16x16x32_bf16 v[20:23], v[196:199], v[180:183], v[20:23]
	v_mfma_f32_16x16x32_bf16 v[16:19], v[212:215], v[180:183], v[16:19]
	v_mfma_f32_16x16x32_bf16 v[4:7], v[196:199], v[188:191], v[4:7]
	v_mfma_f32_16x16x32_bf16 v[0:3], v[212:215], v[188:191], v[0:3]
	v_mfma_f32_16x16x32_bf16 v[52:55], v[208:211], v[148:151], v[52:55]
	v_mfma_f32_16x16x32_bf16 v[48:51], v[216:219], v[148:151], v[48:51]
	v_mfma_f32_16x16x32_bf16 v[36:39], v[208:211], v[176:179], v[36:39]
	v_mfma_f32_16x16x32_bf16 v[32:35], v[216:219], v[176:179], v[32:35]
	v_mfma_f32_16x16x32_bf16 v[20:23], v[208:211], v[184:187], v[20:23]
	v_mfma_f32_16x16x32_bf16 v[16:19], v[216:219], v[184:187], v[16:19]
	v_mfma_f32_16x16x32_bf16 v[4:7], v[208:211], v[192:195], v[4:7]
	v_mfma_f32_16x16x32_bf16 v[0:3], v[216:219], v[192:195], v[0:3]
	s_add_i32 s50, 0, 0x18000
	v_add_u32_e32 v140, s50, v202
	s_barrier
	ds_read_b128 v[144:147], v204 offset:32768
	ds_read_b128 v[148:151], v204 offset:33792
	ds_read_b128 v[172:175], v204 offset:34816
	ds_read_b128 v[176:179], v204 offset:35840
	ds_read_b128 v[180:183], v204 offset:36864
	ds_read_b128 v[184:187], v204 offset:37888
	ds_read_b128 v[188:191], v204 offset:38912
	ds_read_b128 v[192:195], v204 offset:39936
	ds_read_b128 v[128:131], v140
	ds_read_b128 v[132:135], v140 offset:1024
	ds_read_b128 v[136:139], v140 offset:2048
	ds_read_b128 v[140:143], v140 offset:3072
	s_add_u32 s30, s30, 0x4000
	s_addc_u32 s31, s31, 0
	s_mov_b32 m0, s36
	v_lshl_add_u64 v[196:197], s[30:31], 0, v[158:159]
	global_load_lds_dwordx4 v[196:197], off
	v_lshl_add_u64 v[196:197], s[30:31], 0, v[154:155]
	s_mov_b32 m0, s37
	s_nop 0
	global_load_lds_dwordx4 v[196:197], off
	s_waitcnt lgkmcnt(0)
	s_barrier
	s_waitcnt lgkmcnt(0)
	v_mfma_f32_16x16x32_bf16 v[124:127], v[128:131], v[144:147], v[124:127]
	v_mfma_f32_16x16x32_bf16 v[120:123], v[136:139], v[144:147], v[120:123]
	v_mfma_f32_16x16x32_bf16 v[108:111], v[128:131], v[172:175], v[108:111]
	v_mfma_f32_16x16x32_bf16 v[104:107], v[136:139], v[172:175], v[104:107]
	v_mfma_f32_16x16x32_bf16 v[92:95], v[128:131], v[180:183], v[92:95]
	v_mfma_f32_16x16x32_bf16 v[88:91], v[136:139], v[180:183], v[88:91]
	v_mfma_f32_16x16x32_bf16 v[76:79], v[128:131], v[188:191], v[76:79]
	v_mfma_f32_16x16x32_bf16 v[72:75], v[136:139], v[188:191], v[72:75]
	v_mfma_f32_16x16x32_bf16 v[124:127], v[132:135], v[148:151], v[124:127]
	v_mfma_f32_16x16x32_bf16 v[120:123], v[140:143], v[148:151], v[120:123]
	v_mfma_f32_16x16x32_bf16 v[108:111], v[132:135], v[176:179], v[108:111]
	v_mfma_f32_16x16x32_bf16 v[104:107], v[140:143], v[176:179], v[104:107]
	v_mfma_f32_16x16x32_bf16 v[92:95], v[132:135], v[184:187], v[92:95]
	v_mfma_f32_16x16x32_bf16 v[88:91], v[140:143], v[184:187], v[88:91]
	v_mfma_f32_16x16x32_bf16 v[76:79], v[132:135], v[192:195], v[76:79]
	v_mfma_f32_16x16x32_bf16 v[72:75], v[140:143], v[192:195], v[72:75]
	s_barrier
	s_add_i32 s51, 0, 0x1c000
	s_add_u32 s30, s26, 0x20000
	v_add_u32_e32 v200, s51, v202
	s_addc_u32 s31, s27, 0
	s_add_i32 s50, s50, s13
	ds_read_b128 v[196:199], v200
	ds_read_b128 v[208:211], v200 offset:1024
	ds_read_b128 v[212:215], v200 offset:2048
	ds_read_b128 v[216:219], v200 offset:3072
	v_lshl_add_u64 v[200:201], s[30:31], 0, v[156:157]
	s_mov_b32 m0, s50
	s_nop 0
	global_load_lds_dwordx4 v[200:201], off
	v_lshl_add_u64 v[200:201], s[30:31], 0, v[152:153]
	s_add_i32 m0, s50, 0x2000
	s_nop 0
	global_load_lds_dwordx4 v[200:201], off
	s_barrier
	s_waitcnt lgkmcnt(0)
	v_mfma_f32_16x16x32_bf16 v[116:119], v[196:199], v[144:147], v[116:119]
	v_mfma_f32_16x16x32_bf16 v[112:115], v[212:215], v[144:147], v[112:115]
	v_mfma_f32_16x16x32_bf16 v[100:103], v[196:199], v[172:175], v[100:103]
	v_mfma_f32_16x16x32_bf16 v[96:99], v[212:215], v[172:175], v[96:99]
	v_mfma_f32_16x16x32_bf16 v[84:87], v[196:199], v[180:183], v[84:87]
	v_mfma_f32_16x16x32_bf16 v[80:83], v[212:215], v[180:183], v[80:83]
	v_mfma_f32_16x16x32_bf16 v[68:71], v[196:199], v[188:191], v[68:71]
	v_mfma_f32_16x16x32_bf16 v[64:67], v[212:215], v[188:191], v[64:67]
	v_mfma_f32_16x16x32_bf16 v[116:119], v[208:211], v[148:151], v[116:119]
	v_mfma_f32_16x16x32_bf16 v[112:115], v[216:219], v[148:151], v[112:115]
	v_mfma_f32_16x16x32_bf16 v[100:103], v[208:211], v[176:179], v[100:103]
	v_mfma_f32_16x16x32_bf16 v[96:99], v[216:219], v[176:179], v[96:99]
	v_mfma_f32_16x16x32_bf16 v[84:87], v[208:211], v[184:187], v[84:87]
	v_mfma_f32_16x16x32_bf16 v[80:83], v[216:219], v[184:187], v[80:83]
	v_mfma_f32_16x16x32_bf16 v[68:71], v[208:211], v[192:195], v[68:71]
	v_mfma_f32_16x16x32_bf16 v[64:67], v[216:219], v[192:195], v[64:67]
	s_mov_b32 m0, s41
	v_lshl_add_u64 v[200:201], s[28:29], 0, v[158:159]
	s_barrier
	ds_read_b128 v[144:147], v204 offset:49152
	ds_read_b128 v[148:151], v204 offset:50176
	ds_read_b128 v[172:175], v204 offset:51200
	ds_read_b128 v[176:179], v204 offset:52224
	ds_read_b128 v[180:183], v204 offset:53248
	ds_read_b128 v[184:187], v204 offset:54272
	ds_read_b128 v[188:191], v204 offset:55296
	ds_read_b128 v[192:195], v204 offset:56320
	global_load_lds_dwordx4 v[200:201], off
	v_lshl_add_u64 v[200:201], s[28:29], 0, v[154:155]
	s_mov_b32 m0, s42
	s_nop 0
	global_load_lds_dwordx4 v[200:201], off
	s_barrier
	s_waitcnt lgkmcnt(0)
	v_mfma_f32_16x16x32_bf16 v[60:63], v[128:131], v[144:147], v[60:63]
	v_mfma_f32_16x16x32_bf16 v[56:59], v[136:139], v[144:147], v[56:59]
	v_mfma_f32_16x16x32_bf16 v[44:47], v[128:131], v[172:175], v[44:47]
	v_mfma_f32_16x16x32_bf16 v[40:43], v[136:139], v[172:175], v[40:43]
	v_mfma_f32_16x16x32_bf16 v[28:31], v[128:131], v[180:183], v[28:31]
	v_mfma_f32_16x16x32_bf16 v[24:27], v[136:139], v[180:183], v[24:27]
	v_mfma_f32_16x16x32_bf16 v[12:15], v[128:131], v[188:191], v[12:15]
	v_mfma_f32_16x16x32_bf16 v[8:11], v[136:139], v[188:191], v[8:11]
	v_mfma_f32_16x16x32_bf16 v[60:63], v[132:135], v[148:151], v[60:63]
	v_mfma_f32_16x16x32_bf16 v[56:59], v[140:143], v[148:151], v[56:59]
	v_mfma_f32_16x16x32_bf16 v[44:47], v[132:135], v[176:179], v[44:47]
	v_mfma_f32_16x16x32_bf16 v[40:43], v[140:143], v[176:179], v[40:43]
	v_mfma_f32_16x16x32_bf16 v[28:31], v[132:135], v[184:187], v[28:31]
	v_mfma_f32_16x16x32_bf16 v[24:27], v[140:143], v[184:187], v[24:27]
	v_mfma_f32_16x16x32_bf16 v[12:15], v[132:135], v[192:195], v[12:15]
	v_mfma_f32_16x16x32_bf16 v[8:11], v[140:143], v[192:195], v[8:11]
	s_barrier
	s_add_u32 s26, s26, 0x24000
	s_addc_u32 s27, s27, 0
	s_add_i32 s28, s51, s13
	v_lshl_add_u64 v[128:129], s[26:27], 0, v[156:157]
	s_mov_b32 m0, s28
	s_nop 0
	global_load_lds_dwordx4 v[128:129], off
	v_lshl_add_u64 v[128:129], s[26:27], 0, v[152:153]
	s_add_i32 m0, s28, 0x2000
	s_nop 0
	global_load_lds_dwordx4 v[128:129], off
	s_waitcnt vmcnt(6)
	s_barrier
	v_mfma_f32_16x16x32_bf16 v[52:55], v[196:199], v[144:147], v[52:55]
	v_mfma_f32_16x16x32_bf16 v[48:51], v[212:215], v[144:147], v[48:51]
	v_mfma_f32_16x16x32_bf16 v[36:39], v[196:199], v[172:175], v[36:39]
	v_mfma_f32_16x16x32_bf16 v[32:35], v[212:215], v[172:175], v[32:35]
	v_mfma_f32_16x16x32_bf16 v[20:23], v[196:199], v[180:183], v[20:23]
	v_mfma_f32_16x16x32_bf16 v[16:19], v[212:215], v[180:183], v[16:19]
	v_mfma_f32_16x16x32_bf16 v[4:7], v[196:199], v[188:191], v[4:7]
	v_mfma_f32_16x16x32_bf16 v[0:3], v[212:215], v[188:191], v[0:3]
	v_mfma_f32_16x16x32_bf16 v[52:55], v[208:211], v[148:151], v[52:55]
	v_mfma_f32_16x16x32_bf16 v[48:51], v[216:219], v[148:151], v[48:51]
	v_mfma_f32_16x16x32_bf16 v[36:39], v[208:211], v[176:179], v[36:39]
	v_mfma_f32_16x16x32_bf16 v[32:35], v[216:219], v[176:179], v[32:35]
	v_mfma_f32_16x16x32_bf16 v[20:23], v[208:211], v[184:187], v[20:23]
	v_mfma_f32_16x16x32_bf16 v[16:19], v[216:219], v[184:187], v[16:19]
	v_mfma_f32_16x16x32_bf16 v[4:7], v[208:211], v[192:195], v[4:7]
	v_mfma_f32_16x16x32_bf16 v[0:3], v[216:219], v[192:195], v[0:3]
	s_add_i32 s49, s49, 2
	s_add_u32 s17, s17, 0x40000
	s_addc_u32 s48, s48, 0
	s_add_u32 s24, s24, 0x800000
	s_addc_u32 s25, s25, 0
	s_cmp_gt_u32 s49, 61
	s_barrier
	s_cbranch_scc0 .LBB0_1512
	s_nop 0
	s_lshl_b32 s24, s4, 8
	v_readlane_b32 s68, v253, 38
	v_readlane_b32 s69, v253, 39
	s_ashr_i32 s25, s24, 31
	s_lshl_b32 s4, s4, 2
	v_readlane_b32 s70, v253, 40
	v_readlane_b32 s71, v253, 41
	s_mov_b64 s[48:49], s[68:69]
	v_lshl_add_u32 v178, s6, 8, v163
	s_ashr_i32 s5, s4, 31
	s_lshl_b64 s[26:27], s[24:25], 1
	s_mov_b64 s[50:51], s[70:71]
	s_add_u32 s26, s50, s26
	v_ashrrev_i32_e32 v179, 31, v178
	s_addc_u32 s27, s51, s27
	v_lshlrev_b64 v[128:129], 11, v[178:179]
	v_lshl_add_u64 v[128:129], s[26:27], 0, v[128:129]
	v_lshl_add_u64 v[128:129], v[128:129], 0, v[160:161]
	global_load_dwordx4 v[180:183], v[128:129], off
	global_load_dwordx4 v[184:187], v[128:129], off offset:256
	v_or_b32_e32 v176, 16, v178
	v_or_b32_e32 v174, 32, v178
	v_or_b32_e32 v172, 48, v178
	v_ashrrev_i32_e32 v177, 31, v176
	v_ashrrev_i32_e32 v175, 31, v174
	v_ashrrev_i32_e32 v173, 31, v172
	v_lshlrev_b64 v[128:129], 11, v[176:177]
	v_lshlrev_b64 v[130:131], 11, v[174:175]
	v_lshlrev_b64 v[132:133], 11, v[172:173]
	v_lshl_add_u64 v[128:129], s[26:27], 0, v[128:129]
	v_lshl_add_u64 v[130:131], s[26:27], 0, v[130:131]
	v_lshl_add_u64 v[132:133], s[26:27], 0, v[132:133]
	v_lshl_add_u64 v[128:129], v[128:129], 0, v[160:161]
	v_lshl_add_u64 v[130:131], v[130:131], 0, v[160:161]
	v_lshl_add_u64 v[188:189], v[132:133], 0, v[160:161]
	global_load_dwordx4 v[148:151], v[128:129], off
	global_load_dwordx4 v[144:147], v[128:129], off offset:256
	global_load_dwordx4 v[140:143], v[130:131], off
	global_load_dwordx4 v[136:139], v[130:131], off offset:256
	global_load_dwordx4 v[132:135], v[188:189], off
	s_nop 0
	global_load_dwordx4 v[128:131], v[188:189], off offset:256
	v_and_b32_e32 v189, 64, v206
	v_xor_b32_e32 v188, 16, v206
	v_add_u32_e32 v196, 64, v189
	v_cmp_lt_i32_e32 vcc, v188, v196
	s_nop 1
	v_cndmask_b32_e32 v188, v206, v188, vcc
	v_lshlrev_b32_e32 v207, 2, v188
	s_nop 7
	s_nop 0
	s_waitcnt vmcnt(0)
	v_lshlrev_b32_e32 v190, 16, v182
	v_and_b32_e32 v191, 0xffff0000, v182
	v_lshlrev_b32_e32 v188, 16, v180
	v_and_b32_e32 v189, 0xffff0000, v180
	v_lshlrev_b32_e32 v180, 16, v181
	v_and_b32_e32 v181, 0xffff0000, v181
	v_lshlrev_b32_e32 v182, 16, v183
	v_and_b32_e32 v183, 0xffff0000, v183
	v_pk_add_f32 v[120:121], v[120:121], v[190:191]
	v_pk_add_f32 v[126:127], v[126:127], v[180:181]
	v_pk_add_f32 v[124:125], v[124:125], v[188:189]
	v_pk_add_f32 v[122:123], v[122:123], v[182:183]
	v_mul_f32_e32 v180, v120, v120
	v_mul_f32_e32 v181, v121, v121
	v_lshlrev_b32_e32 v194, 16, v186
	v_and_b32_e32 v195, 0xffff0000, v186
	v_mul_f32_e32 v182, v122, v122
	v_fmac_f32_e32 v180, v124, v124
	v_fmac_f32_e32 v181, v125, v125
	v_lshlrev_b32_e32 v192, 16, v184
	v_and_b32_e32 v193, 0xffff0000, v184
	v_lshlrev_b32_e32 v184, 16, v185
	v_and_b32_e32 v185, 0xffff0000, v185
	v_pk_add_f32 v[112:113], v[112:113], v[194:195]
	v_mul_f32_e32 v183, v123, v123
	v_fmac_f32_e32 v182, v126, v126
	v_add_f32_e32 v180, v180, v181
	v_lshlrev_b32_e32 v186, 16, v187
	v_and_b32_e32 v187, 0xffff0000, v187
	v_pk_add_f32 v[118:119], v[118:119], v[184:185]
	v_pk_add_f32 v[116:117], v[116:117], v[192:193]
	v_mul_f32_e32 v184, v112, v112
	v_fmac_f32_e32 v183, v127, v127
	v_add_f32_e32 v180, v182, v180
	v_pk_add_f32 v[114:115], v[114:115], v[186:187]
	v_mul_f32_e32 v185, v113, v113
	v_fmac_f32_e32 v184, v116, v116
	v_add_f32_e32 v180, v183, v180
	v_mul_f32_e32 v186, v114, v114
	v_fmac_f32_e32 v185, v117, v117
	v_add_f32_e32 v180, v184, v180
	v_mul_f32_e32 v187, v115, v115
	v_fmac_f32_e32 v186, v118, v118
	v_add_f32_e32 v180, v185, v180
	v_add_f32_e32 v180, v186, v180
	v_fmac_f32_e32 v187, v119, v119
	v_add_f32_e32 v180, v187, v180
	ds_bpermute_b32 v181, v207, v180
	v_xor_b32_e32 v182, 32, v206
	v_cmp_lt_i32_e32 vcc, v182, v196
	v_lshlrev_b64 v[188:189], 6, v[178:179]
	s_waitcnt lgkmcnt(0)
	v_add_f32_e32 v180, v180, v181
	v_cndmask_b32_e32 v182, v206, v182, vcc
	v_lshlrev_b32_e32 v208, 2, v182
	ds_bpermute_b32 v181, v208, v180
	s_and_saveexec_b64 s[28:29], s[0:1]
	s_cbranch_execz .LBB0_1515
	s_waitcnt lgkmcnt(0)
	v_add_f32_e32 v182, v180, v181
	v_lshl_add_u64 v[180:181], s[88:89], 0, v[188:189]
	v_lshl_add_u64 v[180:181], s[4:5], 2, v[180:181]
	s_lshl_b32 s8, s40, 2
	v_lshl_add_u64 v[180:181], v[180:181], 0, s[8:9]
	global_store_dword v[180:181], v182, off sc1
